# D1 + batch-1 q/k norm+rotary moved from the rope phase into the overlapped selection/attention phase (selecting waves)
# speedup vs baseline: 1.0222x; 1.0022x over previous
; template <bool NORM, int ROT> __device__ __forceinline__ void rope_chunk(bf16_t* p, const u32x4 w, const f32x4 (&tb)[4], const float* g, float sc, int lane) {
;     const int j = lane & 15;
;     float x[8] = {bflo(w.x), bfhi(w.x), bflo(w.y), bfhi(w.y), bflo(w.z), bfhi(w.z), bflo(w.w), bfhi(w.w)};
;     if (NORM) {
;         float ss = 0.f;
; #pragma unroll
;         for (int q = 0; q < 8; ++q) ss += x[q] * x[q];
;         ss = row16_sum(ss);
;         const float rstd = rsqrtf(ss * (1.f / 128.f) + EPS);
;         const f32x4 g0 = *(const f32x4*)(g + j * 8), g1 = *(const f32x4*)(g + j * 8 + 4);
; #pragma unroll
;         for (int q = 0; q < 4; ++q) { x[q] *= rstd * g0[q]; x[4 + q] *= rstd * g1[q]; }
;     }
;     constexpr int HALFL = ROT / 16;
;     const bool rot = (ROT == 128) || (j < 8); const bool first = (j & HALFL) == 0;
;     float o[8];
; #pragma unroll
;     for (int q = 0; q < 8; ++q) {
;         const float other = (ROT == 128) ? DPPF(x[q], 0x128)   : shx(x[q], HALFL, lane);
;         const float cs = tb[q >> 1][(q & 1) * 2], sn = tb[q >> 1][(q & 1) * 2 + 1];
;         const float r = first ? (x[q] * cs - other * sn) : (x[q] * cs + other * sn);
;         o[q] = (rot ? r : x[q]) * sc;
;     }
;     u32x4 ow; ow.x = cvt_pk_bf16(o[0], o[1]); ow.y = cvt_pk_bf16(o[2], o[3]); ow.z = cvt_pk_bf16(o[4], o[5]); ow.w = cvt_pk_bf16(o[6], o[7]);
;     *(u32x4*)(p + lane * 8) = ow;
; }
; template <bool NORM, int ROT, bool PERTOK> __device__ __forceinline__ void rope_pass(bf16_t* base, int nchunks, const float* g, const float* tab, float sc, int gw, int NGW, int lane) {
;     constexpr int NB = 8, HALFL = ROT / 16; const int j = lane & 15;
;     for (int it0 = gw * NB; it0 < nchunks; it0 += NGW * NB) {
;         u32x4 w[NB]; f32x4 tb[NB][4];
; #pragma unroll
;         for (int k = 0; k < NB; ++k) { const int it = it0 + k;
;             w[k] = *(const u32x4*)(base + (size_t)it * 512 + lane * 8);
;             const int pos = PERTOK ? ((it >> 2) & 8191) : (((it * 4) & 8191) + (lane >> 4));
;             const float* tp = tab + (size_t)pos * ROT + (j & (HALFL - 1)) * 16;
; #pragma unroll
;             for (int q = 0; q < 4; ++q) tb[k][q] = *(const f32x4*)(tp + q * 4); }
; #pragma unroll
;         for (int k = 0; k < NB; ++k) rope_chunk<NORM, ROT>(base + (size_t)(it0 + k) * 512, w[k], tb[k], g, sc, lane);
;     }
.LBB0_1071:
	v_add_co_u32_e32 v122, vcc, 0xffffe400, v108
	flat_load_dwordx4 v[0:3], v[108:109]
	s_nop 0
	v_addc_co_u32_e32 v123, vcc, -1, v109, vcc
	flat_load_dwordx4 v[4:7], v[122:123]
	flat_load_dwordx4 v[126:129], v[106:107]
	flat_load_dwordx4 v[130:133], v[106:107] offset:16
	s_and_b32 s20, s1, 0xfff00
	s_lshl_b32 s20, s20, 2
	v_lshl_add_u64 v[8:9], v[104:105], 0, s[20:21]
	flat_load_dwordx4 v[92:95], v[8:9]
	flat_load_dwordx4 v[88:91], v[8:9] offset:16
	flat_load_dwordx4 v[84:87], v[8:9] offset:32
	flat_load_dwordx4 v[80:83], v[8:9] offset:48
	v_add_co_u32_e32 v120, vcc, s19, v108
	s_add_i32 s31, s1, 0x80
	s_nop 0
	v_addc_co_u32_e32 v121, vcc, -1, v109, vcc
	s_add_i32 s33, s1, 0xa0
	s_and_b32 s31, s31, 0xfff80
	v_add_co_u32_e32 v118, vcc, s23, v108
	s_add_i32 s34, s1, 0xc0
	s_and_b32 s33, s33, 0xfff80
	s_lshl_b32 s20, s31, 2
	v_addc_co_u32_e32 v119, vcc, -1, v109, vcc
	s_and_b32 s34, s34, 0xfff80
	v_add_co_u32_e32 v116, vcc, s26, v108
	v_lshl_add_u64 v[8:9], v[104:105], 0, s[20:21]
	s_lshl_b32 s20, s33, 2
	flat_load_dwordx4 v[134:137], v[120:121]
	flat_load_dwordx4 v[100:103], v[118:119]
	v_addc_co_u32_e32 v117, vcc, -1, v109, vcc
	flat_load_dwordx4 v[72:75], v[8:9]
	flat_load_dwordx4 v[68:71], v[8:9] offset:16
	flat_load_dwordx4 v[64:67], v[8:9] offset:32
	flat_load_dwordx4 v[60:63], v[8:9] offset:48
	v_lshl_add_u64 v[8:9], v[104:105], 0, s[20:21]
	s_lshl_b32 s20, s34, 2
	v_add_co_u32_e32 v114, vcc, s27, v108
	flat_load_dwordx4 v[52:55], v[8:9]
	flat_load_dwordx4 v[48:51], v[8:9] offset:16
	flat_load_dwordx4 v[44:47], v[8:9] offset:32
	flat_load_dwordx4 v[40:43], v[8:9] offset:48
	v_lshl_add_u64 v[8:9], v[104:105], 0, s[20:21]
	v_addc_co_u32_e32 v115, vcc, -1, v109, vcc
	flat_load_dwordx4 v[96:99], v[116:117]
	flat_load_dwordx4 v[76:79], v[114:115]
	flat_load_dwordx4 v[32:35], v[8:9]
	flat_load_dwordx4 v[28:31], v[8:9] offset:16
	flat_load_dwordx4 v[24:27], v[8:9] offset:32
	flat_load_dwordx4 v[20:23], v[8:9] offset:48
	v_add_co_u32_e32 v112, vcc, s28, v108
	s_add_i32 s35, s1, 0xe0
	s_nop 0
	v_addc_co_u32_e32 v113, vcc, -1, v109, vcc
	v_add_co_u32_e32 v110, vcc, s29, v108
	s_and_b32 s35, s35, 0xfff80
	s_nop 0
	v_addc_co_u32_e32 v111, vcc, -1, v109, vcc
	s_lshl_b32 s20, s35, 2
	v_lshl_add_u64 v[138:139], v[104:105], 0, s[20:21]
	flat_load_dwordx4 v[56:59], v[112:113]
	flat_load_dwordx4 v[36:39], v[110:111]
	s_add_i32 s18, s18, s22
	s_add_i32 s1, s1, s3
	s_cmp_lt_i32 s18, 0x8000
	s_waitcnt vmcnt(0) lgkmcnt(0)
	v_and_b32_e32 v147, 0xffff0000, v4
	v_lshlrev_b32_e32 v146, 16, v4
	v_and_b32_e32 v140, 0xffff0000, v5
	v_mul_f32_e32 v8, v147, v147
	v_lshlrev_b32_e32 v141, 16, v5
	v_fmac_f32_e32 v8, v146, v146
	v_pk_mul_f32 v[4:5], v[140:141], v[140:141]
	v_and_b32_e32 v142, 0xffff0000, v6
	v_add_f32_e32 v5, v5, v8
	v_lshlrev_b32_e32 v143, 16, v6
	v_add_f32_e32 v8, v4, v5
	v_pk_mul_f32 v[4:5], v[142:143], v[142:143]
	v_and_b32_e32 v144, 0xffff0000, v7
	v_add_f32_e32 v5, v5, v8
	v_lshlrev_b32_e32 v145, 16, v7
	v_add_f32_e32 v6, v4, v5
	v_pk_mul_f32 v[4:5], v[144:145], v[144:145]
	s_nop 0
	v_add_f32_e32 v5, v5, v6
	v_add_f32_e32 v4, v4, v5
	s_nop 1
	v_add_f32_dpp v4, v4, v4 quad_perm:[1,0,3,2] row_mask:0xf bank_mask:0xf bound_ctrl:1
	s_nop 1
	v_add_f32_dpp v4, v4, v4 quad_perm:[2,3,0,1] row_mask:0xf bank_mask:0xf bound_ctrl:1
	s_nop 1
	v_add_f32_dpp v4, v4, v4 row_half_mirror row_mask:0xf bank_mask:0xf bound_ctrl:1
	s_nop 1
	v_add_f32_dpp v4, v4, v4 row_mirror row_mask:0xf bank_mask:0xf bound_ctrl:1
	v_fmamk_f32 v4, v4, 0x3c000000, v125
	v_mul_f32_e32 v5, 0x4b800000, v4
	v_cmp_gt_f32_e32 vcc, s30, v4
	s_nop 1
	v_cndmask_b32_e32 v4, v4, v5, vcc
	v_rsq_f32_e32 v148, v4
	flat_load_dwordx4 v[16:19], v[138:139]
	flat_load_dwordx4 v[12:15], v[138:139] offset:16
	flat_load_dwordx4 v[8:11], v[138:139] offset:32
	flat_load_dwordx4 v[4:7], v[138:139] offset:48
	v_mul_f32_e32 v138, 0x45800000, v148
	v_cndmask_b32_e32 v138, v148, v138, vcc
	v_mul_f32_e32 v126, v126, v138
	v_mul_f32_e32 v126, v126, v146
	v_mul_f32_e32 v130, v130, v138
	v_mul_f32_e32 v127, v127, v138
	v_mul_f32_e32 v131, v131, v138
	v_mul_f32_e32 v128, v128, v138
	v_mul_f32_e32 v132, v132, v138
	v_mul_f32_e32 v129, v129, v138
	v_mul_f32_e32 v133, v133, v138
	v_mul_f32_dpp v138, v126, v93 row_ror:8 row_mask:0xf bank_mask:0xf bound_ctrl:1
	v_cndmask_b32_e64 v138, v138, -v138, s[4:5]
	v_mul_f32_e32 v127, v127, v147
	v_fmac_f32_e32 v138, v92, v126
	v_mul_f32_e32 v126, 0x3e0293ee, v138
	v_mul_f32_e32 v128, v128, v141
	v_mul_f32_dpp v138, v127, v95 row_ror:8 row_mask:0xf bank_mask:0xf bound_ctrl:1
	v_cndmask_b32_e64 v138, v138, -v138, s[4:5]
	v_fmac_f32_e32 v138, v94, v127
	v_mul_f32_e32 v127, 0x3e0293ee, v138
	v_mul_f32_e32 v129, v129, v140
	v_mul_f32_dpp v138, v128, v89 row_ror:8 row_mask:0xf bank_mask:0xf bound_ctrl:1
	v_cndmask_b32_e64 v138, v138, -v138, s[4:5]
	v_fmac_f32_e32 v138, v88, v128
	v_mul_f32_e32 v128, 0x3e0293ee, v138
	v_mul_f32_e32 v130, v130, v143
	v_mul_f32_dpp v138, v129, v91 row_ror:8 row_mask:0xf bank_mask:0xf bound_ctrl:1
	v_cndmask_b32_e64 v138, v138, -v138, s[4:5]
	v_fmac_f32_e32 v138, v90, v129
	v_mul_f32_e32 v129, 0x3e0293ee, v138
	v_mul_f32_e32 v131, v131, v142
	v_mul_f32_dpp v138, v130, v85 row_ror:8 row_mask:0xf bank_mask:0xf bound_ctrl:1
	v_cndmask_b32_e64 v138, v138, -v138, s[4:5]
	v_fmac_f32_e32 v138, v84, v130
	v_mul_f32_e32 v130, 0x3e0293ee, v138
	v_mul_f32_e32 v132, v132, v145
	v_mul_f32_dpp v138, v131, v87 row_ror:8 row_mask:0xf bank_mask:0xf bound_ctrl:1
	v_cndmask_b32_e64 v138, v138, -v138, s[4:5]
	v_fmac_f32_e32 v138, v86, v131
	v_mul_f32_e32 v131, 0x3e0293ee, v138
	v_mul_f32_e32 v133, v133, v144
	v_mul_f32_dpp v138, v132, v81 row_ror:8 row_mask:0xf bank_mask:0xf bound_ctrl:1
; __device__ __forceinline__ unsigned cvt_pk_bf16(float lo, float hi) { unsigned r; asm volatile("v_cvt_pk_bf16_f32 %0, %1, %2" : "=v"(r) : "v"(lo), "v"(hi)); return r; }
; __device__ __forceinline__ float bflo(unsigned w) { return __uint_as_float(w << 16); }
; __device__ __forceinline__ float bfhi(unsigned w) { return __uint_as_float(w & 0xffff0000u); }
; __device__ __forceinline__ float shx(float v, int m, int lane) { return __int_as_float(__builtin_amdgcn_ds_bpermute((lane ^ m) << 2, __float_as_int(v))); }
; #define DPPF(v, ctrl) __int_as_float(__builtin_amdgcn_update_dpp(0, __float_as_int(v), (ctrl), 0xf, 0xf, false))
; __device__ __forceinline__ float row16_sum(float x) { x += DPPF(x, 0xB1); x += DPPF(x, 0x4E); x += DPPF(x, 0x141); x += DPPF(x, 0x140); return x; }
; template <bool NORM, int ROT> __device__ __forceinline__ void rope_chunk(bf16_t* p, const u32x4 w, const f32x4 (&tb)[4], const float* g, float sc, int lane) {
;     const int j = lane & 15;
;     float x[8] = {bflo(w.x), bfhi(w.x), bflo(w.y), bfhi(w.y), bflo(w.z), bfhi(w.z), bflo(w.w), bfhi(w.w)};
;     if (NORM) {
;         float ss = 0.f;
; #pragma unroll
;         for (int q = 0; q < 8; ++q) ss += x[q] * x[q];
;         ss = row16_sum(ss);
;         const float rstd = rsqrtf(ss * (1.f / 128.f) + EPS);
;         const f32x4 g0 = *(const f32x4*)(g + j * 8), g1 = *(const f32x4*)(g + j * 8 + 4);
; #pragma unroll
;         for (int q = 0; q < 4; ++q) { x[q] *= rstd * g0[q]; x[4 + q] *= rstd * g1[q]; }
;     }
;     constexpr int HALFL = ROT / 16;
;     const bool rot = (ROT == 128) || (j < 8); const bool first = (j & HALFL) == 0;
;     float o[8];
; #pragma unroll
;     for (int q = 0; q < 8; ++q) {
;         const float other = (ROT == 128) ? DPPF(x[q], 0x128)   : shx(x[q], HALFL, lane);
;         const float cs = tb[q >> 1][(q & 1) * 2], sn = tb[q >> 1][(q & 1) * 2 + 1];
;         const float r = first ? (x[q] * cs - other * sn) : (x[q] * cs + other * sn);
;         o[q] = (rot ? r : x[q]) * sc;
;     }
;     u32x4 ow; ow.x = cvt_pk_bf16(o[0], o[1]); ow.y = cvt_pk_bf16(o[2], o[3]); ow.z = cvt_pk_bf16(o[4], o[5]); ow.w = cvt_pk_bf16(o[6], o[7]);
;     *(u32x4*)(p + lane * 8) = ow;
; }
	v_cndmask_b32_e64 v138, v138, -v138, s[4:5]
	v_fmac_f32_e32 v138, v80, v132
	v_mul_f32_e32 v132, 0x3e0293ee, v138
	v_cvt_pk_bf16_f32 v126, v126, v127
	v_cvt_pk_bf16_f32 v127, v128, v129
	v_cvt_pk_bf16_f32 v128, v130, v131
	v_and_b32_e32 v141, 0xffff0000, v134
	v_mul_f32_dpp v138, v133, v83 row_ror:8 row_mask:0xf bank_mask:0xf bound_ctrl:1
	v_cndmask_b32_e64 v138, v138, -v138, s[4:5]
	v_fmac_f32_e32 v138, v82, v133
	v_mul_f32_e32 v133, 0x3e0293ee, v138
	v_cvt_pk_bf16_f32 v129, v132, v133
	flat_store_dwordx4 v[122:123], v[126:129]
	flat_load_dwordx4 v[126:129], v[106:107]
	s_nop 0
	flat_load_dwordx4 v[130:133], v[106:107] offset:16
	v_lshlrev_b32_e32 v140, 16, v134
	v_mul_f32_e32 v138, v141, v141
	v_and_b32_e32 v122, 0xffff0000, v135
	v_lshlrev_b32_e32 v123, 16, v135
	v_fmac_f32_e32 v138, v140, v140
	v_pk_mul_f32 v[134:135], v[122:123], v[122:123]
	s_nop 0
	v_add_f32_e32 v135, v135, v138
	v_add_f32_e32 v142, v134, v135
	v_and_b32_e32 v134, 0xffff0000, v136
	v_lshlrev_b32_e32 v135, 16, v136
	v_pk_mul_f32 v[138:139], v[134:135], v[134:135]
	s_nop 0
	v_add_f32_e32 v136, v139, v142
	v_add_f32_e32 v142, v138, v136
	v_and_b32_e32 v136, 0xffff0000, v137
	v_lshlrev_b32_e32 v137, 16, v137
	v_pk_mul_f32 v[138:139], v[136:137], v[136:137]
	s_nop 0
	v_add_f32_e32 v139, v139, v142
	v_add_f32_e32 v138, v138, v139
	s_nop 1
	v_add_f32_dpp v138, v138, v138 quad_perm:[1,0,3,2] row_mask:0xf bank_mask:0xf bound_ctrl:1
	s_nop 1
	v_add_f32_dpp v138, v138, v138 quad_perm:[2,3,0,1] row_mask:0xf bank_mask:0xf bound_ctrl:1
	s_nop 1
	v_add_f32_dpp v138, v138, v138 row_half_mirror row_mask:0xf bank_mask:0xf bound_ctrl:1
	s_nop 1
	v_add_f32_dpp v138, v138, v138 row_mirror row_mask:0xf bank_mask:0xf bound_ctrl:1
	v_fmamk_f32 v138, v138, 0x3c000000, v125
	v_mul_f32_e32 v139, 0x4b800000, v138
	v_cmp_gt_f32_e32 vcc, s30, v138
	s_nop 1
	v_cndmask_b32_e32 v138, v138, v139, vcc
	v_rsq_f32_e32 v138, v138
	s_nop 0
	v_mul_f32_e32 v139, 0x45800000, v138
	v_cndmask_b32_e32 v138, v138, v139, vcc
	s_waitcnt vmcnt(0) lgkmcnt(0)
	v_mul_f32_e32 v126, v126, v138
	v_mul_f32_e32 v126, v126, v140
	v_mul_f32_e32 v128, v128, v138
	v_mul_f32_e32 v123, v128, v123
	v_mul_f32_e32 v128, v132, v138
	v_mul_f32_dpp v132, v126, v93 row_ror:8 row_mask:0xf bank_mask:0xf bound_ctrl:1
	v_mul_f32_e32 v127, v127, v138
	v_cndmask_b32_e64 v132, v132, -v132, s[4:5]
	v_mul_f32_e32 v127, v127, v141
	v_fmac_f32_e32 v132, v92, v126
	v_mul_f32_e32 v126, 0x3e0293ee, v132
	v_mul_f32_e32 v129, v129, v138
	v_mul_f32_dpp v132, v127, v95 row_ror:8 row_mask:0xf bank_mask:0xf bound_ctrl:1
	v_cndmask_b32_e64 v132, v132, -v132, s[4:5]
	v_fmac_f32_e32 v132, v94, v127
	v_mul_f32_e32 v127, 0x3e0293ee, v132
	v_mul_f32_e32 v122, v129, v122
	v_mul_f32_dpp v132, v123, v89 row_ror:8 row_mask:0xf bank_mask:0xf bound_ctrl:1
	v_cndmask_b32_e64 v132, v132, -v132, s[4:5]
	v_fmac_f32_e32 v132, v88, v123
	v_mul_f32_e32 v123, 0x3e0293ee, v132
	v_mul_f32_e32 v130, v130, v138
	v_mul_f32_dpp v132, v122, v91 row_ror:8 row_mask:0xf bank_mask:0xf bound_ctrl:1
	v_cndmask_b32_e64 v132, v132, -v132, s[4:5]
	v_mul_f32_e32 v130, v130, v135
	v_fmac_f32_e32 v132, v90, v122
	v_mul_f32_e32 v122, 0x3e0293ee, v132
	v_mul_f32_e32 v131, v131, v138
	v_mul_f32_dpp v132, v130, v85 row_ror:8 row_mask:0xf bank_mask:0xf bound_ctrl:1
	v_cndmask_b32_e64 v132, v132, -v132, s[4:5]
	v_mul_f32_e32 v131, v131, v134
	v_fmac_f32_e32 v132, v84, v130
	v_mul_f32_e32 v130, 0x3e0293ee, v132
	v_mul_f32_e32 v128, v128, v137
	v_mul_f32_dpp v132, v131, v87 row_ror:8 row_mask:0xf bank_mask:0xf bound_ctrl:1
	v_cndmask_b32_e64 v132, v132, -v132, s[4:5]
	v_fmac_f32_e32 v132, v86, v131
	v_mul_f32_e32 v129, v133, v138
	v_mul_f32_e32 v131, 0x3e0293ee, v132
	v_mul_f32_dpp v132, v128, v81 row_ror:8 row_mask:0xf bank_mask:0xf bound_ctrl:1
	v_mul_f32_e32 v129, v129, v136
	v_cndmask_b32_e64 v132, v132, -v132, s[4:5]
	v_fmac_f32_e32 v132, v80, v128
	v_mul_f32_dpp v128, v129, v83 row_ror:8 row_mask:0xf bank_mask:0xf bound_ctrl:1
	v_cndmask_b32_e64 v128, v128, -v128, s[4:5]
	v_fmac_f32_e32 v128, v82, v129
	v_mul_f32_e32 v129, 0x3e0293ee, v128
	v_mul_f32_e32 v132, 0x3e0293ee, v132
	v_cvt_pk_bf16_f32 v126, v126, v127
	v_cvt_pk_bf16_f32 v127, v123, v122
	v_cvt_pk_bf16_f32 v128, v130, v131
	v_cvt_pk_bf16_f32 v129, v132, v129
	flat_store_dwordx4 v[120:121], v[126:129]
	flat_load_dwordx4 v[120:123], v[106:107]
	s_nop 0
	flat_load_dwordx4 v[126:129], v[106:107] offset:16
	v_and_b32_e32 v135, 0xffff0000, v100
	v_lshlrev_b32_e32 v134, 16, v100
	v_mul_f32_e32 v132, v135, v135
	v_and_b32_e32 v100, 0xffff0000, v101
	v_lshlrev_b32_e32 v101, 16, v101
	v_fmac_f32_e32 v132, v134, v134
	v_pk_mul_f32 v[130:131], v[100:101], v[100:101]
	s_nop 0
	v_add_f32_e32 v131, v131, v132
	v_add_f32_e32 v136, v130, v131
	v_and_b32_e32 v130, 0xffff0000, v102
	v_lshlrev_b32_e32 v131, 16, v102
	v_pk_mul_f32 v[132:133], v[130:131], v[130:131]
	s_nop 0
	v_add_f32_e32 v102, v133, v136
	v_add_f32_e32 v136, v132, v102
	v_and_b32_e32 v102, 0xffff0000, v103
	v_lshlrev_b32_e32 v103, 16, v103
	v_pk_mul_f32 v[132:133], v[102:103], v[102:103]
	s_nop 0
	v_add_f32_e32 v133, v133, v136
	v_add_f32_e32 v132, v132, v133
	s_nop 1
	v_add_f32_dpp v132, v132, v132 quad_perm:[1,0,3,2] row_mask:0xf bank_mask:0xf bound_ctrl:1
	s_nop 1
	v_add_f32_dpp v132, v132, v132 quad_perm:[2,3,0,1] row_mask:0xf bank_mask:0xf bound_ctrl:1
	s_nop 1
	v_add_f32_dpp v132, v132, v132 row_half_mirror row_mask:0xf bank_mask:0xf bound_ctrl:1
	s_nop 1
	v_add_f32_dpp v132, v132, v132 row_mirror row_mask:0xf bank_mask:0xf bound_ctrl:1
	v_fmamk_f32 v132, v132, 0x3c000000, v125
	v_mul_f32_e32 v133, 0x4b800000, v132
	v_cmp_gt_f32_e32 vcc, s30, v132
	s_nop 1
	v_cndmask_b32_e32 v132, v132, v133, vcc
	v_rsq_f32_e32 v132, v132
	s_nop 0
	v_mul_f32_e32 v133, 0x45800000, v132
	v_cndmask_b32_e32 v132, v132, v133, vcc
	s_waitcnt vmcnt(0) lgkmcnt(0)
; __device__ __forceinline__ unsigned cvt_pk_bf16(float lo, float hi) { unsigned r; asm volatile("v_cvt_pk_bf16_f32 %0, %1, %2" : "=v"(r) : "v"(lo), "v"(hi)); return r; }
; __device__ __forceinline__ float bflo(unsigned w) { return __uint_as_float(w << 16); }
; __device__ __forceinline__ float bfhi(unsigned w) { return __uint_as_float(w & 0xffff0000u); }
; __device__ __forceinline__ float shx(float v, int m, int lane) { return __int_as_float(__builtin_amdgcn_ds_bpermute((lane ^ m) << 2, __float_as_int(v))); }
; #define DPPF(v, ctrl) __int_as_float(__builtin_amdgcn_update_dpp(0, __float_as_int(v), (ctrl), 0xf, 0xf, false))
; __device__ __forceinline__ float row16_sum(float x) { x += DPPF(x, 0xB1); x += DPPF(x, 0x4E); x += DPPF(x, 0x141); x += DPPF(x, 0x140); return x; }
; template <bool NORM, int ROT> __device__ __forceinline__ void rope_chunk(bf16_t* p, const u32x4 w, const f32x4 (&tb)[4], const float* g, float sc, int lane) {
;     const int j = lane & 15;
;     float x[8] = {bflo(w.x), bfhi(w.x), bflo(w.y), bfhi(w.y), bflo(w.z), bfhi(w.z), bflo(w.w), bfhi(w.w)};
;     if (NORM) {
;         float ss = 0.f;
; #pragma unroll
;         for (int q = 0; q < 8; ++q) ss += x[q] * x[q];
;         ss = row16_sum(ss);
;         const float rstd = rsqrtf(ss * (1.f / 128.f) + EPS);
;         const f32x4 g0 = *(const f32x4*)(g + j * 8), g1 = *(const f32x4*)(g + j * 8 + 4);
; #pragma unroll
;         for (int q = 0; q < 4; ++q) { x[q] *= rstd * g0[q]; x[4 + q] *= rstd * g1[q]; }
;     }
;     constexpr int HALFL = ROT / 16;
;     const bool rot = (ROT == 128) || (j < 8); const bool first = (j & HALFL) == 0;
;     float o[8];
; #pragma unroll
;     for (int q = 0; q < 8; ++q) {
;         const float other = (ROT == 128) ? DPPF(x[q], 0x128)   : shx(x[q], HALFL, lane);
;         const float cs = tb[q >> 1][(q & 1) * 2], sn = tb[q >> 1][(q & 1) * 2 + 1];
;         const float r = first ? (x[q] * cs - other * sn) : (x[q] * cs + other * sn);
;         o[q] = (rot ? r : x[q]) * sc;
;     }
;     u32x4 ow; ow.x = cvt_pk_bf16(o[0], o[1]); ow.y = cvt_pk_bf16(o[2], o[3]); ow.z = cvt_pk_bf16(o[4], o[5]); ow.w = cvt_pk_bf16(o[6], o[7]);
;     *(u32x4*)(p + lane * 8) = ow;
; }
	v_mul_f32_e32 v122, v122, v132
	v_mul_f32_e32 v101, v122, v101
	v_mul_f32_e32 v122, v128, v132
	v_mul_f32_e32 v120, v120, v132
	v_mul_f32_e32 v103, v122, v103
	v_mul_f32_e32 v122, v123, v132
	v_mul_f32_e32 v120, v120, v134
	v_mul_f32_e32 v100, v122, v100
	v_mul_f32_e32 v122, v129, v132
	v_mul_f32_e32 v102, v122, v102
	v_mul_f32_e32 v121, v121, v132
	v_mul_f32_dpp v122, v120, v93 row_ror:8 row_mask:0xf bank_mask:0xf bound_ctrl:1
	v_cndmask_b32_e64 v122, v122, -v122, s[4:5]
	v_mul_f32_e32 v121, v121, v135
	v_fmac_f32_e32 v122, v92, v120
	v_mul_f32_e32 v120, 0x3e0293ee, v122
	v_mul_f32_e32 v126, v126, v132
	v_mul_f32_dpp v122, v121, v95 row_ror:8 row_mask:0xf bank_mask:0xf bound_ctrl:1
	v_cndmask_b32_e64 v122, v122, -v122, s[4:5]
	v_fmac_f32_e32 v122, v94, v121
	v_mul_f32_e32 v121, 0x3e0293ee, v122
	v_mul_f32_e32 v126, v126, v131
	v_mul_f32_dpp v122, v101, v89 row_ror:8 row_mask:0xf bank_mask:0xf bound_ctrl:1
	v_cndmask_b32_e64 v122, v122, -v122, s[4:5]
	v_fmac_f32_e32 v122, v88, v101
	v_mul_f32_e32 v101, 0x3e0293ee, v122
	v_mul_f32_e32 v127, v127, v132
	v_mul_f32_dpp v122, v100, v91 row_ror:8 row_mask:0xf bank_mask:0xf bound_ctrl:1
	v_cndmask_b32_e64 v122, v122, -v122, s[4:5]
	v_fmac_f32_e32 v122, v90, v100
	v_mul_f32_dpp v100, v126, v85 row_ror:8 row_mask:0xf bank_mask:0xf bound_ctrl:1
	v_cndmask_b32_e64 v100, v100, -v100, s[4:5]
	v_mul_f32_e32 v127, v127, v130
	v_fmac_f32_e32 v100, v84, v126
	v_mul_f32_e32 v123, 0x3e0293ee, v100
	v_mul_f32_e32 v122, 0x3e0293ee, v122
	v_mul_f32_dpp v100, v127, v87 row_ror:8 row_mask:0xf bank_mask:0xf bound_ctrl:1
	v_cndmask_b32_e64 v100, v100, -v100, s[4:5]
	v_fmac_f32_e32 v100, v86, v127
	v_mul_f32_e32 v126, 0x3e0293ee, v100
	v_and_b32_e32 v129, 0xffff0000, v96
	v_mul_f32_dpp v100, v103, v81 row_ror:8 row_mask:0xf bank_mask:0xf bound_ctrl:1
	v_cndmask_b32_e64 v100, v100, -v100, s[4:5]
	v_fmac_f32_e32 v100, v80, v103
	v_mul_f32_e32 v103, 0x3e0293ee, v100
	v_lshlrev_b32_e32 v128, 16, v96
	v_mul_f32_dpp v100, v102, v83 row_ror:8 row_mask:0xf bank_mask:0xf bound_ctrl:1
	v_cndmask_b32_e64 v100, v100, -v100, s[4:5]
	v_fmac_f32_e32 v100, v82, v102
	v_mul_f32_e32 v127, 0x3e0293ee, v100
	v_cvt_pk_bf16_f32 v100, v120, v121
	v_cvt_pk_bf16_f32 v101, v101, v122
	v_cvt_pk_bf16_f32 v102, v123, v126
	v_cvt_pk_bf16_f32 v103, v103, v127
	flat_store_dwordx4 v[118:119], v[100:103]
	flat_load_dwordx4 v[100:103], v[106:107]
	s_nop 0
	flat_load_dwordx4 v[118:121], v[106:107] offset:16
	v_mul_f32_e32 v126, v129, v129
	v_and_b32_e32 v96, 0xffff0000, v97
	v_lshlrev_b32_e32 v97, 16, v97
	v_fmac_f32_e32 v126, v128, v128
	v_pk_mul_f32 v[122:123], v[96:97], v[96:97]
	s_nop 0
	v_add_f32_e32 v123, v123, v126
	v_add_f32_e32 v130, v122, v123
	v_and_b32_e32 v122, 0xffff0000, v98
	v_lshlrev_b32_e32 v123, 16, v98
	v_pk_mul_f32 v[126:127], v[122:123], v[122:123]
	s_nop 0
	v_add_f32_e32 v98, v127, v130
	v_add_f32_e32 v130, v126, v98
	v_and_b32_e32 v98, 0xffff0000, v99
	v_lshlrev_b32_e32 v99, 16, v99
	v_pk_mul_f32 v[126:127], v[98:99], v[98:99]
	s_nop 0
	v_add_f32_e32 v127, v127, v130
	v_add_f32_e32 v126, v126, v127
	s_nop 1
	v_add_f32_dpp v126, v126, v126 quad_perm:[1,0,3,2] row_mask:0xf bank_mask:0xf bound_ctrl:1
	s_nop 1
	v_add_f32_dpp v126, v126, v126 quad_perm:[2,3,0,1] row_mask:0xf bank_mask:0xf bound_ctrl:1
	s_nop 1
	v_add_f32_dpp v126, v126, v126 row_half_mirror row_mask:0xf bank_mask:0xf bound_ctrl:1
	s_nop 1
	v_add_f32_dpp v126, v126, v126 row_mirror row_mask:0xf bank_mask:0xf bound_ctrl:1
	v_fmamk_f32 v126, v126, 0x3c000000, v125
	v_mul_f32_e32 v127, 0x4b800000, v126
	v_cmp_gt_f32_e32 vcc, s30, v126
	s_nop 1
	v_cndmask_b32_e32 v126, v126, v127, vcc
	v_rsq_f32_e32 v126, v126
	s_nop 0
	v_mul_f32_e32 v127, 0x45800000, v126
	v_cndmask_b32_e32 v126, v126, v127, vcc
	s_waitcnt vmcnt(0) lgkmcnt(0)
	v_mul_f32_e32 v102, v102, v126
	v_mul_f32_e32 v100, v100, v126
	v_mul_f32_e32 v118, v118, v126
	v_mul_f32_e32 v97, v102, v97
	v_mul_f32_e32 v102, v120, v126
	v_mul_f32_e32 v100, v100, v128
	v_mul_f32_e32 v118, v118, v123
	v_mul_f32_e32 v99, v102, v99
	v_mul_f32_e32 v102, v103, v126
	v_mul_f32_e32 v96, v102, v96
	v_mul_f32_e32 v102, v121, v126
	v_mul_f32_dpp v93, v100, v93 row_ror:8 row_mask:0xf bank_mask:0xf bound_ctrl:1
	v_mul_f32_dpp v89, v97, v89 row_ror:8 row_mask:0xf bank_mask:0xf bound_ctrl:1
	v_mul_f32_dpp v85, v118, v85 row_ror:8 row_mask:0xf bank_mask:0xf bound_ctrl:1
	v_mul_f32_dpp v81, v99, v81 row_ror:8 row_mask:0xf bank_mask:0xf bound_ctrl:1
	v_mul_f32_e32 v101, v101, v126
	v_mul_f32_e32 v119, v119, v126
	v_mul_f32_e32 v98, v102, v98
	v_cndmask_b32_e64 v93, v93, -v93, s[4:5]
	v_cndmask_b32_e64 v89, v89, -v89, s[4:5]
	v_cndmask_b32_e64 v85, v85, -v85, s[4:5]
	v_cndmask_b32_e64 v81, v81, -v81, s[4:5]
	v_mul_f32_e32 v101, v101, v129
	v_mul_f32_e32 v119, v119, v122
	v_fmac_f32_e32 v93, v92, v100
	v_fmac_f32_e32 v89, v88, v97
	v_fmac_f32_e32 v85, v84, v118
	v_fmac_f32_e32 v81, v80, v99
	v_mul_f32_dpp v80, v98, v83 row_ror:8 row_mask:0xf bank_mask:0xf bound_ctrl:1
	v_mul_f32_e32 v92, 0x3e0293ee, v93
	v_mul_f32_dpp v93, v101, v95 row_ror:8 row_mask:0xf bank_mask:0xf bound_ctrl:1
	v_mul_f32_e32 v88, 0x3e0293ee, v89
	v_mul_f32_dpp v89, v96, v91 row_ror:8 row_mask:0xf bank_mask:0xf bound_ctrl:1
	v_mul_f32_e32 v84, 0x3e0293ee, v85
	v_mul_f32_dpp v85, v119, v87 row_ror:8 row_mask:0xf bank_mask:0xf bound_ctrl:1
	v_cndmask_b32_e64 v80, v80, -v80, s[4:5]
	v_cndmask_b32_e64 v93, v93, -v93, s[4:5]
	v_cndmask_b32_e64 v89, v89, -v89, s[4:5]
	v_cndmask_b32_e64 v85, v85, -v85, s[4:5]
	v_fmac_f32_e32 v80, v82, v98
	v_fmac_f32_e32 v93, v94, v101
	v_fmac_f32_e32 v89, v90, v96
	v_fmac_f32_e32 v85, v86, v119
	v_mul_f32_e32 v83, 0x3e0293ee, v80
; __device__ __forceinline__ unsigned cvt_pk_bf16(float lo, float hi) { unsigned r; asm volatile("v_cvt_pk_bf16_f32 %0, %1, %2" : "=v"(r) : "v"(lo), "v"(hi)); return r; }
; __device__ __forceinline__ float bflo(unsigned w) { return __uint_as_float(w << 16); }
; __device__ __forceinline__ float bfhi(unsigned w) { return __uint_as_float(w & 0xffff0000u); }
; __device__ __forceinline__ float shx(float v, int m, int lane) { return __int_as_float(__builtin_amdgcn_ds_bpermute((lane ^ m) << 2, __float_as_int(v))); }
; #define DPPF(v, ctrl) __int_as_float(__builtin_amdgcn_update_dpp(0, __float_as_int(v), (ctrl), 0xf, 0xf, false))
; __device__ __forceinline__ float row16_sum(float x) { x += DPPF(x, 0xB1); x += DPPF(x, 0x4E); x += DPPF(x, 0x141); x += DPPF(x, 0x140); return x; }
; template <bool NORM, int ROT> __device__ __forceinline__ void rope_chunk(bf16_t* p, const u32x4 w, const f32x4 (&tb)[4], const float* g, float sc, int lane) {
;     const int j = lane & 15;
;     float x[8] = {bflo(w.x), bfhi(w.x), bflo(w.y), bfhi(w.y), bflo(w.z), bfhi(w.z), bflo(w.w), bfhi(w.w)};
;     if (NORM) {
;         float ss = 0.f;
; #pragma unroll
;         for (int q = 0; q < 8; ++q) ss += x[q] * x[q];
;         ss = row16_sum(ss);
;         const float rstd = rsqrtf(ss * (1.f / 128.f) + EPS);
;         const f32x4 g0 = *(const f32x4*)(g + j * 8), g1 = *(const f32x4*)(g + j * 8 + 4);
; #pragma unroll
;         for (int q = 0; q < 4; ++q) { x[q] *= rstd * g0[q]; x[4 + q] *= rstd * g1[q]; }
;     }
;     constexpr int HALFL = ROT / 16;
;     const bool rot = (ROT == 128) || (j < 8); const bool first = (j & HALFL) == 0;
;     float o[8];
; #pragma unroll
;     for (int q = 0; q < 8; ++q) {
;         const float other = (ROT == 128) ? DPPF(x[q], 0x128)   : shx(x[q], HALFL, lane);
;         const float cs = tb[q >> 1][(q & 1) * 2], sn = tb[q >> 1][(q & 1) * 2 + 1];
;         const float r = first ? (x[q] * cs - other * sn) : (x[q] * cs + other * sn);
;         o[q] = (rot ? r : x[q]) * sc;
;     }
;     u32x4 ow; ow.x = cvt_pk_bf16(o[0], o[1]); ow.y = cvt_pk_bf16(o[2], o[3]); ow.z = cvt_pk_bf16(o[4], o[5]); ow.w = cvt_pk_bf16(o[6], o[7]);
;     *(u32x4*)(p + lane * 8) = ow;
; }
	v_mul_f32_e32 v93, 0x3e0293ee, v93
	v_mul_f32_e32 v89, 0x3e0293ee, v89
	v_mul_f32_e32 v85, 0x3e0293ee, v85
	v_mul_f32_e32 v86, 0x3e0293ee, v81
	v_cvt_pk_bf16_f32 v80, v92, v93
	v_cvt_pk_bf16_f32 v81, v88, v89
	v_cvt_pk_bf16_f32 v82, v84, v85
	v_cvt_pk_bf16_f32 v83, v86, v83
	flat_store_dwordx4 v[116:117], v[80:83]
	flat_load_dwordx4 v[80:83], v[106:107]
	s_nop 0
	flat_load_dwordx4 v[84:87], v[106:107] offset:16
	v_and_b32_e32 v93, 0xffff0000, v76
	v_lshlrev_b32_e32 v92, 16, v76
	v_mul_f32_e32 v90, v93, v93
	v_and_b32_e32 v76, 0xffff0000, v77
	v_lshlrev_b32_e32 v77, 16, v77
	v_fmac_f32_e32 v90, v92, v92
	v_pk_mul_f32 v[88:89], v[76:77], v[76:77]
	s_nop 0
	v_add_f32_e32 v89, v89, v90
	v_add_f32_e32 v94, v88, v89
	v_and_b32_e32 v88, 0xffff0000, v78
	v_lshlrev_b32_e32 v89, 16, v78
	v_pk_mul_f32 v[90:91], v[88:89], v[88:89]
	s_nop 0
	v_add_f32_e32 v78, v91, v94
	v_add_f32_e32 v94, v90, v78
	v_and_b32_e32 v78, 0xffff0000, v79
	v_lshlrev_b32_e32 v79, 16, v79
	v_pk_mul_f32 v[90:91], v[78:79], v[78:79]
	s_nop 0
	v_add_f32_e32 v91, v91, v94
	v_add_f32_e32 v90, v90, v91
	s_nop 1
	v_add_f32_dpp v90, v90, v90 quad_perm:[1,0,3,2] row_mask:0xf bank_mask:0xf bound_ctrl:1
	s_nop 1
	v_add_f32_dpp v90, v90, v90 quad_perm:[2,3,0,1] row_mask:0xf bank_mask:0xf bound_ctrl:1
	s_nop 1
	v_add_f32_dpp v90, v90, v90 row_half_mirror row_mask:0xf bank_mask:0xf bound_ctrl:1
	s_nop 1
	v_add_f32_dpp v90, v90, v90 row_mirror row_mask:0xf bank_mask:0xf bound_ctrl:1
	v_fmamk_f32 v90, v90, 0x3c000000, v125
	v_mul_f32_e32 v91, 0x4b800000, v90
	v_cmp_gt_f32_e32 vcc, s30, v90
	s_nop 1
	v_cndmask_b32_e32 v90, v90, v91, vcc
	v_rsq_f32_e32 v90, v90
	s_nop 0
	v_mul_f32_e32 v91, 0x45800000, v90
	v_cndmask_b32_e32 v90, v90, v91, vcc
	s_waitcnt vmcnt(0) lgkmcnt(0)
	v_mul_f32_e32 v82, v82, v90
	v_mul_f32_e32 v80, v80, v90
	v_mul_f32_e32 v84, v84, v90
	v_mul_f32_e32 v77, v82, v77
	v_mul_f32_e32 v82, v86, v90
	v_mul_f32_e32 v80, v80, v92
	v_mul_f32_e32 v84, v84, v89
	v_mul_f32_e32 v79, v82, v79
	v_mul_f32_e32 v82, v83, v90
	v_mul_f32_e32 v76, v82, v76
	v_mul_f32_e32 v82, v87, v90
	v_mul_f32_dpp v73, v80, v73 row_ror:8 row_mask:0xf bank_mask:0xf bound_ctrl:1
	v_mul_f32_dpp v69, v77, v69 row_ror:8 row_mask:0xf bank_mask:0xf bound_ctrl:1
	v_mul_f32_dpp v65, v84, v65 row_ror:8 row_mask:0xf bank_mask:0xf bound_ctrl:1
	v_mul_f32_dpp v61, v79, v61 row_ror:8 row_mask:0xf bank_mask:0xf bound_ctrl:1
	v_mul_f32_e32 v81, v81, v90
	v_mul_f32_e32 v85, v85, v90
	v_mul_f32_e32 v78, v82, v78
	v_cndmask_b32_e64 v73, v73, -v73, s[4:5]
	v_cndmask_b32_e64 v69, v69, -v69, s[4:5]
	v_cndmask_b32_e64 v65, v65, -v65, s[4:5]
	v_cndmask_b32_e64 v61, v61, -v61, s[4:5]
	v_mul_f32_e32 v81, v81, v93
	v_mul_f32_e32 v85, v85, v88
	v_fmac_f32_e32 v73, v72, v80
	v_fmac_f32_e32 v69, v68, v77
	v_fmac_f32_e32 v65, v64, v84
	v_fmac_f32_e32 v61, v60, v79
	v_mul_f32_dpp v60, v78, v63 row_ror:8 row_mask:0xf bank_mask:0xf bound_ctrl:1
	v_mul_f32_e32 v72, 0x3e0293ee, v73
	v_mul_f32_dpp v73, v81, v75 row_ror:8 row_mask:0xf bank_mask:0xf bound_ctrl:1
	v_mul_f32_e32 v68, 0x3e0293ee, v69
	v_mul_f32_dpp v69, v76, v71 row_ror:8 row_mask:0xf bank_mask:0xf bound_ctrl:1
	v_mul_f32_e32 v64, 0x3e0293ee, v65
	v_mul_f32_dpp v65, v85, v67 row_ror:8 row_mask:0xf bank_mask:0xf bound_ctrl:1
	v_cndmask_b32_e64 v60, v60, -v60, s[4:5]
	v_cndmask_b32_e64 v73, v73, -v73, s[4:5]
	v_cndmask_b32_e64 v69, v69, -v69, s[4:5]
	v_cndmask_b32_e64 v65, v65, -v65, s[4:5]
	v_fmac_f32_e32 v60, v62, v78
	v_fmac_f32_e32 v73, v74, v81
	v_fmac_f32_e32 v69, v70, v76
	v_fmac_f32_e32 v65, v66, v85
	v_mul_f32_e32 v63, 0x3e0293ee, v60
	v_mul_f32_e32 v73, 0x3e0293ee, v73
	v_mul_f32_e32 v69, 0x3e0293ee, v69
	v_mul_f32_e32 v65, 0x3e0293ee, v65
	v_mul_f32_e32 v66, 0x3e0293ee, v61
	v_cvt_pk_bf16_f32 v60, v72, v73
	v_cvt_pk_bf16_f32 v61, v68, v69
	v_cvt_pk_bf16_f32 v62, v64, v65
	v_cvt_pk_bf16_f32 v63, v66, v63
	flat_store_dwordx4 v[114:115], v[60:63]
	flat_load_dwordx4 v[60:63], v[106:107]
	s_nop 0
	flat_load_dwordx4 v[64:67], v[106:107] offset:16
	v_and_b32_e32 v77, 0xffff0000, v56
	v_lshlrev_b32_e32 v76, 16, v56
	v_and_b32_e32 v56, 0xffff0000, v57
	v_lshlrev_b32_e32 v57, 16, v57
	v_mul_f32_e32 v78, v77, v77
	v_pk_mul_f32 v[70:71], v[56:57], v[56:57]
	v_fmac_f32_e32 v78, v76, v76
	v_and_b32_e32 v68, 0xffff0000, v58
	v_lshlrev_b32_e32 v69, 16, v58
	v_add_f32_e32 v71, v71, v78
	v_pk_mul_f32 v[72:73], v[68:69], v[68:69]
	v_add_f32_e32 v70, v70, v71
	v_and_b32_e32 v58, 0xffff0000, v59
	v_lshlrev_b32_e32 v59, 16, v59
	v_add_f32_e32 v70, v73, v70
	v_pk_mul_f32 v[74:75], v[58:59], v[58:59]
	v_add_f32_e32 v70, v72, v70
	v_add_f32_e32 v70, v75, v70
	v_add_f32_e32 v70, v74, v70
	s_nop 1
	v_add_f32_dpp v70, v70, v70 quad_perm:[1,0,3,2] row_mask:0xf bank_mask:0xf bound_ctrl:1
	s_nop 1
	v_add_f32_dpp v70, v70, v70 quad_perm:[2,3,0,1] row_mask:0xf bank_mask:0xf bound_ctrl:1
	s_nop 1
	v_add_f32_dpp v70, v70, v70 row_half_mirror row_mask:0xf bank_mask:0xf bound_ctrl:1
	s_nop 1
	v_add_f32_dpp v70, v70, v70 row_mirror row_mask:0xf bank_mask:0xf bound_ctrl:1
	v_fmamk_f32 v70, v70, 0x3c000000, v125
	v_mul_f32_e32 v71, 0x4b800000, v70
	v_cmp_gt_f32_e32 vcc, s30, v70
	s_nop 1
	v_cndmask_b32_e32 v70, v70, v71, vcc
	v_rsq_f32_e32 v70, v70
	s_nop 0
	v_mul_f32_e32 v71, 0x45800000, v70
	v_cndmask_b32_e32 v70, v70, v71, vcc
	s_waitcnt vmcnt(0) lgkmcnt(0)
; __device__ __forceinline__ unsigned cvt_pk_bf16(float lo, float hi) { unsigned r; asm volatile("v_cvt_pk_bf16_f32 %0, %1, %2" : "=v"(r) : "v"(lo), "v"(hi)); return r; }
; __device__ __forceinline__ float bflo(unsigned w) { return __uint_as_float(w << 16); }
; __device__ __forceinline__ float bfhi(unsigned w) { return __uint_as_float(w & 0xffff0000u); }
; __device__ __forceinline__ float shx(float v, int m, int lane) { return __int_as_float(__builtin_amdgcn_ds_bpermute((lane ^ m) << 2, __float_as_int(v))); }
; #define DPPF(v, ctrl) __int_as_float(__builtin_amdgcn_update_dpp(0, __float_as_int(v), (ctrl), 0xf, 0xf, false))
; __device__ __forceinline__ float row16_sum(float x) { x += DPPF(x, 0xB1); x += DPPF(x, 0x4E); x += DPPF(x, 0x141); x += DPPF(x, 0x140); return x; }
; template <bool NORM, int ROT> __device__ __forceinline__ void rope_chunk(bf16_t* p, const u32x4 w, const f32x4 (&tb)[4], const float* g, float sc, int lane) {
;     const int j = lane & 15;
;     float x[8] = {bflo(w.x), bfhi(w.x), bflo(w.y), bfhi(w.y), bflo(w.z), bfhi(w.z), bflo(w.w), bfhi(w.w)};
;     if (NORM) {
;         float ss = 0.f;
; #pragma unroll
;         for (int q = 0; q < 8; ++q) ss += x[q] * x[q];
;         ss = row16_sum(ss);
;         const float rstd = rsqrtf(ss * (1.f / 128.f) + EPS);
;         const f32x4 g0 = *(const f32x4*)(g + j * 8), g1 = *(const f32x4*)(g + j * 8 + 4);
; #pragma unroll
;         for (int q = 0; q < 4; ++q) { x[q] *= rstd * g0[q]; x[4 + q] *= rstd * g1[q]; }
;     }
;     constexpr int HALFL = ROT / 16;
;     const bool rot = (ROT == 128) || (j < 8); const bool first = (j & HALFL) == 0;
;     float o[8];
; #pragma unroll
;     for (int q = 0; q < 8; ++q) {
;         const float other = (ROT == 128) ? DPPF(x[q], 0x128)   : shx(x[q], HALFL, lane);
;         const float cs = tb[q >> 1][(q & 1) * 2], sn = tb[q >> 1][(q & 1) * 2 + 1];
;         const float r = first ? (x[q] * cs - other * sn) : (x[q] * cs + other * sn);
;         o[q] = (rot ? r : x[q]) * sc;
;     }
;     u32x4 ow; ow.x = cvt_pk_bf16(o[0], o[1]); ow.y = cvt_pk_bf16(o[2], o[3]); ow.z = cvt_pk_bf16(o[4], o[5]); ow.w = cvt_pk_bf16(o[6], o[7]);
;     *(u32x4*)(p + lane * 8) = ow;
; }
	v_mul_f32_e32 v62, v62, v70
	v_mul_f32_e32 v60, v60, v70
	v_mul_f32_e32 v64, v64, v70
	v_mul_f32_e32 v57, v62, v57
	v_mul_f32_e32 v62, v66, v70
	v_mul_f32_e32 v60, v60, v76
	v_mul_f32_e32 v64, v64, v69
	v_mul_f32_e32 v59, v62, v59
	v_mul_f32_e32 v62, v63, v70
	v_mul_f32_e32 v56, v62, v56
	v_mul_f32_e32 v62, v67, v70
	v_mul_f32_dpp v53, v60, v53 row_ror:8 row_mask:0xf bank_mask:0xf bound_ctrl:1
	v_mul_f32_dpp v49, v57, v49 row_ror:8 row_mask:0xf bank_mask:0xf bound_ctrl:1
	v_mul_f32_dpp v45, v64, v45 row_ror:8 row_mask:0xf bank_mask:0xf bound_ctrl:1
	v_mul_f32_dpp v41, v59, v41 row_ror:8 row_mask:0xf bank_mask:0xf bound_ctrl:1
	v_mul_f32_e32 v61, v61, v70
	v_mul_f32_e32 v65, v65, v70
	v_mul_f32_e32 v58, v62, v58
	v_cndmask_b32_e64 v53, v53, -v53, s[4:5]
	v_cndmask_b32_e64 v49, v49, -v49, s[4:5]
	v_cndmask_b32_e64 v45, v45, -v45, s[4:5]
	v_cndmask_b32_e64 v41, v41, -v41, s[4:5]
	v_mul_f32_e32 v61, v61, v77
	v_mul_f32_e32 v65, v65, v68
	v_fmac_f32_e32 v53, v52, v60
	v_fmac_f32_e32 v49, v48, v57
	v_fmac_f32_e32 v45, v44, v64
	v_fmac_f32_e32 v41, v40, v59
	v_mul_f32_dpp v40, v58, v43 row_ror:8 row_mask:0xf bank_mask:0xf bound_ctrl:1
	v_mul_f32_e32 v52, 0x3e0293ee, v53
	v_mul_f32_dpp v53, v61, v55 row_ror:8 row_mask:0xf bank_mask:0xf bound_ctrl:1
	v_mul_f32_e32 v48, 0x3e0293ee, v49
	v_mul_f32_dpp v49, v56, v51 row_ror:8 row_mask:0xf bank_mask:0xf bound_ctrl:1
	v_mul_f32_e32 v44, 0x3e0293ee, v45
	v_mul_f32_dpp v45, v65, v47 row_ror:8 row_mask:0xf bank_mask:0xf bound_ctrl:1
	v_cndmask_b32_e64 v40, v40, -v40, s[4:5]
	v_cndmask_b32_e64 v53, v53, -v53, s[4:5]
	v_cndmask_b32_e64 v49, v49, -v49, s[4:5]
	v_cndmask_b32_e64 v45, v45, -v45, s[4:5]
	v_fmac_f32_e32 v40, v42, v58
	v_fmac_f32_e32 v53, v54, v61
	v_fmac_f32_e32 v49, v50, v56
	v_fmac_f32_e32 v45, v46, v65
	v_mul_f32_e32 v43, 0x3e0293ee, v40
	v_mul_f32_e32 v53, 0x3e0293ee, v53
	v_mul_f32_e32 v49, 0x3e0293ee, v49
	v_mul_f32_e32 v45, 0x3e0293ee, v45
	v_mul_f32_e32 v46, 0x3e0293ee, v41
	v_cvt_pk_bf16_f32 v40, v52, v53
	v_cvt_pk_bf16_f32 v41, v48, v49
	v_cvt_pk_bf16_f32 v42, v44, v45
	v_cvt_pk_bf16_f32 v43, v46, v43
	flat_store_dwordx4 v[112:113], v[40:43]
	flat_load_dwordx4 v[40:43], v[106:107]
	s_nop 0
	flat_load_dwordx4 v[44:47], v[106:107] offset:16
	v_and_b32_e32 v57, 0xffff0000, v36
	v_lshlrev_b32_e32 v56, 16, v36
	v_and_b32_e32 v36, 0xffff0000, v37
	v_lshlrev_b32_e32 v37, 16, v37
	v_mul_f32_e32 v58, v57, v57
	v_pk_mul_f32 v[50:51], v[36:37], v[36:37]
	v_fmac_f32_e32 v58, v56, v56
	v_and_b32_e32 v48, 0xffff0000, v38
	v_lshlrev_b32_e32 v49, 16, v38
	v_add_f32_e32 v51, v51, v58
	v_pk_mul_f32 v[52:53], v[48:49], v[48:49]
	v_add_f32_e32 v50, v50, v51
	v_and_b32_e32 v38, 0xffff0000, v39
	v_lshlrev_b32_e32 v39, 16, v39
	v_add_f32_e32 v50, v53, v50
	v_pk_mul_f32 v[54:55], v[38:39], v[38:39]
	v_add_f32_e32 v50, v52, v50
	v_add_f32_e32 v50, v55, v50
	v_add_f32_e32 v50, v54, v50
	s_nop 1
	v_add_f32_dpp v50, v50, v50 quad_perm:[1,0,3,2] row_mask:0xf bank_mask:0xf bound_ctrl:1
	s_nop 1
	v_add_f32_dpp v50, v50, v50 quad_perm:[2,3,0,1] row_mask:0xf bank_mask:0xf bound_ctrl:1
	s_nop 1
	v_add_f32_dpp v50, v50, v50 row_half_mirror row_mask:0xf bank_mask:0xf bound_ctrl:1
	s_nop 1
	v_add_f32_dpp v50, v50, v50 row_mirror row_mask:0xf bank_mask:0xf bound_ctrl:1
	v_fmamk_f32 v50, v50, 0x3c000000, v125
	v_mul_f32_e32 v51, 0x4b800000, v50
	v_cmp_gt_f32_e32 vcc, s30, v50
	s_nop 1
	v_cndmask_b32_e32 v50, v50, v51, vcc
	v_rsq_f32_e32 v50, v50
	s_nop 0
	v_mul_f32_e32 v51, 0x45800000, v50
	v_cndmask_b32_e32 v50, v50, v51, vcc
	s_waitcnt vmcnt(0) lgkmcnt(0)
	v_mul_f32_e32 v42, v42, v50
	v_mul_f32_e32 v40, v40, v50
	v_mul_f32_e32 v44, v44, v50
	v_mul_f32_e32 v37, v42, v37
	v_mul_f32_e32 v42, v46, v50
	v_mul_f32_e32 v40, v40, v56
	v_mul_f32_e32 v44, v44, v49
	v_mul_f32_e32 v39, v42, v39
	v_mul_f32_e32 v42, v43, v50
	v_mul_f32_e32 v36, v42, v36
	v_mul_f32_e32 v42, v47, v50
	v_mul_f32_dpp v33, v40, v33 row_ror:8 row_mask:0xf bank_mask:0xf bound_ctrl:1
	v_mul_f32_dpp v29, v37, v29 row_ror:8 row_mask:0xf bank_mask:0xf bound_ctrl:1
	v_mul_f32_dpp v25, v44, v25 row_ror:8 row_mask:0xf bank_mask:0xf bound_ctrl:1
	v_mul_f32_dpp v21, v39, v21 row_ror:8 row_mask:0xf bank_mask:0xf bound_ctrl:1
	v_mul_f32_e32 v41, v41, v50
	v_mul_f32_e32 v45, v45, v50
	v_mul_f32_e32 v38, v42, v38
	v_cndmask_b32_e64 v33, v33, -v33, s[4:5]
	v_cndmask_b32_e64 v29, v29, -v29, s[4:5]
	v_cndmask_b32_e64 v25, v25, -v25, s[4:5]
	v_cndmask_b32_e64 v21, v21, -v21, s[4:5]
	v_mul_f32_e32 v41, v41, v57
	v_mul_f32_e32 v45, v45, v48
	v_fmac_f32_e32 v33, v32, v40
	v_fmac_f32_e32 v29, v28, v37
	v_fmac_f32_e32 v25, v24, v44
	v_fmac_f32_e32 v21, v20, v39
	v_mul_f32_dpp v20, v38, v23 row_ror:8 row_mask:0xf bank_mask:0xf bound_ctrl:1
	v_mul_f32_e32 v32, 0x3e0293ee, v33
	v_mul_f32_dpp v33, v41, v35 row_ror:8 row_mask:0xf bank_mask:0xf bound_ctrl:1
	v_mul_f32_e32 v28, 0x3e0293ee, v29
	v_mul_f32_dpp v29, v36, v31 row_ror:8 row_mask:0xf bank_mask:0xf bound_ctrl:1
	v_mul_f32_e32 v24, 0x3e0293ee, v25
	v_mul_f32_dpp v25, v45, v27 row_ror:8 row_mask:0xf bank_mask:0xf bound_ctrl:1
	v_cndmask_b32_e64 v20, v20, -v20, s[4:5]
	v_cndmask_b32_e64 v33, v33, -v33, s[4:5]
	v_cndmask_b32_e64 v29, v29, -v29, s[4:5]
	v_cndmask_b32_e64 v25, v25, -v25, s[4:5]
	v_fmac_f32_e32 v20, v22, v38
	v_fmac_f32_e32 v33, v34, v41
	v_fmac_f32_e32 v29, v30, v36
	v_fmac_f32_e32 v25, v26, v45
	v_mul_f32_e32 v23, 0x3e0293ee, v20
	v_mul_f32_e32 v33, 0x3e0293ee, v33
	v_mul_f32_e32 v29, 0x3e0293ee, v29
	v_mul_f32_e32 v25, 0x3e0293ee, v25
	v_mul_f32_e32 v26, 0x3e0293ee, v21
	v_cvt_pk_bf16_f32 v20, v32, v33
	v_cvt_pk_bf16_f32 v21, v28, v29
	v_cvt_pk_bf16_f32 v22, v24, v25
	v_cvt_pk_bf16_f32 v23, v26, v23
; template <bool NORM, int ROT, bool PERTOK> __device__ __forceinline__ void rope_pass(bf16_t* base, int nchunks, const float* g, const float* tab, float sc, int gw, int NGW, int lane) {
;     constexpr int NB = 8, HALFL = ROT / 16; const int j = lane & 15;
;     for (int it0 = gw * NB; it0 < nchunks; it0 += NGW * NB) {
;         u32x4 w[NB]; f32x4 tb[NB][4];
; #pragma unroll
;         for (int k = 0; k < NB; ++k) { const int it = it0 + k;
;             w[k] = *(const u32x4*)(base + (size_t)it * 512 + lane * 8);
;             const int pos = PERTOK ? ((it >> 2) & 8191) : (((it * 4) & 8191) + (lane >> 4));
;             const float* tp = tab + (size_t)pos * ROT + (j & (HALFL - 1)) * 16;
; #pragma unroll
;             for (int q = 0; q < 4; ++q) tb[k][q] = *(const f32x4*)(tp + q * 4); }
; #pragma unroll
;         for (int k = 0; k < NB; ++k) rope_chunk<NORM, ROT>(base + (size_t)(it0 + k) * 512, w[k], tb[k], g, sc, lane);
;     }
; }
; __device__ __forceinline__ void post_proj(const Args& A, int gw, int NGW, int lane) {
;     unsigned char* ws = A.ws;
;     const float* R1 = (const float*)(ws + WS_ROPE1); const float* R2 = (const float*)(ws + WS_ROPE2);
;     const float qs = 0.08838834764831845f;
;     rope_pass<true, 128, true>((bf16_t*)(ws + WS_DQ), T * 4, A.q_norm_g, R1, qs * 1.4426950408889634f  , gw, NGW, lane);
;     rope_pass<true, 128, false>((bf16_t*)(ws + WS_DK), T, A.k_norm_g, R1, 1.f, gw, NGW, lane);
	flat_store_dwordx4 v[110:111], v[20:23]
	flat_load_dwordx4 v[20:23], v[106:107]
	s_nop 0
	flat_load_dwordx4 v[24:27], v[106:107] offset:16
	v_and_b32_e32 v37, 0xffff0000, v0
	v_lshlrev_b32_e32 v36, 16, v0
	v_and_b32_e32 v0, 0xffff0000, v1
	v_lshlrev_b32_e32 v1, 16, v1
	v_mul_f32_e32 v38, v37, v37
	v_pk_mul_f32 v[30:31], v[0:1], v[0:1]
	v_fmac_f32_e32 v38, v36, v36
	v_and_b32_e32 v28, 0xffff0000, v2
	v_lshlrev_b32_e32 v29, 16, v2
	v_add_f32_e32 v31, v31, v38
	v_pk_mul_f32 v[32:33], v[28:29], v[28:29]
	v_add_f32_e32 v30, v30, v31
	v_and_b32_e32 v2, 0xffff0000, v3
	v_lshlrev_b32_e32 v3, 16, v3
	v_add_f32_e32 v30, v33, v30
	v_pk_mul_f32 v[34:35], v[2:3], v[2:3]
	v_add_f32_e32 v30, v32, v30
	v_add_f32_e32 v30, v35, v30
	v_add_f32_e32 v30, v34, v30
	s_nop 1
	v_add_f32_dpp v30, v30, v30 quad_perm:[1,0,3,2] row_mask:0xf bank_mask:0xf bound_ctrl:1
	s_nop 1
	v_add_f32_dpp v30, v30, v30 quad_perm:[2,3,0,1] row_mask:0xf bank_mask:0xf bound_ctrl:1
	s_nop 1
	v_add_f32_dpp v30, v30, v30 row_half_mirror row_mask:0xf bank_mask:0xf bound_ctrl:1
	s_nop 1
	v_add_f32_dpp v30, v30, v30 row_mirror row_mask:0xf bank_mask:0xf bound_ctrl:1
	v_fmamk_f32 v30, v30, 0x3c000000, v125
	v_mul_f32_e32 v31, 0x4b800000, v30
	v_cmp_gt_f32_e32 vcc, s30, v30
	s_nop 1
	v_cndmask_b32_e32 v30, v30, v31, vcc
	v_rsq_f32_e32 v30, v30
	s_nop 0
	v_mul_f32_e32 v31, 0x45800000, v30
	v_cndmask_b32_e32 v30, v30, v31, vcc
	s_waitcnt vmcnt(0) lgkmcnt(0)
	v_mul_f32_e32 v22, v22, v30
	v_mul_f32_e32 v1, v22, v1
	v_mul_f32_e32 v23, v23, v30
	v_mul_f32_e32 v0, v23, v0
	v_mul_f32_dpp v13, v1, v13 row_ror:8 row_mask:0xf bank_mask:0xf bound_ctrl:1
	v_cndmask_b32_e64 v13, v13, -v13, s[4:5]
	v_mul_f32_e32 v24, v24, v30
	v_fmac_f32_e32 v13, v12, v1
	v_mul_f32_dpp v12, v0, v15 row_ror:8 row_mask:0xf bank_mask:0xf bound_ctrl:1
	v_mul_f32_e32 v24, v24, v29
	v_cndmask_b32_e64 v12, v12, -v12, s[4:5]
	v_fmac_f32_e32 v12, v14, v0
	v_mul_f32_dpp v0, v24, v9 row_ror:8 row_mask:0xf bank_mask:0xf bound_ctrl:1
	v_mul_f32_e32 v25, v25, v30
	v_cndmask_b32_e64 v0, v0, -v0, s[4:5]
	v_mul_f32_e32 v25, v25, v28
	v_fmac_f32_e32 v0, v8, v24
	v_mul_f32_e32 v8, 0x3e0293ee, v0
	v_mul_f32_e32 v20, v20, v30
	v_mul_f32_dpp v0, v25, v11 row_ror:8 row_mask:0xf bank_mask:0xf bound_ctrl:1
	v_mul_f32_e32 v26, v26, v30
	v_cndmask_b32_e64 v0, v0, -v0, s[4:5]
	v_mul_f32_e32 v20, v20, v36
	v_mul_f32_e32 v3, v26, v3
	v_fmac_f32_e32 v0, v10, v25
	v_mul_f32_dpp v17, v20, v17 row_ror:8 row_mask:0xf bank_mask:0xf bound_ctrl:1
	v_mul_f32_e32 v9, 0x3e0293ee, v0
	v_mul_f32_dpp v0, v3, v5 row_ror:8 row_mask:0xf bank_mask:0xf bound_ctrl:1
	v_mul_f32_e32 v21, v21, v30
	v_mul_f32_e32 v22, v27, v30
	v_cndmask_b32_e64 v17, v17, -v17, s[4:5]
	v_cndmask_b32_e64 v0, v0, -v0, s[4:5]
	v_mul_f32_e32 v21, v21, v37
	v_mul_f32_e32 v2, v22, v2
	v_fmac_f32_e32 v17, v16, v20
	v_fmac_f32_e32 v0, v4, v3
	v_mul_f32_e32 v16, 0x3e0293ee, v17
	v_mul_f32_dpp v17, v21, v19 row_ror:8 row_mask:0xf bank_mask:0xf bound_ctrl:1
	v_mul_f32_e32 v3, 0x3e0293ee, v0
	v_mul_f32_dpp v0, v2, v7 row_ror:8 row_mask:0xf bank_mask:0xf bound_ctrl:1
	v_cndmask_b32_e64 v17, v17, -v17, s[4:5]
	v_cndmask_b32_e64 v0, v0, -v0, s[4:5]
	v_fmac_f32_e32 v17, v18, v21
	v_mul_f32_e32 v1, 0x3e0293ee, v13
	v_fmac_f32_e32 v0, v6, v2
	v_mul_f32_e32 v17, 0x3e0293ee, v17
	v_mul_f32_e32 v12, 0x3e0293ee, v12
	v_mul_f32_e32 v4, 0x3e0293ee, v0
	v_cvt_pk_bf16_f32 v0, v16, v17
	v_cvt_pk_bf16_f32 v1, v1, v12
	v_cvt_pk_bf16_f32 v2, v8, v9
	v_cvt_pk_bf16_f32 v3, v3, v4
	flat_store_dwordx4 v[108:109], v[0:3]
	v_lshl_add_u64 v[108:109], v[108:109], 0, s[24:25]
	s_cbranch_scc1 .LBB0_1071
.LBB0_1072:
	s_cmpk_gt_i32 s0, 0x3ff
	v_ashrrev_i32_e32 v178, 4, v179
	s_cbranch_scc1 .LBB0_1075
	s_lshl_b32 s18, s0, 3
	v_and_b32_e32 v0, 0x1c0, v180
	v_mov_b32_e32 v1, 0
	v_readlane_b32 s3, v255, 3
	v_lshl_add_u64 v[158:159], s[16:17], 0, v[0:1]
	v_and_b32_e32 v0, 0x1e0, v124
	s_lshl_b32 s1, s2, 8
	s_lshl_b32 s3, s3, 5
	s_ashr_i32 s19, s18, 31
	v_lshl_add_u64 v[160:161], s[6:7], 0, v[0:1]
	s_lshl_b32 s6, s44, 6
	s_add_i32 s1, s1, s3
	s_lshl_b32 s3, s44, 8
	s_lshl_b64 s[16:17], s[18:19], 10
	s_add_u32 s16, s10, s16
	v_ashrrev_i32_e32 v157, 31, v156
	s_addc_u32 s17, s11, s17
	v_lshl_add_u64 v[0:1], v[156:157], 1, s[16:17]
	s_mov_b64 s[16:17], 0x11801c00
	s_ashr_i32 s7, s6, 31
	v_cmp_eq_u32_e64 s[4:5], 0, v181
	v_lshl_add_u64 v[162:163], v[0:1], 0, s[16:17]
	s_lshl_b64 s[16:17], s[6:7], 10
	s_movk_i32 s7, 0xe800
	s_movk_i32 s19, 0xec00
	s_movk_i32 s20, 0xf000
	s_movk_i32 s21, 0xf400
	s_movk_i32 s22, 0xf800
	s_movk_i32 s23, 0xfc00
	v_mov_b32_e32 v157, 0x358637bd
	s_mov_b32 s24, 0x800000
; template <bool NORM, int ROT> __device__ __forceinline__ void rope_chunk(bf16_t* p, const u32x4 w, const f32x4 (&tb)[4], const float* g, float sc, int lane) {
;     const int j = lane & 15;
;     float x[8] = {bflo(w.x), bfhi(w.x), bflo(w.y), bfhi(w.y), bflo(w.z), bfhi(w.z), bflo(w.w), bfhi(w.w)};
;     if (NORM) {
;         float ss = 0.f;
; #pragma unroll
;         for (int q = 0; q < 8; ++q) ss += x[q] * x[q];
;         ss = row16_sum(ss);
;         const float rstd = rsqrtf(ss * (1.f / 128.f) + EPS);
;         const f32x4 g0 = *(const f32x4*)(g + j * 8), g1 = *(const f32x4*)(g + j * 8 + 4);
; #pragma unroll
;         for (int q = 0; q < 4; ++q) { x[q] *= rstd * g0[q]; x[4 + q] *= rstd * g1[q]; }
;     }
;     constexpr int HALFL = ROT / 16;
;     const bool rot = (ROT == 128) || (j < 8); const bool first = (j & HALFL) == 0;
;     float o[8];
; #pragma unroll
;     for (int q = 0; q < 8; ++q) {
;         const float other = (ROT == 128) ? DPPF(x[q], 0x128)   : shx(x[q], HALFL, lane);
;         const float cs = tb[q >> 1][(q & 1) * 2], sn = tb[q >> 1][(q & 1) * 2 + 1];
;         const float r = first ? (x[q] * cs - other * sn) : (x[q] * cs + other * sn);
;         o[q] = (rot ? r : x[q]) * sc;
;     }
;     u32x4 ow; ow.x = cvt_pk_bf16(o[0], o[1]); ow.y = cvt_pk_bf16(o[2], o[3]); ow.z = cvt_pk_bf16(o[4], o[5]); ow.w = cvt_pk_bf16(o[6], o[7]);
;     *(u32x4*)(p + lane * 8) = ow;
; }
; template <bool NORM, int ROT, bool PERTOK> __device__ __forceinline__ void rope_pass(bf16_t* base, int nchunks, const float* g, const float* tab, float sc, int gw, int NGW, int lane) {
;     constexpr int NB = 8, HALFL = ROT / 16; const int j = lane & 15;
;     for (int it0 = gw * NB; it0 < nchunks; it0 += NGW * NB) {
;         u32x4 w[NB]; f32x4 tb[NB][4];
; #pragma unroll
;         for (int k = 0; k < NB; ++k) { const int it = it0 + k;
;             w[k] = *(const u32x4*)(base + (size_t)it * 512 + lane * 8);
;             const int pos = PERTOK ? ((it >> 2) & 8191) : (((it * 4) & 8191) + (lane >> 4));
;             const float* tp = tab + (size_t)pos * ROT + (j & (HALFL - 1)) * 16;
; #pragma unroll
;             for (int q = 0; q < 4; ++q) tb[k][q] = *(const f32x4*)(tp + q * 4); }
; #pragma unroll
;         for (int k = 0; k < NB; ++k) rope_chunk<NORM, ROT>(base + (size_t)(it0 + k) * 512, w[k], tb[k], g, sc, lane);
;     }
.LBB0_1074:
	v_add_co_u32_e32 v176, vcc, 0xffffe400, v162
	s_and_b32 s25, s1, 0x1fe0
	s_nop 0
	v_addc_co_u32_e32 v177, vcc, -1, v163, vcc
	flat_load_dwordx4 v[0:3], v[176:177]
	v_add_u32_e32 v4, s25, v178
	v_ashrrev_i32_e32 v5, 31, v4
	v_lshlrev_b64 v[4:5], 9, v[4:5]
	s_add_i32 s25, s1, 4
	v_lshl_add_u64 v[4:5], v[158:159], 0, v[4:5]
	s_and_b32 s25, s25, 0x1fe4
	flat_load_dwordx4 v[152:155], v[4:5]
	flat_load_dwordx4 v[148:151], v[4:5] offset:16
	flat_load_dwordx4 v[144:147], v[4:5] offset:32
	flat_load_dwordx4 v[140:143], v[4:5] offset:48
	v_add_u32_e32 v4, s25, v178
	v_ashrrev_i32_e32 v5, 31, v4
	v_add_co_u32_e32 v174, vcc, s7, v162
	v_lshlrev_b64 v[4:5], 9, v[4:5]
	s_add_i32 s25, s1, 8
	v_addc_co_u32_e32 v175, vcc, -1, v163, vcc
	v_lshl_add_u64 v[4:5], v[158:159], 0, v[4:5]
	s_and_b32 s25, s25, 0x1fe8
	flat_load_dwordx4 v[136:139], v[174:175]
	flat_load_dwordx4 v[132:135], v[4:5]
	flat_load_dwordx4 v[128:131], v[4:5] offset:16
	flat_load_dwordx4 v[124:127], v[4:5] offset:32
	flat_load_dwordx4 v[120:123], v[4:5] offset:48
	v_add_u32_e32 v4, s25, v178
	v_ashrrev_i32_e32 v5, 31, v4
	v_add_co_u32_e32 v172, vcc, s19, v162
	v_lshlrev_b64 v[4:5], 9, v[4:5]
	s_add_i32 s25, s1, 12
	v_addc_co_u32_e32 v173, vcc, -1, v163, vcc
	v_lshl_add_u64 v[4:5], v[158:159], 0, v[4:5]
	s_and_b32 s25, s25, 0x1fec
	flat_load_dwordx4 v[116:119], v[172:173]
	flat_load_dwordx4 v[112:115], v[4:5]
	flat_load_dwordx4 v[108:111], v[4:5] offset:16
	flat_load_dwordx4 v[104:107], v[4:5] offset:32
	flat_load_dwordx4 v[100:103], v[4:5] offset:48
	v_add_u32_e32 v4, s25, v178
	v_ashrrev_i32_e32 v5, 31, v4
	v_add_co_u32_e32 v170, vcc, s20, v162
	v_lshlrev_b64 v[4:5], 9, v[4:5]
	s_add_i32 s25, s1, 16
	v_addc_co_u32_e32 v171, vcc, -1, v163, vcc
	v_lshl_add_u64 v[4:5], v[158:159], 0, v[4:5]
	s_and_b32 s25, s25, 0x1ff0
	flat_load_dwordx4 v[96:99], v[170:171]
	flat_load_dwordx4 v[92:95], v[4:5]
	flat_load_dwordx4 v[88:91], v[4:5] offset:16
	flat_load_dwordx4 v[80:83], v[4:5] offset:32
	flat_load_dwordx4 v[72:75], v[4:5] offset:48
	v_add_u32_e32 v4, s25, v178
	v_add_co_u32_e32 v168, vcc, s21, v162
	v_ashrrev_i32_e32 v5, 31, v4
	s_nop 0
	v_addc_co_u32_e32 v169, vcc, -1, v163, vcc
	v_lshlrev_b64 v[4:5], 9, v[4:5]
	flat_load_dwordx4 v[60:63], v[168:169]
	flat_load_dwordx4 v[182:185], v[160:161]
	v_lshl_add_u64 v[4:5], v[158:159], 0, v[4:5]
	flat_load_dwordx4 v[186:189], v[160:161] offset:16
	flat_load_dwordx4 v[84:87], v[4:5]
	flat_load_dwordx4 v[76:79], v[4:5] offset:16
	flat_load_dwordx4 v[68:71], v[4:5] offset:32
	flat_load_dwordx4 v[64:67], v[4:5] offset:48
	s_add_i32 s25, s1, 20
	s_and_b32 s25, s25, 0x1ff4
	v_add_u32_e32 v4, s25, v178
	v_ashrrev_i32_e32 v5, 31, v4
	v_add_co_u32_e32 v166, vcc, s22, v162
	v_lshlrev_b64 v[4:5], 9, v[4:5]
	s_add_i32 s25, s1, 24
	v_addc_co_u32_e32 v167, vcc, -1, v163, vcc
	v_lshl_add_u64 v[4:5], v[158:159], 0, v[4:5]
	s_and_b32 s25, s25, 0x1ff8
	flat_load_dwordx4 v[56:59], v[166:167]
	flat_load_dwordx4 v[52:55], v[4:5]
	flat_load_dwordx4 v[48:51], v[4:5] offset:16
	flat_load_dwordx4 v[44:47], v[4:5] offset:32
	flat_load_dwordx4 v[40:43], v[4:5] offset:48
	v_add_u32_e32 v4, s25, v178
	v_ashrrev_i32_e32 v5, 31, v4
	v_add_co_u32_e32 v164, vcc, s23, v162
	v_lshlrev_b64 v[4:5], 9, v[4:5]
	s_add_i32 s25, s1, 28
	v_addc_co_u32_e32 v165, vcc, -1, v163, vcc
	v_lshl_add_u64 v[4:5], v[158:159], 0, v[4:5]
	s_and_b32 s25, s25, 0x1ffc
	flat_load_dwordx4 v[36:39], v[164:165]
	flat_load_dwordx4 v[32:35], v[4:5]
	flat_load_dwordx4 v[28:31], v[4:5] offset:16
	flat_load_dwordx4 v[24:27], v[4:5] offset:32
	flat_load_dwordx4 v[20:23], v[4:5] offset:48
	flat_load_dwordx4 v[16:19], v[162:163]
	v_add_u32_e32 v4, s25, v178
	v_ashrrev_i32_e32 v5, 31, v4
	v_lshlrev_b64 v[4:5], 9, v[4:5]
	s_waitcnt vmcnt(0) lgkmcnt(0)
	v_and_b32_e32 v199, 0xffff0000, v0
	v_lshl_add_u64 v[190:191], v[158:159], 0, v[4:5]
	v_lshlrev_b32_e32 v198, 16, v0
	v_mul_f32_e32 v4, v199, v199
	v_and_b32_e32 v192, 0xffff0000, v1
	v_lshlrev_b32_e32 v193, 16, v1
	v_fmac_f32_e32 v4, v198, v198
	v_pk_mul_f32 v[0:1], v[192:193], v[192:193]
	v_and_b32_e32 v194, 0xffff0000, v2
	v_add_f32_e32 v1, v1, v4
	v_lshlrev_b32_e32 v195, 16, v2
	v_add_f32_e32 v4, v0, v1
	v_pk_mul_f32 v[0:1], v[194:195], v[194:195]
	v_and_b32_e32 v196, 0xffff0000, v3
	v_add_f32_e32 v1, v1, v4
	v_lshlrev_b32_e32 v197, 16, v3
	v_add_f32_e32 v2, v0, v1
	v_pk_mul_f32 v[0:1], v[196:197], v[196:197]
	s_add_i32 s18, s18, s6
	v_add_f32_e32 v1, v1, v2
	v_add_f32_e32 v0, v0, v1
	s_add_i32 s1, s1, s3
	s_cmpk_lt_i32 s18, 0x2000
	v_add_f32_dpp v0, v0, v0 quad_perm:[1,0,3,2] row_mask:0xf bank_mask:0xf bound_ctrl:1
	s_nop 1
	v_add_f32_dpp v0, v0, v0 quad_perm:[2,3,0,1] row_mask:0xf bank_mask:0xf bound_ctrl:1
	s_nop 1
	v_add_f32_dpp v0, v0, v0 row_half_mirror row_mask:0xf bank_mask:0xf bound_ctrl:1
	s_nop 1
	v_add_f32_dpp v0, v0, v0 row_mirror row_mask:0xf bank_mask:0xf bound_ctrl:1
	v_fmamk_f32 v0, v0, 0x3c000000, v157
	v_mul_f32_e32 v1, 0x4b800000, v0
	v_cmp_gt_f32_e32 vcc, s24, v0
	s_nop 1
	v_cndmask_b32_e32 v0, v0, v1, vcc
	v_rsq_f32_e32 v200, v0
	flat_load_dwordx4 v[12:15], v[190:191]
	flat_load_dwordx4 v[8:11], v[190:191] offset:16
	flat_load_dwordx4 v[4:7], v[190:191] offset:32
	flat_load_dwordx4 v[0:3], v[190:191] offset:48
	v_mul_f32_e32 v190, 0x45800000, v200
	v_cndmask_b32_e32 v190, v200, v190, vcc
	v_mul_f32_e32 v186, v186, v190
	v_mul_f32_e32 v186, v186, v195
	v_mul_f32_e32 v187, v187, v190
	v_mul_f32_e32 v187, v187, v194
	v_mul_f32_dpp v145, v186, v145 row_ror:8 row_mask:0xf bank_mask:0xf bound_ctrl:1
	v_mul_f32_e32 v188, v188, v190
	v_cndmask_b32_e64 v145, v145, -v145, s[4:5]
	v_mul_f32_e32 v182, v182, v190
	v_mul_f32_e32 v184, v184, v190
; __device__ __forceinline__ unsigned cvt_pk_bf16(float lo, float hi) { unsigned r; asm volatile("v_cvt_pk_bf16_f32 %0, %1, %2" : "=v"(r) : "v"(lo), "v"(hi)); return r; }
; __device__ __forceinline__ float bflo(unsigned w) { return __uint_as_float(w << 16); }
; __device__ __forceinline__ float bfhi(unsigned w) { return __uint_as_float(w & 0xffff0000u); }
; __device__ __forceinline__ float shx(float v, int m, int lane) { return __int_as_float(__builtin_amdgcn_ds_bpermute((lane ^ m) << 2, __float_as_int(v))); }
; #define DPPF(v, ctrl) __int_as_float(__builtin_amdgcn_update_dpp(0, __float_as_int(v), (ctrl), 0xf, 0xf, false))
; __device__ __forceinline__ float row16_sum(float x) { x += DPPF(x, 0xB1); x += DPPF(x, 0x4E); x += DPPF(x, 0x141); x += DPPF(x, 0x140); return x; }
; template <bool NORM, int ROT> __device__ __forceinline__ void rope_chunk(bf16_t* p, const u32x4 w, const f32x4 (&tb)[4], const float* g, float sc, int lane) {
;     const int j = lane & 15;
;     float x[8] = {bflo(w.x), bfhi(w.x), bflo(w.y), bfhi(w.y), bflo(w.z), bfhi(w.z), bflo(w.w), bfhi(w.w)};
;     if (NORM) {
;         float ss = 0.f;
; #pragma unroll
;         for (int q = 0; q < 8; ++q) ss += x[q] * x[q];
;         ss = row16_sum(ss);
;         const float rstd = rsqrtf(ss * (1.f / 128.f) + EPS);
;         const f32x4 g0 = *(const f32x4*)(g + j * 8), g1 = *(const f32x4*)(g + j * 8 + 4);
; #pragma unroll
;         for (int q = 0; q < 4; ++q) { x[q] *= rstd * g0[q]; x[4 + q] *= rstd * g1[q]; }
;     }
;     constexpr int HALFL = ROT / 16;
;     const bool rot = (ROT == 128) || (j < 8); const bool first = (j & HALFL) == 0;
;     float o[8];
; #pragma unroll
;     for (int q = 0; q < 8; ++q) {
;         const float other = (ROT == 128) ? DPPF(x[q], 0x128)   : shx(x[q], HALFL, lane);
;         const float cs = tb[q >> 1][(q & 1) * 2], sn = tb[q >> 1][(q & 1) * 2 + 1];
;         const float r = first ? (x[q] * cs - other * sn) : (x[q] * cs + other * sn);
;         o[q] = (rot ? r : x[q]) * sc;
;     }
;     u32x4 ow; ow.x = cvt_pk_bf16(o[0], o[1]); ow.y = cvt_pk_bf16(o[2], o[3]); ow.z = cvt_pk_bf16(o[4], o[5]); ow.w = cvt_pk_bf16(o[6], o[7]);
;     *(u32x4*)(p + lane * 8) = ow;
; }
	v_mul_f32_e32 v188, v188, v197
	v_fmac_f32_e32 v145, v144, v186
	v_mul_f32_dpp v144, v187, v147 row_ror:8 row_mask:0xf bank_mask:0xf bound_ctrl:1
	v_mul_f32_e32 v182, v182, v198
	v_mul_f32_e32 v184, v184, v193
	v_mul_f32_e32 v189, v189, v190
	v_cndmask_b32_e64 v144, v144, -v144, s[4:5]
	v_mul_f32_dpp v141, v188, v141 row_ror:8 row_mask:0xf bank_mask:0xf bound_ctrl:1
	v_mul_f32_e32 v183, v183, v190
	v_mul_f32_e32 v185, v185, v190
	v_mul_f32_e32 v189, v189, v196
	v_mul_f32_dpp v153, v182, v153 row_ror:8 row_mask:0xf bank_mask:0xf bound_ctrl:1
	v_mul_f32_dpp v149, v184, v149 row_ror:8 row_mask:0xf bank_mask:0xf bound_ctrl:1
	v_fmac_f32_e32 v144, v146, v187
	v_cndmask_b32_e64 v146, v141, -v141, s[4:5]
	v_mul_f32_e32 v183, v183, v199
	v_mul_f32_e32 v185, v185, v192
	v_cndmask_b32_e64 v153, v153, -v153, s[4:5]
	v_cndmask_b32_e64 v149, v149, -v149, s[4:5]
	v_fmac_f32_e32 v146, v140, v188
	v_mul_f32_dpp v140, v189, v143 row_ror:8 row_mask:0xf bank_mask:0xf bound_ctrl:1
	v_fmac_f32_e32 v153, v152, v182
	v_mul_f32_dpp v152, v183, v155 row_ror:8 row_mask:0xf bank_mask:0xf bound_ctrl:1
	v_fmac_f32_e32 v149, v148, v184
	v_mul_f32_dpp v148, v185, v151 row_ror:8 row_mask:0xf bank_mask:0xf bound_ctrl:1
	v_cndmask_b32_e64 v143, v140, -v140, s[4:5]
	v_cndmask_b32_e64 v152, v152, -v152, s[4:5]
	v_cndmask_b32_e64 v148, v148, -v148, s[4:5]
	v_fmac_f32_e32 v143, v142, v189
	v_fmac_f32_e32 v152, v154, v183
	v_fmac_f32_e32 v148, v150, v185
	v_cvt_pk_bf16_f32 v140, v153, v152
	v_cvt_pk_bf16_f32 v141, v149, v148
	v_cvt_pk_bf16_f32 v142, v145, v144
	v_cvt_pk_bf16_f32 v143, v146, v143
	flat_store_dwordx4 v[176:177], v[140:143]
	flat_load_dwordx4 v[140:143], v[160:161]
	s_nop 0
	flat_load_dwordx4 v[144:147], v[160:161] offset:16
	v_and_b32_e32 v153, 0xffff0000, v136
	v_lshlrev_b32_e32 v152, 16, v136
	v_mul_f32_e32 v150, v153, v153
	v_and_b32_e32 v136, 0xffff0000, v137
	v_lshlrev_b32_e32 v137, 16, v137
	v_fmac_f32_e32 v150, v152, v152
	v_pk_mul_f32 v[148:149], v[136:137], v[136:137]
	s_nop 0
	v_add_f32_e32 v149, v149, v150
	v_add_f32_e32 v154, v148, v149
	v_and_b32_e32 v148, 0xffff0000, v138
	v_lshlrev_b32_e32 v149, 16, v138
	v_pk_mul_f32 v[150:151], v[148:149], v[148:149]
	s_nop 0
	v_add_f32_e32 v138, v151, v154
	v_add_f32_e32 v154, v150, v138
	v_and_b32_e32 v138, 0xffff0000, v139
	v_lshlrev_b32_e32 v139, 16, v139
	v_pk_mul_f32 v[150:151], v[138:139], v[138:139]
	s_nop 0
	v_add_f32_e32 v151, v151, v154
	v_add_f32_e32 v150, v150, v151
	s_nop 1
	v_add_f32_dpp v150, v150, v150 quad_perm:[1,0,3,2] row_mask:0xf bank_mask:0xf bound_ctrl:1
	s_nop 1
	v_add_f32_dpp v150, v150, v150 quad_perm:[2,3,0,1] row_mask:0xf bank_mask:0xf bound_ctrl:1
	s_nop 1
	v_add_f32_dpp v150, v150, v150 row_half_mirror row_mask:0xf bank_mask:0xf bound_ctrl:1
	s_nop 1
	v_add_f32_dpp v150, v150, v150 row_mirror row_mask:0xf bank_mask:0xf bound_ctrl:1
	v_fmamk_f32 v150, v150, 0x3c000000, v157
	v_mul_f32_e32 v151, 0x4b800000, v150
	v_cmp_gt_f32_e32 vcc, s24, v150
	s_nop 1
	v_cndmask_b32_e32 v150, v150, v151, vcc
	v_rsq_f32_e32 v150, v150
	s_nop 0
	v_mul_f32_e32 v151, 0x45800000, v150
	v_cndmask_b32_e32 v150, v150, v151, vcc
	s_waitcnt vmcnt(0) lgkmcnt(0)
	v_mul_f32_e32 v142, v142, v150
	v_mul_f32_e32 v144, v144, v150
	v_mul_f32_e32 v144, v144, v149
	v_mul_f32_e32 v145, v145, v150
	v_mul_f32_e32 v145, v145, v148
	v_mul_f32_dpp v125, v144, v125 row_ror:8 row_mask:0xf bank_mask:0xf bound_ctrl:1
	v_mul_f32_e32 v137, v142, v137
	v_mul_f32_e32 v142, v146, v150
	v_cndmask_b32_e64 v125, v125, -v125, s[4:5]
	v_mul_f32_e32 v140, v140, v150
	v_mul_f32_e32 v139, v142, v139
	v_mul_f32_e32 v142, v143, v150
	v_fmac_f32_e32 v125, v124, v144
	v_mul_f32_dpp v124, v145, v127 row_ror:8 row_mask:0xf bank_mask:0xf bound_ctrl:1
	v_mul_f32_e32 v140, v140, v152
	v_mul_f32_e32 v136, v142, v136
	v_mul_f32_e32 v142, v147, v150
	v_cndmask_b32_e64 v124, v124, -v124, s[4:5]
	v_mul_f32_dpp v121, v139, v121 row_ror:8 row_mask:0xf bank_mask:0xf bound_ctrl:1
	v_mul_f32_e32 v141, v141, v150
	v_mul_f32_e32 v138, v142, v138
	v_mul_f32_dpp v133, v140, v133 row_ror:8 row_mask:0xf bank_mask:0xf bound_ctrl:1
	v_mul_f32_dpp v129, v137, v129 row_ror:8 row_mask:0xf bank_mask:0xf bound_ctrl:1
	v_fmac_f32_e32 v124, v126, v145
	v_cndmask_b32_e64 v126, v121, -v121, s[4:5]
	v_mul_f32_e32 v141, v141, v153
	v_cndmask_b32_e64 v133, v133, -v133, s[4:5]
	v_cndmask_b32_e64 v129, v129, -v129, s[4:5]
	v_fmac_f32_e32 v126, v120, v139
	v_mul_f32_dpp v120, v138, v123 row_ror:8 row_mask:0xf bank_mask:0xf bound_ctrl:1
	v_fmac_f32_e32 v133, v132, v140
	v_mul_f32_dpp v132, v141, v135 row_ror:8 row_mask:0xf bank_mask:0xf bound_ctrl:1
	v_fmac_f32_e32 v129, v128, v137
	v_mul_f32_dpp v128, v136, v131 row_ror:8 row_mask:0xf bank_mask:0xf bound_ctrl:1
	v_cndmask_b32_e64 v123, v120, -v120, s[4:5]
	v_cndmask_b32_e64 v132, v132, -v132, s[4:5]
	v_cndmask_b32_e64 v128, v128, -v128, s[4:5]
	v_fmac_f32_e32 v123, v122, v138
	v_fmac_f32_e32 v132, v134, v141
	v_fmac_f32_e32 v128, v130, v136
	v_cvt_pk_bf16_f32 v120, v133, v132
	v_cvt_pk_bf16_f32 v121, v129, v128
	v_cvt_pk_bf16_f32 v122, v125, v124
	v_cvt_pk_bf16_f32 v123, v126, v123
	flat_store_dwordx4 v[174:175], v[120:123]
	flat_load_dwordx4 v[120:123], v[160:161]
	s_nop 0
	flat_load_dwordx4 v[124:127], v[160:161] offset:16
	v_and_b32_e32 v133, 0xffff0000, v116
	v_lshlrev_b32_e32 v132, 16, v116
	v_mul_f32_e32 v130, v133, v133
	v_and_b32_e32 v116, 0xffff0000, v117
	v_lshlrev_b32_e32 v117, 16, v117
	v_fmac_f32_e32 v130, v132, v132
	v_pk_mul_f32 v[128:129], v[116:117], v[116:117]
	s_nop 0
	v_add_f32_e32 v129, v129, v130
	v_add_f32_e32 v134, v128, v129
	v_and_b32_e32 v128, 0xffff0000, v118
	v_lshlrev_b32_e32 v129, 16, v118
	v_pk_mul_f32 v[130:131], v[128:129], v[128:129]
	s_nop 0
	v_add_f32_e32 v118, v131, v134
	v_add_f32_e32 v134, v130, v118
	v_and_b32_e32 v118, 0xffff0000, v119
	v_lshlrev_b32_e32 v119, 16, v119
	v_pk_mul_f32 v[130:131], v[118:119], v[118:119]
	s_nop 0
	v_add_f32_e32 v131, v131, v134
	v_add_f32_e32 v130, v130, v131
	s_nop 1
	v_add_f32_dpp v130, v130, v130 quad_perm:[1,0,3,2] row_mask:0xf bank_mask:0xf bound_ctrl:1
	s_nop 1
	v_add_f32_dpp v130, v130, v130 quad_perm:[2,3,0,1] row_mask:0xf bank_mask:0xf bound_ctrl:1
	s_nop 1
	v_add_f32_dpp v130, v130, v130 row_half_mirror row_mask:0xf bank_mask:0xf bound_ctrl:1
	s_nop 1
	v_add_f32_dpp v130, v130, v130 row_mirror row_mask:0xf bank_mask:0xf bound_ctrl:1
	v_fmamk_f32 v130, v130, 0x3c000000, v157
	v_mul_f32_e32 v131, 0x4b800000, v130
	v_cmp_gt_f32_e32 vcc, s24, v130
	s_nop 1
	v_cndmask_b32_e32 v130, v130, v131, vcc
	v_rsq_f32_e32 v130, v130
	s_nop 0
	v_mul_f32_e32 v131, 0x45800000, v130
	v_cndmask_b32_e32 v130, v130, v131, vcc
	s_waitcnt vmcnt(0) lgkmcnt(0)
; __device__ __forceinline__ unsigned cvt_pk_bf16(float lo, float hi) { unsigned r; asm volatile("v_cvt_pk_bf16_f32 %0, %1, %2" : "=v"(r) : "v"(lo), "v"(hi)); return r; }
; __device__ __forceinline__ float bflo(unsigned w) { return __uint_as_float(w << 16); }
; __device__ __forceinline__ float bfhi(unsigned w) { return __uint_as_float(w & 0xffff0000u); }
; __device__ __forceinline__ float shx(float v, int m, int lane) { return __int_as_float(__builtin_amdgcn_ds_bpermute((lane ^ m) << 2, __float_as_int(v))); }
; #define DPPF(v, ctrl) __int_as_float(__builtin_amdgcn_update_dpp(0, __float_as_int(v), (ctrl), 0xf, 0xf, false))
; __device__ __forceinline__ float row16_sum(float x) { x += DPPF(x, 0xB1); x += DPPF(x, 0x4E); x += DPPF(x, 0x141); x += DPPF(x, 0x140); return x; }
; template <bool NORM, int ROT> __device__ __forceinline__ void rope_chunk(bf16_t* p, const u32x4 w, const f32x4 (&tb)[4], const float* g, float sc, int lane) {
;     const int j = lane & 15;
;     float x[8] = {bflo(w.x), bfhi(w.x), bflo(w.y), bfhi(w.y), bflo(w.z), bfhi(w.z), bflo(w.w), bfhi(w.w)};
;     if (NORM) {
;         float ss = 0.f;
; #pragma unroll
;         for (int q = 0; q < 8; ++q) ss += x[q] * x[q];
;         ss = row16_sum(ss);
;         const float rstd = rsqrtf(ss * (1.f / 128.f) + EPS);
;         const f32x4 g0 = *(const f32x4*)(g + j * 8), g1 = *(const f32x4*)(g + j * 8 + 4);
; #pragma unroll
;         for (int q = 0; q < 4; ++q) { x[q] *= rstd * g0[q]; x[4 + q] *= rstd * g1[q]; }
;     }
;     constexpr int HALFL = ROT / 16;
;     const bool rot = (ROT == 128) || (j < 8); const bool first = (j & HALFL) == 0;
;     float o[8];
; #pragma unroll
;     for (int q = 0; q < 8; ++q) {
;         const float other = (ROT == 128) ? DPPF(x[q], 0x128)   : shx(x[q], HALFL, lane);
;         const float cs = tb[q >> 1][(q & 1) * 2], sn = tb[q >> 1][(q & 1) * 2 + 1];
;         const float r = first ? (x[q] * cs - other * sn) : (x[q] * cs + other * sn);
;         o[q] = (rot ? r : x[q]) * sc;
;     }
;     u32x4 ow; ow.x = cvt_pk_bf16(o[0], o[1]); ow.y = cvt_pk_bf16(o[2], o[3]); ow.z = cvt_pk_bf16(o[4], o[5]); ow.w = cvt_pk_bf16(o[6], o[7]);
;     *(u32x4*)(p + lane * 8) = ow;
; }
	v_mul_f32_e32 v122, v122, v130
	v_mul_f32_e32 v124, v124, v130
	v_mul_f32_e32 v124, v124, v129
	v_mul_f32_e32 v125, v125, v130
	v_mul_f32_e32 v125, v125, v128
	v_mul_f32_dpp v105, v124, v105 row_ror:8 row_mask:0xf bank_mask:0xf bound_ctrl:1
	v_mul_f32_e32 v117, v122, v117
	v_mul_f32_e32 v122, v126, v130
	v_cndmask_b32_e64 v105, v105, -v105, s[4:5]
	v_mul_f32_e32 v120, v120, v130
	v_mul_f32_e32 v119, v122, v119
	v_mul_f32_e32 v122, v123, v130
	v_fmac_f32_e32 v105, v104, v124
	v_mul_f32_dpp v104, v125, v107 row_ror:8 row_mask:0xf bank_mask:0xf bound_ctrl:1
	v_mul_f32_e32 v120, v120, v132
	v_mul_f32_e32 v116, v122, v116
	v_mul_f32_e32 v122, v127, v130
	v_cndmask_b32_e64 v104, v104, -v104, s[4:5]
	v_mul_f32_dpp v101, v119, v101 row_ror:8 row_mask:0xf bank_mask:0xf bound_ctrl:1
	v_mul_f32_e32 v121, v121, v130
	v_mul_f32_e32 v118, v122, v118
	v_mul_f32_dpp v113, v120, v113 row_ror:8 row_mask:0xf bank_mask:0xf bound_ctrl:1
	v_mul_f32_dpp v109, v117, v109 row_ror:8 row_mask:0xf bank_mask:0xf bound_ctrl:1
	v_fmac_f32_e32 v104, v106, v125
	v_cndmask_b32_e64 v106, v101, -v101, s[4:5]
	v_mul_f32_e32 v121, v121, v133
	v_cndmask_b32_e64 v113, v113, -v113, s[4:5]
	v_cndmask_b32_e64 v109, v109, -v109, s[4:5]
	v_fmac_f32_e32 v106, v100, v119
	v_mul_f32_dpp v100, v118, v103 row_ror:8 row_mask:0xf bank_mask:0xf bound_ctrl:1
	v_fmac_f32_e32 v113, v112, v120
	v_mul_f32_dpp v112, v121, v115 row_ror:8 row_mask:0xf bank_mask:0xf bound_ctrl:1
	v_fmac_f32_e32 v109, v108, v117
	v_mul_f32_dpp v108, v116, v111 row_ror:8 row_mask:0xf bank_mask:0xf bound_ctrl:1
	v_cndmask_b32_e64 v103, v100, -v100, s[4:5]
	v_cndmask_b32_e64 v112, v112, -v112, s[4:5]
	v_cndmask_b32_e64 v108, v108, -v108, s[4:5]
	v_fmac_f32_e32 v103, v102, v118
	v_fmac_f32_e32 v112, v114, v121
	v_fmac_f32_e32 v108, v110, v116
	v_cvt_pk_bf16_f32 v100, v113, v112
	v_cvt_pk_bf16_f32 v101, v109, v108
	v_cvt_pk_bf16_f32 v102, v105, v104
	v_cvt_pk_bf16_f32 v103, v106, v103
	flat_store_dwordx4 v[172:173], v[100:103]
	flat_load_dwordx4 v[100:103], v[160:161]
	s_nop 0
	flat_load_dwordx4 v[104:107], v[160:161] offset:16
	v_and_b32_e32 v113, 0xffff0000, v96
	v_lshlrev_b32_e32 v112, 16, v96
	v_mul_f32_e32 v110, v113, v113
	v_and_b32_e32 v96, 0xffff0000, v97
	v_lshlrev_b32_e32 v97, 16, v97
	v_fmac_f32_e32 v110, v112, v112
	v_pk_mul_f32 v[108:109], v[96:97], v[96:97]
	s_nop 0
	v_add_f32_e32 v109, v109, v110
	v_add_f32_e32 v114, v108, v109
	v_and_b32_e32 v108, 0xffff0000, v98
	v_lshlrev_b32_e32 v109, 16, v98
	v_pk_mul_f32 v[110:111], v[108:109], v[108:109]
	s_nop 0
	v_add_f32_e32 v98, v111, v114
	v_add_f32_e32 v114, v110, v98
	v_and_b32_e32 v98, 0xffff0000, v99
	v_lshlrev_b32_e32 v99, 16, v99
	v_pk_mul_f32 v[110:111], v[98:99], v[98:99]
	s_nop 0
	v_add_f32_e32 v111, v111, v114
	v_add_f32_e32 v110, v110, v111
	s_nop 1
	v_add_f32_dpp v110, v110, v110 quad_perm:[1,0,3,2] row_mask:0xf bank_mask:0xf bound_ctrl:1
	s_nop 1
	v_add_f32_dpp v110, v110, v110 quad_perm:[2,3,0,1] row_mask:0xf bank_mask:0xf bound_ctrl:1
	s_nop 1
	v_add_f32_dpp v110, v110, v110 row_half_mirror row_mask:0xf bank_mask:0xf bound_ctrl:1
	s_nop 1
	v_add_f32_dpp v110, v110, v110 row_mirror row_mask:0xf bank_mask:0xf bound_ctrl:1
	v_fmamk_f32 v110, v110, 0x3c000000, v157
	v_mul_f32_e32 v111, 0x4b800000, v110
	v_cmp_gt_f32_e32 vcc, s24, v110
	s_nop 1
	v_cndmask_b32_e32 v110, v110, v111, vcc
	v_rsq_f32_e32 v110, v110
	s_nop 0
	v_mul_f32_e32 v111, 0x45800000, v110
	v_cndmask_b32_e32 v110, v110, v111, vcc
	s_waitcnt vmcnt(0) lgkmcnt(0)
	v_mul_f32_e32 v102, v102, v110
	v_mul_f32_e32 v104, v104, v110
	v_mul_f32_e32 v104, v104, v109
	v_mul_f32_e32 v105, v105, v110
	v_mul_f32_e32 v105, v105, v108
	v_mul_f32_dpp v81, v104, v81 row_ror:8 row_mask:0xf bank_mask:0xf bound_ctrl:1
	v_mul_f32_e32 v97, v102, v97
	v_mul_f32_e32 v102, v106, v110
	v_cndmask_b32_e64 v81, v81, -v81, s[4:5]
	v_mul_f32_e32 v100, v100, v110
	v_mul_f32_e32 v99, v102, v99
	v_mul_f32_e32 v102, v103, v110
	v_fmac_f32_e32 v81, v80, v104
	v_mul_f32_dpp v80, v105, v83 row_ror:8 row_mask:0xf bank_mask:0xf bound_ctrl:1
	v_mul_f32_e32 v100, v100, v112
	v_mul_f32_e32 v96, v102, v96
	v_mul_f32_e32 v102, v107, v110
	v_cndmask_b32_e64 v80, v80, -v80, s[4:5]
	v_mul_f32_dpp v73, v99, v73 row_ror:8 row_mask:0xf bank_mask:0xf bound_ctrl:1
	v_mul_f32_e32 v101, v101, v110
	v_mul_f32_e32 v98, v102, v98
	v_mul_f32_dpp v93, v100, v93 row_ror:8 row_mask:0xf bank_mask:0xf bound_ctrl:1
	v_mul_f32_dpp v89, v97, v89 row_ror:8 row_mask:0xf bank_mask:0xf bound_ctrl:1
	v_fmac_f32_e32 v80, v82, v105
	v_cndmask_b32_e64 v82, v73, -v73, s[4:5]
	v_mul_f32_e32 v101, v101, v113
	v_cndmask_b32_e64 v93, v93, -v93, s[4:5]
	v_cndmask_b32_e64 v89, v89, -v89, s[4:5]
	v_fmac_f32_e32 v82, v72, v99
	v_mul_f32_dpp v72, v98, v75 row_ror:8 row_mask:0xf bank_mask:0xf bound_ctrl:1
	v_fmac_f32_e32 v93, v92, v100
	v_mul_f32_dpp v92, v101, v95 row_ror:8 row_mask:0xf bank_mask:0xf bound_ctrl:1
	v_fmac_f32_e32 v89, v88, v97
	v_mul_f32_dpp v88, v96, v91 row_ror:8 row_mask:0xf bank_mask:0xf bound_ctrl:1
	v_cndmask_b32_e64 v75, v72, -v72, s[4:5]
	v_cndmask_b32_e64 v92, v92, -v92, s[4:5]
	v_cndmask_b32_e64 v88, v88, -v88, s[4:5]
	v_fmac_f32_e32 v75, v74, v98
	v_fmac_f32_e32 v92, v94, v101
	v_fmac_f32_e32 v88, v90, v96
	v_cvt_pk_bf16_f32 v72, v93, v92
	v_cvt_pk_bf16_f32 v73, v89, v88
	v_cvt_pk_bf16_f32 v74, v81, v80
	v_cvt_pk_bf16_f32 v75, v82, v75
	flat_store_dwordx4 v[170:171], v[72:75]
	flat_load_dwordx4 v[72:75], v[160:161]
	s_nop 0
	flat_load_dwordx4 v[80:83], v[160:161] offset:16
	v_and_b32_e32 v93, 0xffff0000, v60
	v_lshlrev_b32_e32 v92, 16, v60
	v_mul_f32_e32 v90, v93, v93
	v_and_b32_e32 v60, 0xffff0000, v61
	v_lshlrev_b32_e32 v61, 16, v61
	v_fmac_f32_e32 v90, v92, v92
	v_pk_mul_f32 v[88:89], v[60:61], v[60:61]
	s_nop 0
	v_add_f32_e32 v89, v89, v90
	v_add_f32_e32 v94, v88, v89
	v_and_b32_e32 v88, 0xffff0000, v62
	v_lshlrev_b32_e32 v89, 16, v62
	v_pk_mul_f32 v[90:91], v[88:89], v[88:89]
	s_nop 0
	v_add_f32_e32 v62, v91, v94
	v_add_f32_e32 v94, v90, v62
	v_and_b32_e32 v62, 0xffff0000, v63
	v_lshlrev_b32_e32 v63, 16, v63
	v_pk_mul_f32 v[90:91], v[62:63], v[62:63]
	s_nop 0
	v_add_f32_e32 v91, v91, v94
	v_add_f32_e32 v90, v90, v91
	s_nop 1
	v_add_f32_dpp v90, v90, v90 quad_perm:[1,0,3,2] row_mask:0xf bank_mask:0xf bound_ctrl:1
	s_nop 1
	v_add_f32_dpp v90, v90, v90 quad_perm:[2,3,0,1] row_mask:0xf bank_mask:0xf bound_ctrl:1
	s_nop 1
	v_add_f32_dpp v90, v90, v90 row_half_mirror row_mask:0xf bank_mask:0xf bound_ctrl:1
	s_nop 1
	v_add_f32_dpp v90, v90, v90 row_mirror row_mask:0xf bank_mask:0xf bound_ctrl:1
	v_fmamk_f32 v90, v90, 0x3c000000, v157
	v_mul_f32_e32 v91, 0x4b800000, v90
	v_cmp_gt_f32_e32 vcc, s24, v90
	s_nop 1
	v_cndmask_b32_e32 v90, v90, v91, vcc
	v_rsq_f32_e32 v90, v90
	s_nop 0
	v_mul_f32_e32 v91, 0x45800000, v90
	v_cndmask_b32_e32 v90, v90, v91, vcc
	s_waitcnt vmcnt(0) lgkmcnt(0)
; __device__ __forceinline__ unsigned cvt_pk_bf16(float lo, float hi) { unsigned r; asm volatile("v_cvt_pk_bf16_f32 %0, %1, %2" : "=v"(r) : "v"(lo), "v"(hi)); return r; }
; __device__ __forceinline__ float bflo(unsigned w) { return __uint_as_float(w << 16); }
; __device__ __forceinline__ float bfhi(unsigned w) { return __uint_as_float(w & 0xffff0000u); }
; __device__ __forceinline__ float shx(float v, int m, int lane) { return __int_as_float(__builtin_amdgcn_ds_bpermute((lane ^ m) << 2, __float_as_int(v))); }
; #define DPPF(v, ctrl) __int_as_float(__builtin_amdgcn_update_dpp(0, __float_as_int(v), (ctrl), 0xf, 0xf, false))
; __device__ __forceinline__ float row16_sum(float x) { x += DPPF(x, 0xB1); x += DPPF(x, 0x4E); x += DPPF(x, 0x141); x += DPPF(x, 0x140); return x; }
; template <bool NORM, int ROT> __device__ __forceinline__ void rope_chunk(bf16_t* p, const u32x4 w, const f32x4 (&tb)[4], const float* g, float sc, int lane) {
;     const int j = lane & 15;
;     float x[8] = {bflo(w.x), bfhi(w.x), bflo(w.y), bfhi(w.y), bflo(w.z), bfhi(w.z), bflo(w.w), bfhi(w.w)};
;     if (NORM) {
;         float ss = 0.f;
; #pragma unroll
;         for (int q = 0; q < 8; ++q) ss += x[q] * x[q];
;         ss = row16_sum(ss);
;         const float rstd = rsqrtf(ss * (1.f / 128.f) + EPS);
;         const f32x4 g0 = *(const f32x4*)(g + j * 8), g1 = *(const f32x4*)(g + j * 8 + 4);
; #pragma unroll
;         for (int q = 0; q < 4; ++q) { x[q] *= rstd * g0[q]; x[4 + q] *= rstd * g1[q]; }
;     }
;     constexpr int HALFL = ROT / 16;
;     const bool rot = (ROT == 128) || (j < 8); const bool first = (j & HALFL) == 0;
;     float o[8];
; #pragma unroll
;     for (int q = 0; q < 8; ++q) {
;         const float other = (ROT == 128) ? DPPF(x[q], 0x128)   : shx(x[q], HALFL, lane);
;         const float cs = tb[q >> 1][(q & 1) * 2], sn = tb[q >> 1][(q & 1) * 2 + 1];
;         const float r = first ? (x[q] * cs - other * sn) : (x[q] * cs + other * sn);
;         o[q] = (rot ? r : x[q]) * sc;
;     }
;     u32x4 ow; ow.x = cvt_pk_bf16(o[0], o[1]); ow.y = cvt_pk_bf16(o[2], o[3]); ow.z = cvt_pk_bf16(o[4], o[5]); ow.w = cvt_pk_bf16(o[6], o[7]);
;     *(u32x4*)(p + lane * 8) = ow;
; }
	v_mul_f32_e32 v74, v74, v90
	v_mul_f32_e32 v61, v74, v61
	v_mul_f32_e32 v74, v82, v90
	v_mul_f32_e32 v72, v72, v90
	v_mul_f32_e32 v63, v74, v63
	v_mul_f32_e32 v74, v75, v90
	v_mul_f32_e32 v72, v72, v92
	v_mul_f32_e32 v60, v74, v60
	v_mul_f32_e32 v74, v83, v90
	v_mul_f32_e32 v73, v73, v90
	v_mul_f32_e32 v62, v74, v62
	v_mul_f32_dpp v74, v72, v85 row_ror:8 row_mask:0xf bank_mask:0xf bound_ctrl:1
	v_mul_f32_e32 v73, v73, v93
	v_cndmask_b32_e64 v74, v74, -v74, s[4:5]
	v_fmac_f32_e32 v74, v84, v72
	v_mul_f32_dpp v72, v73, v87 row_ror:8 row_mask:0xf bank_mask:0xf bound_ctrl:1
	v_cndmask_b32_e64 v72, v72, -v72, s[4:5]
	v_fmac_f32_e32 v72, v86, v73
	v_mul_f32_dpp v73, v61, v77 row_ror:8 row_mask:0xf bank_mask:0xf bound_ctrl:1
	v_cndmask_b32_e64 v73, v73, -v73, s[4:5]
	v_mul_f32_e32 v80, v80, v90
	v_fmac_f32_e32 v73, v76, v61
	v_mul_f32_dpp v61, v60, v79 row_ror:8 row_mask:0xf bank_mask:0xf bound_ctrl:1
	v_mul_f32_e32 v80, v80, v89
	v_mul_f32_e32 v81, v81, v90
	v_cndmask_b32_e64 v61, v61, -v61, s[4:5]
	v_mul_f32_e32 v81, v81, v88
	v_fmac_f32_e32 v61, v78, v60
	v_mul_f32_dpp v60, v80, v69 row_ror:8 row_mask:0xf bank_mask:0xf bound_ctrl:1
	v_cndmask_b32_e64 v69, v60, -v60, s[4:5]
	v_fmac_f32_e32 v69, v68, v80
	v_mul_f32_dpp v60, v81, v71 row_ror:8 row_mask:0xf bank_mask:0xf bound_ctrl:1
	v_cndmask_b32_e64 v68, v60, -v60, s[4:5]
	v_fmac_f32_e32 v68, v70, v81
	v_mul_f32_dpp v60, v63, v65 row_ror:8 row_mask:0xf bank_mask:0xf bound_ctrl:1
	v_cndmask_b32_e64 v65, v60, -v60, s[4:5]
	v_fmac_f32_e32 v65, v64, v63
	v_mul_f32_dpp v60, v62, v67 row_ror:8 row_mask:0xf bank_mask:0xf bound_ctrl:1
	v_cndmask_b32_e64 v63, v60, -v60, s[4:5]
	v_fmac_f32_e32 v63, v66, v62
	v_cvt_pk_bf16_f32 v60, v74, v72
	v_cvt_pk_bf16_f32 v61, v73, v61
	v_cvt_pk_bf16_f32 v62, v69, v68
	v_cvt_pk_bf16_f32 v63, v65, v63
	flat_store_dwordx4 v[168:169], v[60:63]
	flat_load_dwordx4 v[60:63], v[160:161]
	s_nop 0
	flat_load_dwordx4 v[64:67], v[160:161] offset:16
	v_and_b32_e32 v73, 0xffff0000, v56
	v_lshlrev_b32_e32 v72, 16, v56
	v_mul_f32_e32 v70, v73, v73
	v_and_b32_e32 v56, 0xffff0000, v57
	v_lshlrev_b32_e32 v57, 16, v57
	v_fmac_f32_e32 v70, v72, v72
	v_pk_mul_f32 v[68:69], v[56:57], v[56:57]
	s_nop 0
	v_add_f32_e32 v69, v69, v70
	v_add_f32_e32 v74, v68, v69
	v_and_b32_e32 v68, 0xffff0000, v58
	v_lshlrev_b32_e32 v69, 16, v58
	v_pk_mul_f32 v[70:71], v[68:69], v[68:69]
	s_nop 0
	v_add_f32_e32 v58, v71, v74
	v_add_f32_e32 v74, v70, v58
	v_and_b32_e32 v58, 0xffff0000, v59
	v_lshlrev_b32_e32 v59, 16, v59
	v_pk_mul_f32 v[70:71], v[58:59], v[58:59]
	s_nop 0
	v_add_f32_e32 v71, v71, v74
	v_add_f32_e32 v70, v70, v71
	s_nop 1
	v_add_f32_dpp v70, v70, v70 quad_perm:[1,0,3,2] row_mask:0xf bank_mask:0xf bound_ctrl:1
	s_nop 1
	v_add_f32_dpp v70, v70, v70 quad_perm:[2,3,0,1] row_mask:0xf bank_mask:0xf bound_ctrl:1
	s_nop 1
	v_add_f32_dpp v70, v70, v70 row_half_mirror row_mask:0xf bank_mask:0xf bound_ctrl:1
	s_nop 1
	v_add_f32_dpp v70, v70, v70 row_mirror row_mask:0xf bank_mask:0xf bound_ctrl:1
	v_fmamk_f32 v70, v70, 0x3c000000, v157
	v_mul_f32_e32 v71, 0x4b800000, v70
	v_cmp_gt_f32_e32 vcc, s24, v70
	s_nop 1
	v_cndmask_b32_e32 v70, v70, v71, vcc
	v_rsq_f32_e32 v70, v70
	s_nop 0
	v_mul_f32_e32 v71, 0x45800000, v70
	v_cndmask_b32_e32 v70, v70, v71, vcc
	s_waitcnt vmcnt(0) lgkmcnt(0)
	v_mul_f32_e32 v62, v62, v70
	v_mul_f32_e32 v64, v64, v70
	v_mul_f32_e32 v64, v64, v69
	v_mul_f32_e32 v65, v65, v70
	v_mul_f32_e32 v65, v65, v68
	v_mul_f32_dpp v45, v64, v45 row_ror:8 row_mask:0xf bank_mask:0xf bound_ctrl:1
	v_mul_f32_e32 v57, v62, v57
	v_mul_f32_e32 v62, v66, v70
	v_cndmask_b32_e64 v45, v45, -v45, s[4:5]
	v_mul_f32_e32 v60, v60, v70
	v_mul_f32_e32 v59, v62, v59
	v_mul_f32_e32 v62, v63, v70
	v_fmac_f32_e32 v45, v44, v64
	v_mul_f32_dpp v44, v65, v47 row_ror:8 row_mask:0xf bank_mask:0xf bound_ctrl:1
	v_mul_f32_e32 v60, v60, v72
	v_mul_f32_e32 v56, v62, v56
	v_mul_f32_e32 v62, v67, v70
	v_cndmask_b32_e64 v44, v44, -v44, s[4:5]
	v_mul_f32_dpp v41, v59, v41 row_ror:8 row_mask:0xf bank_mask:0xf bound_ctrl:1
	v_mul_f32_e32 v61, v61, v70
	v_mul_f32_e32 v58, v62, v58
	v_mul_f32_dpp v53, v60, v53 row_ror:8 row_mask:0xf bank_mask:0xf bound_ctrl:1
	v_mul_f32_dpp v49, v57, v49 row_ror:8 row_mask:0xf bank_mask:0xf bound_ctrl:1
	v_fmac_f32_e32 v44, v46, v65
	v_cndmask_b32_e64 v46, v41, -v41, s[4:5]
	v_mul_f32_e32 v61, v61, v73
	v_cndmask_b32_e64 v53, v53, -v53, s[4:5]
	v_cndmask_b32_e64 v49, v49, -v49, s[4:5]
	v_fmac_f32_e32 v46, v40, v59
	v_mul_f32_dpp v40, v58, v43 row_ror:8 row_mask:0xf bank_mask:0xf bound_ctrl:1
	v_fmac_f32_e32 v53, v52, v60
	v_mul_f32_dpp v52, v61, v55 row_ror:8 row_mask:0xf bank_mask:0xf bound_ctrl:1
	v_fmac_f32_e32 v49, v48, v57
	v_mul_f32_dpp v48, v56, v51 row_ror:8 row_mask:0xf bank_mask:0xf bound_ctrl:1
	v_cndmask_b32_e64 v43, v40, -v40, s[4:5]
	v_cndmask_b32_e64 v52, v52, -v52, s[4:5]
	v_cndmask_b32_e64 v48, v48, -v48, s[4:5]
	v_fmac_f32_e32 v43, v42, v58
	v_fmac_f32_e32 v52, v54, v61
	v_fmac_f32_e32 v48, v50, v56
	v_cvt_pk_bf16_f32 v40, v53, v52
	v_cvt_pk_bf16_f32 v41, v49, v48
	v_cvt_pk_bf16_f32 v42, v45, v44
	v_cvt_pk_bf16_f32 v43, v46, v43
	flat_store_dwordx4 v[166:167], v[40:43]
	flat_load_dwordx4 v[40:43], v[160:161]
	s_nop 0
	flat_load_dwordx4 v[44:47], v[160:161] offset:16
	v_and_b32_e32 v57, 0xffff0000, v36
	v_lshlrev_b32_e32 v56, 16, v36
	v_and_b32_e32 v36, 0xffff0000, v37
	v_lshlrev_b32_e32 v37, 16, v37
	v_mul_f32_e32 v58, v57, v57
	v_pk_mul_f32 v[50:51], v[36:37], v[36:37]
	v_fmac_f32_e32 v58, v56, v56
	v_and_b32_e32 v48, 0xffff0000, v38
	v_lshlrev_b32_e32 v49, 16, v38
	v_add_f32_e32 v51, v51, v58
	v_pk_mul_f32 v[52:53], v[48:49], v[48:49]
	v_add_f32_e32 v50, v50, v51
	v_and_b32_e32 v38, 0xffff0000, v39
	v_lshlrev_b32_e32 v39, 16, v39
	v_add_f32_e32 v50, v53, v50
	v_pk_mul_f32 v[54:55], v[38:39], v[38:39]
	v_add_f32_e32 v50, v52, v50
	v_add_f32_e32 v50, v55, v50
	v_add_f32_e32 v50, v54, v50
	s_nop 1
	v_add_f32_dpp v50, v50, v50 quad_perm:[1,0,3,2] row_mask:0xf bank_mask:0xf bound_ctrl:1
	s_nop 1
	v_add_f32_dpp v50, v50, v50 quad_perm:[2,3,0,1] row_mask:0xf bank_mask:0xf bound_ctrl:1
	s_nop 1
	v_add_f32_dpp v50, v50, v50 row_half_mirror row_mask:0xf bank_mask:0xf bound_ctrl:1
	s_nop 1
	v_add_f32_dpp v50, v50, v50 row_mirror row_mask:0xf bank_mask:0xf bound_ctrl:1
	v_fmamk_f32 v50, v50, 0x3c000000, v157
	v_mul_f32_e32 v51, 0x4b800000, v50
	v_cmp_gt_f32_e32 vcc, s24, v50
	s_nop 1
	v_cndmask_b32_e32 v50, v50, v51, vcc
	v_rsq_f32_e32 v50, v50
	s_nop 0
	v_mul_f32_e32 v51, 0x45800000, v50
	v_cndmask_b32_e32 v50, v50, v51, vcc
	s_waitcnt vmcnt(0) lgkmcnt(0)
; __device__ __forceinline__ unsigned cvt_pk_bf16(float lo, float hi) { unsigned r; asm volatile("v_cvt_pk_bf16_f32 %0, %1, %2" : "=v"(r) : "v"(lo), "v"(hi)); return r; }
; __device__ __forceinline__ float bflo(unsigned w) { return __uint_as_float(w << 16); }
; __device__ __forceinline__ float bfhi(unsigned w) { return __uint_as_float(w & 0xffff0000u); }
; __device__ __forceinline__ float shx(float v, int m, int lane) { return __int_as_float(__builtin_amdgcn_ds_bpermute((lane ^ m) << 2, __float_as_int(v))); }
; #define DPPF(v, ctrl) __int_as_float(__builtin_amdgcn_update_dpp(0, __float_as_int(v), (ctrl), 0xf, 0xf, false))
; __device__ __forceinline__ float row16_sum(float x) { x += DPPF(x, 0xB1); x += DPPF(x, 0x4E); x += DPPF(x, 0x141); x += DPPF(x, 0x140); return x; }
; template <bool NORM, int ROT> __device__ __forceinline__ void rope_chunk(bf16_t* p, const u32x4 w, const f32x4 (&tb)[4], const float* g, float sc, int lane) {
;     const int j = lane & 15;
;     float x[8] = {bflo(w.x), bfhi(w.x), bflo(w.y), bfhi(w.y), bflo(w.z), bfhi(w.z), bflo(w.w), bfhi(w.w)};
;     if (NORM) {
;         float ss = 0.f;
; #pragma unroll
;         for (int q = 0; q < 8; ++q) ss += x[q] * x[q];
;         ss = row16_sum(ss);
;         const float rstd = rsqrtf(ss * (1.f / 128.f) + EPS);
;         const f32x4 g0 = *(const f32x4*)(g + j * 8), g1 = *(const f32x4*)(g + j * 8 + 4);
; #pragma unroll
;         for (int q = 0; q < 4; ++q) { x[q] *= rstd * g0[q]; x[4 + q] *= rstd * g1[q]; }
;     }
;     constexpr int HALFL = ROT / 16;
;     const bool rot = (ROT == 128) || (j < 8); const bool first = (j & HALFL) == 0;
;     float o[8];
; #pragma unroll
;     for (int q = 0; q < 8; ++q) {
;         const float other = (ROT == 128) ? DPPF(x[q], 0x128)   : shx(x[q], HALFL, lane);
;         const float cs = tb[q >> 1][(q & 1) * 2], sn = tb[q >> 1][(q & 1) * 2 + 1];
;         const float r = first ? (x[q] * cs - other * sn) : (x[q] * cs + other * sn);
;         o[q] = (rot ? r : x[q]) * sc;
;     }
;     u32x4 ow; ow.x = cvt_pk_bf16(o[0], o[1]); ow.y = cvt_pk_bf16(o[2], o[3]); ow.z = cvt_pk_bf16(o[4], o[5]); ow.w = cvt_pk_bf16(o[6], o[7]);
;     *(u32x4*)(p + lane * 8) = ow;
; }
	v_mul_f32_e32 v42, v42, v50
	v_mul_f32_e32 v44, v44, v50
	v_mul_f32_e32 v44, v44, v49
	v_mul_f32_e32 v45, v45, v50
	v_mul_f32_e32 v46, v46, v50
	v_mul_f32_dpp v25, v44, v25 row_ror:8 row_mask:0xf bank_mask:0xf bound_ctrl:1
	v_mul_f32_e32 v45, v45, v48
	v_cndmask_b32_e64 v25, v25, -v25, s[4:5]
	v_mul_f32_e32 v40, v40, v50
	v_mul_f32_e32 v37, v42, v37
	v_mul_f32_e32 v39, v46, v39
	v_mul_f32_e32 v42, v43, v50
	v_fmac_f32_e32 v25, v24, v44
	v_mul_f32_dpp v24, v45, v27 row_ror:8 row_mask:0xf bank_mask:0xf bound_ctrl:1
	v_mul_f32_e32 v40, v40, v56
	v_mul_f32_e32 v36, v42, v36
	v_mul_f32_e32 v42, v47, v50
	v_cndmask_b32_e64 v24, v24, -v24, s[4:5]
	v_mul_f32_dpp v21, v39, v21 row_ror:8 row_mask:0xf bank_mask:0xf bound_ctrl:1
	v_mul_f32_e32 v41, v41, v50
	v_mul_f32_e32 v38, v42, v38
	v_mul_f32_dpp v33, v40, v33 row_ror:8 row_mask:0xf bank_mask:0xf bound_ctrl:1
	v_mul_f32_dpp v29, v37, v29 row_ror:8 row_mask:0xf bank_mask:0xf bound_ctrl:1
	v_fmac_f32_e32 v24, v26, v45
	v_cndmask_b32_e64 v26, v21, -v21, s[4:5]
	v_mul_f32_e32 v41, v41, v57
	v_cndmask_b32_e64 v33, v33, -v33, s[4:5]
	v_cndmask_b32_e64 v29, v29, -v29, s[4:5]
	v_fmac_f32_e32 v26, v20, v39
	v_mul_f32_dpp v20, v38, v23 row_ror:8 row_mask:0xf bank_mask:0xf bound_ctrl:1
	v_fmac_f32_e32 v33, v32, v40
	v_mul_f32_dpp v32, v41, v35 row_ror:8 row_mask:0xf bank_mask:0xf bound_ctrl:1
	v_fmac_f32_e32 v29, v28, v37
	v_mul_f32_dpp v28, v36, v31 row_ror:8 row_mask:0xf bank_mask:0xf bound_ctrl:1
	v_cndmask_b32_e64 v23, v20, -v20, s[4:5]
	v_cndmask_b32_e64 v32, v32, -v32, s[4:5]
	v_cndmask_b32_e64 v28, v28, -v28, s[4:5]
	v_fmac_f32_e32 v23, v22, v38
	v_fmac_f32_e32 v32, v34, v41
	v_fmac_f32_e32 v28, v30, v36
	v_cvt_pk_bf16_f32 v20, v33, v32
	v_cvt_pk_bf16_f32 v21, v29, v28
	v_cvt_pk_bf16_f32 v22, v25, v24
	v_cvt_pk_bf16_f32 v23, v26, v23
	flat_store_dwordx4 v[164:165], v[20:23]
	flat_load_dwordx4 v[20:23], v[160:161]
	s_nop 0
	flat_load_dwordx4 v[24:27], v[160:161] offset:16
	v_and_b32_e32 v37, 0xffff0000, v16
	v_lshlrev_b32_e32 v36, 16, v16
	v_and_b32_e32 v16, 0xffff0000, v17
	v_lshlrev_b32_e32 v17, 16, v17
	v_mul_f32_e32 v38, v37, v37
	v_pk_mul_f32 v[30:31], v[16:17], v[16:17]
	v_fmac_f32_e32 v38, v36, v36
	v_and_b32_e32 v28, 0xffff0000, v18
	v_lshlrev_b32_e32 v29, 16, v18
	v_add_f32_e32 v31, v31, v38
	v_pk_mul_f32 v[32:33], v[28:29], v[28:29]
	v_add_f32_e32 v30, v30, v31
	v_and_b32_e32 v18, 0xffff0000, v19
	v_lshlrev_b32_e32 v19, 16, v19
	v_add_f32_e32 v30, v33, v30
	v_pk_mul_f32 v[34:35], v[18:19], v[18:19]
	v_add_f32_e32 v30, v32, v30
	v_add_f32_e32 v30, v35, v30
	v_add_f32_e32 v30, v34, v30
	s_nop 1
	v_add_f32_dpp v30, v30, v30 quad_perm:[1,0,3,2] row_mask:0xf bank_mask:0xf bound_ctrl:1
	s_nop 1
	v_add_f32_dpp v30, v30, v30 quad_perm:[2,3,0,1] row_mask:0xf bank_mask:0xf bound_ctrl:1
	s_nop 1
	v_add_f32_dpp v30, v30, v30 row_half_mirror row_mask:0xf bank_mask:0xf bound_ctrl:1
	s_nop 1
	v_add_f32_dpp v30, v30, v30 row_mirror row_mask:0xf bank_mask:0xf bound_ctrl:1
	v_fmamk_f32 v30, v30, 0x3c000000, v157
	v_mul_f32_e32 v31, 0x4b800000, v30
	v_cmp_gt_f32_e32 vcc, s24, v30
	s_nop 1
	v_cndmask_b32_e32 v30, v30, v31, vcc
	v_rsq_f32_e32 v30, v30
	s_nop 0
	v_mul_f32_e32 v31, 0x45800000, v30
	v_cndmask_b32_e32 v30, v30, v31, vcc
	s_waitcnt vmcnt(0) lgkmcnt(0)
	v_mul_f32_e32 v22, v22, v30
	v_mul_f32_e32 v24, v24, v30
	v_mul_f32_e32 v24, v24, v29
	v_mul_f32_e32 v25, v25, v30
	v_mul_f32_e32 v26, v26, v30
	v_mul_f32_dpp v5, v24, v5 row_ror:8 row_mask:0xf bank_mask:0xf bound_ctrl:1
	v_mul_f32_e32 v25, v25, v28
	v_cndmask_b32_e64 v5, v5, -v5, s[4:5]
	v_mul_f32_e32 v19, v26, v19
	v_fmac_f32_e32 v5, v4, v24
	v_mul_f32_dpp v4, v25, v7 row_ror:8 row_mask:0xf bank_mask:0xf bound_ctrl:1
	v_mul_f32_e32 v27, v27, v30
	v_mul_f32_e32 v17, v22, v17
	v_cndmask_b32_e64 v4, v4, -v4, s[4:5]
	v_mul_f32_dpp v1, v19, v1 row_ror:8 row_mask:0xf bank_mask:0xf bound_ctrl:1
	v_mul_f32_e32 v20, v20, v30
	v_mul_f32_e32 v21, v21, v30
	v_mul_f32_e32 v23, v23, v30
	v_mul_f32_e32 v18, v27, v18
	v_mul_f32_dpp v9, v17, v9 row_ror:8 row_mask:0xf bank_mask:0xf bound_ctrl:1
	v_fmac_f32_e32 v4, v6, v25
	v_cndmask_b32_e64 v6, v1, -v1, s[4:5]
	v_mul_f32_e32 v20, v20, v36
	v_mul_f32_e32 v21, v21, v37
	v_mul_f32_e32 v16, v23, v16
	v_cndmask_b32_e64 v9, v9, -v9, s[4:5]
	v_fmac_f32_e32 v6, v0, v19
	v_mul_f32_dpp v0, v18, v3 row_ror:8 row_mask:0xf bank_mask:0xf bound_ctrl:1
	v_mul_f32_dpp v13, v20, v13 row_ror:8 row_mask:0xf bank_mask:0xf bound_ctrl:1
	v_mul_f32_dpp v15, v21, v15 row_ror:8 row_mask:0xf bank_mask:0xf bound_ctrl:1
	v_fmac_f32_e32 v9, v8, v17
	v_mul_f32_dpp v8, v16, v11 row_ror:8 row_mask:0xf bank_mask:0xf bound_ctrl:1
	v_cndmask_b32_e64 v3, v0, -v0, s[4:5]
	v_cndmask_b32_e64 v13, v13, -v13, s[4:5]
	v_cndmask_b32_e64 v15, v15, -v15, s[4:5]
	v_cndmask_b32_e64 v8, v8, -v8, s[4:5]
	v_fmac_f32_e32 v3, v2, v18
	v_fmac_f32_e32 v13, v12, v20
	v_fmac_f32_e32 v15, v14, v21
	v_fmac_f32_e32 v8, v10, v16
	v_cvt_pk_bf16_f32 v0, v13, v15
	v_cvt_pk_bf16_f32 v1, v9, v8
	v_cvt_pk_bf16_f32 v2, v5, v4
	v_cvt_pk_bf16_f32 v3, v6, v3
	flat_store_dwordx4 v[162:163], v[0:3]
	v_lshl_add_u64 v[162:163], v[162:163], 0, s[16:17]
	s_cbranch_scc1 .LBB0_1074

; template <bool NORM, int ROT, bool PERTOK> __device__ __forceinline__ void rope_pass(bf16_t* base, int nchunks, const float* g, const float* tab, float sc, int gw, int NGW, int lane) {
;     constexpr int NB = 8, HALFL = ROT / 16; const int j = lane & 15;
;     for (int it0 = gw * NB; it0 < nchunks; it0 += NGW * NB) {
;         u32x4 w[NB]; f32x4 tb[NB][4];
; #pragma unroll
;         for (int k = 0; k < NB; ++k) { const int it = it0 + k;
;             w[k] = *(const u32x4*)(base + (size_t)it * 512 + lane * 8);
;             const int pos = PERTOK ? ((it >> 2) & 8191) : (((it * 4) & 8191) + (lane >> 4));
;             const float* tp = tab + (size_t)pos * ROT + (j & (HALFL - 1)) * 16;
; #pragma unroll
;             for (int q = 0; q < 4; ++q) tb[k][q] = *(const f32x4*)(tp + q * 4); }
; #pragma unroll
;         for (int k = 0; k < NB; ++k) rope_chunk<NORM, ROT>(base + (size_t)(it0 + k) * 512, w[k], tb[k], g, sc, lane);
;     }
; }
; __device__ __forceinline__ void post_proj(const Args& A, int gw, int NGW, int lane) {
;     unsigned char* ws = A.ws;
;     const float* R1 = (const float*)(ws + WS_ROPE1); const float* R2 = (const float*)(ws + WS_ROPE2);
;     const float qs = 0.08838834764831845f;
;     rope_pass<true, 128, true>((bf16_t*)(ws + WS_DQ), T * 4, A.q_norm_g, R1, qs * 1.4426950408889634f  , gw, NGW, lane);
;     rope_pass<true, 128, false>((bf16_t*)(ws + WS_DK), T, A.k_norm_g, R1, 1.f, gw, NGW, lane);
.Lrope_b1:
	v_readlane_b32 s91, v255, 3
	s_lshl_b32 s92, s2, 3
	s_add_i32 s92, s92, s91
	s_mov_b32 s94, s44
	s_and_b64 vcc, exec, s[88:89]
	s_cbranch_vccz .Lrb_mode_done
	s_lshl_b32 s92, s2, 2
	s_add_i32 s92, s92, s91
	s_add_i32 s92, s92, -4
	s_lshr_b32 s94, s44, 1
.Lrb_mode_done:
	s_mov_b32 s93, s92
	s_add_i32 s92, s92, 0x1000
	s_lshr_b32 s96, s92, 3
	s_and_b32 s97, s92, 7
	v_readlane_b32 s0, v255, 0
	v_readlane_b32 s1, v255, 1
	s_load_dwordx2 s[10:11], s[0:1], 0x88
	s_load_dwordx4 s[4:7], s[0:1], 0x38
	s_load_dwordx2 s[12:13], s[0:1], 0x48
	s_lshl_b32 s0, s96, 3
	s_mov_b32 s1, s97
	s_add_i32 s0, s1, s0
	s_waitcnt lgkmcnt(0)
	s_add_u32 s16, s10, 0x400000
	s_addc_u32 s17, s11, 0
	s_cmpk_lt_i32 s0, 0x2000
	v_mbcnt_lo_u32_b32 v179, -1, 0
	v_mbcnt_hi_u32_b32 v179, -1, v179
	s_cselect_b64 s[14:15], -1, 0
	s_cmpk_gt_i32 s0, 0x1fff
	v_lshlrev_b32_e32 v156, 3, v179
	v_lshlrev_b32_e32 v180, 6, v179
	v_lshlrev_b32_e32 v124, 5, v179
	v_and_b32_e32 v181, 8, v179
	s_cbranch_scc1 .Lrb_1072
	s_lshl_b32 s18, s0, 3
	s_mov_b32 s3, s97
	s_lshl_b32 s1, s96, 11
	s_lshl_b32 s3, s3, 8
	s_ashr_i32 s19, s18, 31
	s_lshl_b32 s22, s94, 6
	s_add_i32 s1, s1, s3
	s_lshl_b32 s3, s94, 11
	s_lshl_b64 s[24:25], s[18:19], 10
	v_and_b32_e32 v0, 0x1c0, v180
	v_mov_b32_e32 v1, 0
	s_add_u32 s24, s10, s24
	v_ashrrev_i32_e32 v157, 31, v156
	v_lshl_add_u64 v[104:105], s[16:17], 0, v[0:1]
	v_and_b32_e32 v0, 0x1e0, v124
	s_addc_u32 s25, s11, s25
	v_lshl_add_u64 v[106:107], s[4:5], 0, v[0:1]
	v_lshl_add_u64 v[0:1], v[156:157], 1, s[24:25]
	s_mov_b64 s[24:25], 0xd801c00
	s_ashr_i32 s23, s22, 31
	s_mov_b32 s21, 0
	v_cmp_eq_u32_e64 s[4:5], 0, v181
	v_lshl_add_u64 v[108:109], v[0:1], 0, s[24:25]
	s_lshl_b64 s[24:25], s[22:23], 10
	s_movk_i32 s19, 0xe800
	s_movk_i32 s23, 0xec00
	s_movk_i32 s26, 0xf000
	s_movk_i32 s27, 0xf400
	s_movk_i32 s28, 0xf800
	s_movk_i32 s29, 0xfc00
	v_mov_b32_e32 v125, 0x358637bd
	s_mov_b32 s30, 0x800000

; template <bool NORM, int ROT, bool PERTOK> __device__ __forceinline__ void rope_pass(bf16_t* base, int nchunks, const float* g, const float* tab, float sc, int gw, int NGW, int lane) {
;     constexpr int NB = 8, HALFL = ROT / 16; const int j = lane & 15;
;     for (int it0 = gw * NB; it0 < nchunks; it0 += NGW * NB) {
;         u32x4 w[NB]; f32x4 tb[NB][4];
; #pragma unroll
;         for (int k = 0; k < NB; ++k) { const int it = it0 + k;
;             w[k] = *(const u32x4*)(base + (size_t)it * 512 + lane * 8);
;             const int pos = PERTOK ? ((it >> 2) & 8191) : (((it * 4) & 8191) + (lane >> 4));
;             const float* tp = tab + (size_t)pos * ROT + (j & (HALFL - 1)) * 16;
; #pragma unroll
;             for (int q = 0; q < 4; ++q) tb[k][q] = *(const f32x4*)(tp + q * 4); }
; #pragma unroll
;         for (int k = 0; k < NB; ++k) rope_chunk<NORM, ROT>(base + (size_t)(it0 + k) * 512, w[k], tb[k], g, sc, lane);
;     }
.Lrb_1072:
	s_add_i32 s92, s93, 0x400
	s_lshr_b32 s96, s92, 3
	s_and_b32 s97, s92, 7
	s_mov_b32 s0, s92
	s_cmpk_gt_i32 s0, 0x7ff
	v_ashrrev_i32_e32 v178, 4, v179
	s_cbranch_scc1 .Lrb_1075
	s_lshl_b32 s18, s0, 3
	v_and_b32_e32 v0, 0x1c0, v180
	v_mov_b32_e32 v1, 0
	s_mov_b32 s3, s97
	v_lshl_add_u64 v[158:159], s[16:17], 0, v[0:1]
	v_and_b32_e32 v0, 0x1e0, v124
	s_lshl_b32 s1, s96, 8
	s_lshl_b32 s3, s3, 5
	s_ashr_i32 s19, s18, 31
	v_lshl_add_u64 v[160:161], s[6:7], 0, v[0:1]
	s_lshl_b32 s6, s94, 6
	s_add_i32 s1, s1, s3
	s_lshl_b32 s3, s94, 8
	s_lshl_b64 s[16:17], s[18:19], 10
	s_add_u32 s16, s10, s16
	v_ashrrev_i32_e32 v157, 31, v156
	s_addc_u32 s17, s11, s17
	v_lshl_add_u64 v[0:1], v[156:157], 1, s[16:17]
	s_mov_b64 s[16:17], 0x11801c00
	s_ashr_i32 s7, s6, 31
	v_cmp_eq_u32_e64 s[4:5], 0, v181
	v_lshl_add_u64 v[162:163], v[0:1], 0, s[16:17]
	s_lshl_b64 s[16:17], s[6:7], 10
	s_movk_i32 s7, 0xe800
	s_movk_i32 s19, 0xec00
	s_movk_i32 s20, 0xf000
	s_movk_i32 s21, 0xf400
	s_movk_i32 s22, 0xf800
	s_movk_i32 s23, 0xfc00
	v_mov_b32_e32 v157, 0x358637bd
	s_mov_b32 s24, 0x800000
.Lrb_1074:
	v_add_co_u32_e32 v176, vcc, 0xffffe400, v162
	s_and_b32 s25, s1, 0x1fe0
	s_nop 0
	v_addc_co_u32_e32 v177, vcc, -1, v163, vcc
	flat_load_dwordx4 v[0:3], v[176:177]
	v_add_u32_e32 v4, s25, v178
	v_ashrrev_i32_e32 v5, 31, v4
	v_lshlrev_b64 v[4:5], 9, v[4:5]
	s_add_i32 s25, s1, 4
	v_lshl_add_u64 v[4:5], v[158:159], 0, v[4:5]
	s_and_b32 s25, s25, 0x1fe4
	flat_load_dwordx4 v[152:155], v[4:5]
	flat_load_dwordx4 v[148:151], v[4:5] offset:16
	flat_load_dwordx4 v[144:147], v[4:5] offset:32
	flat_load_dwordx4 v[140:143], v[4:5] offset:48
	v_add_u32_e32 v4, s25, v178
	v_ashrrev_i32_e32 v5, 31, v4
	v_add_co_u32_e32 v174, vcc, s7, v162
	v_lshlrev_b64 v[4:5], 9, v[4:5]
	s_add_i32 s25, s1, 8
	v_addc_co_u32_e32 v175, vcc, -1, v163, vcc
	v_lshl_add_u64 v[4:5], v[158:159], 0, v[4:5]
	s_and_b32 s25, s25, 0x1fe8
	flat_load_dwordx4 v[136:139], v[174:175]
	flat_load_dwordx4 v[132:135], v[4:5]
	flat_load_dwordx4 v[128:131], v[4:5] offset:16
	flat_load_dwordx4 v[124:127], v[4:5] offset:32
	flat_load_dwordx4 v[120:123], v[4:5] offset:48
	v_add_u32_e32 v4, s25, v178
	v_ashrrev_i32_e32 v5, 31, v4
	v_add_co_u32_e32 v172, vcc, s19, v162
	v_lshlrev_b64 v[4:5], 9, v[4:5]
	s_add_i32 s25, s1, 12
	v_addc_co_u32_e32 v173, vcc, -1, v163, vcc
	v_lshl_add_u64 v[4:5], v[158:159], 0, v[4:5]
	s_and_b32 s25, s25, 0x1fec
	flat_load_dwordx4 v[116:119], v[172:173]
	flat_load_dwordx4 v[112:115], v[4:5]
	flat_load_dwordx4 v[108:111], v[4:5] offset:16
	flat_load_dwordx4 v[104:107], v[4:5] offset:32
	flat_load_dwordx4 v[100:103], v[4:5] offset:48
	v_add_u32_e32 v4, s25, v178
	v_ashrrev_i32_e32 v5, 31, v4
	v_add_co_u32_e32 v170, vcc, s20, v162
	v_lshlrev_b64 v[4:5], 9, v[4:5]
	s_add_i32 s25, s1, 16
	v_addc_co_u32_e32 v171, vcc, -1, v163, vcc
	v_lshl_add_u64 v[4:5], v[158:159], 0, v[4:5]
	s_and_b32 s25, s25, 0x1ff0
	flat_load_dwordx4 v[96:99], v[170:171]
	flat_load_dwordx4 v[92:95], v[4:5]
	flat_load_dwordx4 v[88:91], v[4:5] offset:16
	flat_load_dwordx4 v[80:83], v[4:5] offset:32
	flat_load_dwordx4 v[72:75], v[4:5] offset:48
	v_add_u32_e32 v4, s25, v178
	v_add_co_u32_e32 v168, vcc, s21, v162
	v_ashrrev_i32_e32 v5, 31, v4
	s_nop 0
	v_addc_co_u32_e32 v169, vcc, -1, v163, vcc
	v_lshlrev_b64 v[4:5], 9, v[4:5]
	flat_load_dwordx4 v[60:63], v[168:169]
	flat_load_dwordx4 v[182:185], v[160:161]
	v_lshl_add_u64 v[4:5], v[158:159], 0, v[4:5]
	flat_load_dwordx4 v[186:189], v[160:161] offset:16
	flat_load_dwordx4 v[84:87], v[4:5]
	flat_load_dwordx4 v[76:79], v[4:5] offset:16
	flat_load_dwordx4 v[68:71], v[4:5] offset:32
	flat_load_dwordx4 v[64:67], v[4:5] offset:48
	s_add_i32 s25, s1, 20
	s_and_b32 s25, s25, 0x1ff4
	v_add_u32_e32 v4, s25, v178
	v_ashrrev_i32_e32 v5, 31, v4
	v_add_co_u32_e32 v166, vcc, s22, v162
	v_lshlrev_b64 v[4:5], 9, v[4:5]
	s_add_i32 s25, s1, 24
	v_addc_co_u32_e32 v167, vcc, -1, v163, vcc
	v_lshl_add_u64 v[4:5], v[158:159], 0, v[4:5]
	s_and_b32 s25, s25, 0x1ff8
	flat_load_dwordx4 v[56:59], v[166:167]
	flat_load_dwordx4 v[52:55], v[4:5]
	flat_load_dwordx4 v[48:51], v[4:5] offset:16
	flat_load_dwordx4 v[44:47], v[4:5] offset:32
	flat_load_dwordx4 v[40:43], v[4:5] offset:48
	v_add_u32_e32 v4, s25, v178
	v_ashrrev_i32_e32 v5, 31, v4
	v_add_co_u32_e32 v164, vcc, s23, v162
	v_lshlrev_b64 v[4:5], 9, v[4:5]
	s_add_i32 s25, s1, 28
	v_addc_co_u32_e32 v165, vcc, -1, v163, vcc
	v_lshl_add_u64 v[4:5], v[158:159], 0, v[4:5]
	s_and_b32 s25, s25, 0x1ffc
	flat_load_dwordx4 v[36:39], v[164:165]
	flat_load_dwordx4 v[32:35], v[4:5]
	flat_load_dwordx4 v[28:31], v[4:5] offset:16
	flat_load_dwordx4 v[24:27], v[4:5] offset:32
	flat_load_dwordx4 v[20:23], v[4:5] offset:48
	flat_load_dwordx4 v[16:19], v[162:163]
	v_add_u32_e32 v4, s25, v178
	v_ashrrev_i32_e32 v5, 31, v4
	v_lshlrev_b64 v[4:5], 9, v[4:5]
	s_waitcnt vmcnt(0) lgkmcnt(0)
; __device__ __forceinline__ unsigned cvt_pk_bf16(float lo, float hi) { unsigned r; asm volatile("v_cvt_pk_bf16_f32 %0, %1, %2" : "=v"(r) : "v"(lo), "v"(hi)); return r; }
; __device__ __forceinline__ float bflo(unsigned w) { return __uint_as_float(w << 16); }
; __device__ __forceinline__ float bfhi(unsigned w) { return __uint_as_float(w & 0xffff0000u); }
; __device__ __forceinline__ float shx(float v, int m, int lane) { return __int_as_float(__builtin_amdgcn_ds_bpermute((lane ^ m) << 2, __float_as_int(v))); }
; #define DPPF(v, ctrl) __int_as_float(__builtin_amdgcn_update_dpp(0, __float_as_int(v), (ctrl), 0xf, 0xf, false))
; __device__ __forceinline__ float row16_sum(float x) { x += DPPF(x, 0xB1); x += DPPF(x, 0x4E); x += DPPF(x, 0x141); x += DPPF(x, 0x140); return x; }
; template <bool NORM, int ROT> __device__ __forceinline__ void rope_chunk(bf16_t* p, const u32x4 w, const f32x4 (&tb)[4], const float* g, float sc, int lane) {
;     const int j = lane & 15;
;     float x[8] = {bflo(w.x), bfhi(w.x), bflo(w.y), bfhi(w.y), bflo(w.z), bfhi(w.z), bflo(w.w), bfhi(w.w)};
;     if (NORM) {
;         float ss = 0.f;
; #pragma unroll
;         for (int q = 0; q < 8; ++q) ss += x[q] * x[q];
;         ss = row16_sum(ss);
;         const float rstd = rsqrtf(ss * (1.f / 128.f) + EPS);
;         const f32x4 g0 = *(const f32x4*)(g + j * 8), g1 = *(const f32x4*)(g + j * 8 + 4);
; #pragma unroll
;         for (int q = 0; q < 4; ++q) { x[q] *= rstd * g0[q]; x[4 + q] *= rstd * g1[q]; }
;     }
;     constexpr int HALFL = ROT / 16;
;     const bool rot = (ROT == 128) || (j < 8); const bool first = (j & HALFL) == 0;
;     float o[8];
; #pragma unroll
;     for (int q = 0; q < 8; ++q) {
;         const float other = (ROT == 128) ? DPPF(x[q], 0x128)   : shx(x[q], HALFL, lane);
;         const float cs = tb[q >> 1][(q & 1) * 2], sn = tb[q >> 1][(q & 1) * 2 + 1];
;         const float r = first ? (x[q] * cs - other * sn) : (x[q] * cs + other * sn);
;         o[q] = (rot ? r : x[q]) * sc;
;     }
;     u32x4 ow; ow.x = cvt_pk_bf16(o[0], o[1]); ow.y = cvt_pk_bf16(o[2], o[3]); ow.z = cvt_pk_bf16(o[4], o[5]); ow.w = cvt_pk_bf16(o[6], o[7]);
;     *(u32x4*)(p + lane * 8) = ow;
; }
	v_and_b32_e32 v199, 0xffff0000, v0
	v_lshl_add_u64 v[190:191], v[158:159], 0, v[4:5]
	v_lshlrev_b32_e32 v198, 16, v0
	v_mul_f32_e32 v4, v199, v199
	v_and_b32_e32 v192, 0xffff0000, v1
	v_lshlrev_b32_e32 v193, 16, v1
	v_fmac_f32_e32 v4, v198, v198
	v_pk_mul_f32 v[0:1], v[192:193], v[192:193]
	v_and_b32_e32 v194, 0xffff0000, v2
	v_add_f32_e32 v1, v1, v4
	v_lshlrev_b32_e32 v195, 16, v2
	v_add_f32_e32 v4, v0, v1
	v_pk_mul_f32 v[0:1], v[194:195], v[194:195]
	v_and_b32_e32 v196, 0xffff0000, v3
	v_add_f32_e32 v1, v1, v4
	v_lshlrev_b32_e32 v197, 16, v3
	v_add_f32_e32 v2, v0, v1
	v_pk_mul_f32 v[0:1], v[196:197], v[196:197]
	s_add_i32 s18, s18, s6
	v_add_f32_e32 v1, v1, v2
	v_add_f32_e32 v0, v0, v1
	s_add_i32 s1, s1, s3
	s_cmpk_lt_i32 s18, 0x4000
	v_add_f32_dpp v0, v0, v0 quad_perm:[1,0,3,2] row_mask:0xf bank_mask:0xf bound_ctrl:1
	s_nop 1
	v_add_f32_dpp v0, v0, v0 quad_perm:[2,3,0,1] row_mask:0xf bank_mask:0xf bound_ctrl:1
	s_nop 1
	v_add_f32_dpp v0, v0, v0 row_half_mirror row_mask:0xf bank_mask:0xf bound_ctrl:1
	s_nop 1
	v_add_f32_dpp v0, v0, v0 row_mirror row_mask:0xf bank_mask:0xf bound_ctrl:1
	v_fmamk_f32 v0, v0, 0x3c000000, v157
	v_mul_f32_e32 v1, 0x4b800000, v0
	v_cmp_gt_f32_e32 vcc, s24, v0
	s_nop 1
	v_cndmask_b32_e32 v0, v0, v1, vcc
	v_rsq_f32_e32 v200, v0
	flat_load_dwordx4 v[12:15], v[190:191]
	flat_load_dwordx4 v[8:11], v[190:191] offset:16
	flat_load_dwordx4 v[4:7], v[190:191] offset:32
	flat_load_dwordx4 v[0:3], v[190:191] offset:48
	v_mul_f32_e32 v190, 0x45800000, v200
	v_cndmask_b32_e32 v190, v200, v190, vcc
	v_mul_f32_e32 v186, v186, v190
	v_mul_f32_e32 v186, v186, v195
	v_mul_f32_e32 v187, v187, v190
	v_mul_f32_e32 v187, v187, v194
	v_mul_f32_dpp v145, v186, v145 row_ror:8 row_mask:0xf bank_mask:0xf bound_ctrl:1
	v_mul_f32_e32 v188, v188, v190
	v_cndmask_b32_e64 v145, v145, -v145, s[4:5]
	v_mul_f32_e32 v182, v182, v190
	v_mul_f32_e32 v184, v184, v190
	v_mul_f32_e32 v188, v188, v197
	v_fmac_f32_e32 v145, v144, v186
	v_mul_f32_dpp v144, v187, v147 row_ror:8 row_mask:0xf bank_mask:0xf bound_ctrl:1
	v_mul_f32_e32 v182, v182, v198
	v_mul_f32_e32 v184, v184, v193
	v_mul_f32_e32 v189, v189, v190
	v_cndmask_b32_e64 v144, v144, -v144, s[4:5]
	v_mul_f32_dpp v141, v188, v141 row_ror:8 row_mask:0xf bank_mask:0xf bound_ctrl:1
	v_mul_f32_e32 v183, v183, v190
	v_mul_f32_e32 v185, v185, v190
	v_mul_f32_e32 v189, v189, v196
	v_mul_f32_dpp v153, v182, v153 row_ror:8 row_mask:0xf bank_mask:0xf bound_ctrl:1
	v_mul_f32_dpp v149, v184, v149 row_ror:8 row_mask:0xf bank_mask:0xf bound_ctrl:1
	v_fmac_f32_e32 v144, v146, v187
	v_cndmask_b32_e64 v146, v141, -v141, s[4:5]
	v_mul_f32_e32 v183, v183, v199
	v_mul_f32_e32 v185, v185, v192
	v_cndmask_b32_e64 v153, v153, -v153, s[4:5]
	v_cndmask_b32_e64 v149, v149, -v149, s[4:5]
	v_fmac_f32_e32 v146, v140, v188
	v_mul_f32_dpp v140, v189, v143 row_ror:8 row_mask:0xf bank_mask:0xf bound_ctrl:1
	v_fmac_f32_e32 v153, v152, v182
	v_mul_f32_dpp v152, v183, v155 row_ror:8 row_mask:0xf bank_mask:0xf bound_ctrl:1
	v_fmac_f32_e32 v149, v148, v184
	v_mul_f32_dpp v148, v185, v151 row_ror:8 row_mask:0xf bank_mask:0xf bound_ctrl:1
	v_cndmask_b32_e64 v143, v140, -v140, s[4:5]
	v_cndmask_b32_e64 v152, v152, -v152, s[4:5]
	v_cndmask_b32_e64 v148, v148, -v148, s[4:5]
	v_fmac_f32_e32 v143, v142, v189
	v_fmac_f32_e32 v152, v154, v183
	v_fmac_f32_e32 v148, v150, v185
	v_cvt_pk_bf16_f32 v140, v153, v152
	v_cvt_pk_bf16_f32 v141, v149, v148
	v_cvt_pk_bf16_f32 v142, v145, v144
	v_cvt_pk_bf16_f32 v143, v146, v143
	flat_store_dwordx4 v[176:177], v[140:143]
	flat_load_dwordx4 v[140:143], v[160:161]
	s_nop 0
	flat_load_dwordx4 v[144:147], v[160:161] offset:16
	v_and_b32_e32 v153, 0xffff0000, v136
	v_lshlrev_b32_e32 v152, 16, v136
	v_mul_f32_e32 v150, v153, v153
	v_and_b32_e32 v136, 0xffff0000, v137
	v_lshlrev_b32_e32 v137, 16, v137
	v_fmac_f32_e32 v150, v152, v152
	v_pk_mul_f32 v[148:149], v[136:137], v[136:137]
	s_nop 0
	v_add_f32_e32 v149, v149, v150
	v_add_f32_e32 v154, v148, v149
	v_and_b32_e32 v148, 0xffff0000, v138
	v_lshlrev_b32_e32 v149, 16, v138
	v_pk_mul_f32 v[150:151], v[148:149], v[148:149]
	s_nop 0
	v_add_f32_e32 v138, v151, v154
	v_add_f32_e32 v154, v150, v138
	v_and_b32_e32 v138, 0xffff0000, v139
	v_lshlrev_b32_e32 v139, 16, v139
	v_pk_mul_f32 v[150:151], v[138:139], v[138:139]
	s_nop 0
	v_add_f32_e32 v151, v151, v154
	v_add_f32_e32 v150, v150, v151
	s_nop 1
	v_add_f32_dpp v150, v150, v150 quad_perm:[1,0,3,2] row_mask:0xf bank_mask:0xf bound_ctrl:1
	s_nop 1
	v_add_f32_dpp v150, v150, v150 quad_perm:[2,3,0,1] row_mask:0xf bank_mask:0xf bound_ctrl:1
	s_nop 1
	v_add_f32_dpp v150, v150, v150 row_half_mirror row_mask:0xf bank_mask:0xf bound_ctrl:1
	s_nop 1
	v_add_f32_dpp v150, v150, v150 row_mirror row_mask:0xf bank_mask:0xf bound_ctrl:1
	v_fmamk_f32 v150, v150, 0x3c000000, v157
	v_mul_f32_e32 v151, 0x4b800000, v150
	v_cmp_gt_f32_e32 vcc, s24, v150
	s_nop 1
	v_cndmask_b32_e32 v150, v150, v151, vcc
	v_rsq_f32_e32 v150, v150
	s_nop 0
	v_mul_f32_e32 v151, 0x45800000, v150
	v_cndmask_b32_e32 v150, v150, v151, vcc
	s_waitcnt vmcnt(0) lgkmcnt(0)
; __device__ __forceinline__ unsigned cvt_pk_bf16(float lo, float hi) { unsigned r; asm volatile("v_cvt_pk_bf16_f32 %0, %1, %2" : "=v"(r) : "v"(lo), "v"(hi)); return r; }
; __device__ __forceinline__ float bflo(unsigned w) { return __uint_as_float(w << 16); }
; __device__ __forceinline__ float bfhi(unsigned w) { return __uint_as_float(w & 0xffff0000u); }
; __device__ __forceinline__ float shx(float v, int m, int lane) { return __int_as_float(__builtin_amdgcn_ds_bpermute((lane ^ m) << 2, __float_as_int(v))); }
; #define DPPF(v, ctrl) __int_as_float(__builtin_amdgcn_update_dpp(0, __float_as_int(v), (ctrl), 0xf, 0xf, false))
; __device__ __forceinline__ float row16_sum(float x) { x += DPPF(x, 0xB1); x += DPPF(x, 0x4E); x += DPPF(x, 0x141); x += DPPF(x, 0x140); return x; }
; template <bool NORM, int ROT> __device__ __forceinline__ void rope_chunk(bf16_t* p, const u32x4 w, const f32x4 (&tb)[4], const float* g, float sc, int lane) {
;     const int j = lane & 15;
;     float x[8] = {bflo(w.x), bfhi(w.x), bflo(w.y), bfhi(w.y), bflo(w.z), bfhi(w.z), bflo(w.w), bfhi(w.w)};
;     if (NORM) {
;         float ss = 0.f;
; #pragma unroll
;         for (int q = 0; q < 8; ++q) ss += x[q] * x[q];
;         ss = row16_sum(ss);
;         const float rstd = rsqrtf(ss * (1.f / 128.f) + EPS);
;         const f32x4 g0 = *(const f32x4*)(g + j * 8), g1 = *(const f32x4*)(g + j * 8 + 4);
; #pragma unroll
;         for (int q = 0; q < 4; ++q) { x[q] *= rstd * g0[q]; x[4 + q] *= rstd * g1[q]; }
;     }
;     constexpr int HALFL = ROT / 16;
;     const bool rot = (ROT == 128) || (j < 8); const bool first = (j & HALFL) == 0;
;     float o[8];
; #pragma unroll
;     for (int q = 0; q < 8; ++q) {
;         const float other = (ROT == 128) ? DPPF(x[q], 0x128)   : shx(x[q], HALFL, lane);
;         const float cs = tb[q >> 1][(q & 1) * 2], sn = tb[q >> 1][(q & 1) * 2 + 1];
;         const float r = first ? (x[q] * cs - other * sn) : (x[q] * cs + other * sn);
;         o[q] = (rot ? r : x[q]) * sc;
;     }
;     u32x4 ow; ow.x = cvt_pk_bf16(o[0], o[1]); ow.y = cvt_pk_bf16(o[2], o[3]); ow.z = cvt_pk_bf16(o[4], o[5]); ow.w = cvt_pk_bf16(o[6], o[7]);
;     *(u32x4*)(p + lane * 8) = ow;
; }
	v_mul_f32_e32 v142, v142, v150
	v_mul_f32_e32 v144, v144, v150
	v_mul_f32_e32 v144, v144, v149
	v_mul_f32_e32 v145, v145, v150
	v_mul_f32_e32 v145, v145, v148
	v_mul_f32_dpp v125, v144, v125 row_ror:8 row_mask:0xf bank_mask:0xf bound_ctrl:1
	v_mul_f32_e32 v137, v142, v137
	v_mul_f32_e32 v142, v146, v150
	v_cndmask_b32_e64 v125, v125, -v125, s[4:5]
	v_mul_f32_e32 v140, v140, v150
	v_mul_f32_e32 v139, v142, v139
	v_mul_f32_e32 v142, v143, v150
	v_fmac_f32_e32 v125, v124, v144
	v_mul_f32_dpp v124, v145, v127 row_ror:8 row_mask:0xf bank_mask:0xf bound_ctrl:1
	v_mul_f32_e32 v140, v140, v152
	v_mul_f32_e32 v136, v142, v136
	v_mul_f32_e32 v142, v147, v150
	v_cndmask_b32_e64 v124, v124, -v124, s[4:5]
	v_mul_f32_dpp v121, v139, v121 row_ror:8 row_mask:0xf bank_mask:0xf bound_ctrl:1
	v_mul_f32_e32 v141, v141, v150
	v_mul_f32_e32 v138, v142, v138
	v_mul_f32_dpp v133, v140, v133 row_ror:8 row_mask:0xf bank_mask:0xf bound_ctrl:1
	v_mul_f32_dpp v129, v137, v129 row_ror:8 row_mask:0xf bank_mask:0xf bound_ctrl:1
	v_fmac_f32_e32 v124, v126, v145
	v_cndmask_b32_e64 v126, v121, -v121, s[4:5]
	v_mul_f32_e32 v141, v141, v153
	v_cndmask_b32_e64 v133, v133, -v133, s[4:5]
	v_cndmask_b32_e64 v129, v129, -v129, s[4:5]
	v_fmac_f32_e32 v126, v120, v139
	v_mul_f32_dpp v120, v138, v123 row_ror:8 row_mask:0xf bank_mask:0xf bound_ctrl:1
	v_fmac_f32_e32 v133, v132, v140
	v_mul_f32_dpp v132, v141, v135 row_ror:8 row_mask:0xf bank_mask:0xf bound_ctrl:1
	v_fmac_f32_e32 v129, v128, v137
	v_mul_f32_dpp v128, v136, v131 row_ror:8 row_mask:0xf bank_mask:0xf bound_ctrl:1
	v_cndmask_b32_e64 v123, v120, -v120, s[4:5]
	v_cndmask_b32_e64 v132, v132, -v132, s[4:5]
	v_cndmask_b32_e64 v128, v128, -v128, s[4:5]
	v_fmac_f32_e32 v123, v122, v138
	v_fmac_f32_e32 v132, v134, v141
	v_fmac_f32_e32 v128, v130, v136
	v_cvt_pk_bf16_f32 v120, v133, v132
	v_cvt_pk_bf16_f32 v121, v129, v128
	v_cvt_pk_bf16_f32 v122, v125, v124
	v_cvt_pk_bf16_f32 v123, v126, v123
	flat_store_dwordx4 v[174:175], v[120:123]
	flat_load_dwordx4 v[120:123], v[160:161]
	s_nop 0
	flat_load_dwordx4 v[124:127], v[160:161] offset:16
	v_and_b32_e32 v133, 0xffff0000, v116
	v_lshlrev_b32_e32 v132, 16, v116
	v_mul_f32_e32 v130, v133, v133
	v_and_b32_e32 v116, 0xffff0000, v117
	v_lshlrev_b32_e32 v117, 16, v117
	v_fmac_f32_e32 v130, v132, v132
	v_pk_mul_f32 v[128:129], v[116:117], v[116:117]
	s_nop 0
	v_add_f32_e32 v129, v129, v130
	v_add_f32_e32 v134, v128, v129
	v_and_b32_e32 v128, 0xffff0000, v118
	v_lshlrev_b32_e32 v129, 16, v118
	v_pk_mul_f32 v[130:131], v[128:129], v[128:129]
	s_nop 0
	v_add_f32_e32 v118, v131, v134
	v_add_f32_e32 v134, v130, v118
	v_and_b32_e32 v118, 0xffff0000, v119
	v_lshlrev_b32_e32 v119, 16, v119
	v_pk_mul_f32 v[130:131], v[118:119], v[118:119]
	s_nop 0
	v_add_f32_e32 v131, v131, v134
	v_add_f32_e32 v130, v130, v131
	s_nop 1
	v_add_f32_dpp v130, v130, v130 quad_perm:[1,0,3,2] row_mask:0xf bank_mask:0xf bound_ctrl:1
	s_nop 1
	v_add_f32_dpp v130, v130, v130 quad_perm:[2,3,0,1] row_mask:0xf bank_mask:0xf bound_ctrl:1
	s_nop 1
	v_add_f32_dpp v130, v130, v130 row_half_mirror row_mask:0xf bank_mask:0xf bound_ctrl:1
	s_nop 1
	v_add_f32_dpp v130, v130, v130 row_mirror row_mask:0xf bank_mask:0xf bound_ctrl:1
	v_fmamk_f32 v130, v130, 0x3c000000, v157
	v_mul_f32_e32 v131, 0x4b800000, v130
	v_cmp_gt_f32_e32 vcc, s24, v130
	s_nop 1
	v_cndmask_b32_e32 v130, v130, v131, vcc
	v_rsq_f32_e32 v130, v130
	s_nop 0
	v_mul_f32_e32 v131, 0x45800000, v130
	v_cndmask_b32_e32 v130, v130, v131, vcc
	s_waitcnt vmcnt(0) lgkmcnt(0)
	v_mul_f32_e32 v122, v122, v130
	v_mul_f32_e32 v124, v124, v130
	v_mul_f32_e32 v124, v124, v129
	v_mul_f32_e32 v125, v125, v130
	v_mul_f32_e32 v125, v125, v128
	v_mul_f32_dpp v105, v124, v105 row_ror:8 row_mask:0xf bank_mask:0xf bound_ctrl:1
	v_mul_f32_e32 v117, v122, v117
	v_mul_f32_e32 v122, v126, v130
	v_cndmask_b32_e64 v105, v105, -v105, s[4:5]
	v_mul_f32_e32 v120, v120, v130
	v_mul_f32_e32 v119, v122, v119
	v_mul_f32_e32 v122, v123, v130
	v_fmac_f32_e32 v105, v104, v124
	v_mul_f32_dpp v104, v125, v107 row_ror:8 row_mask:0xf bank_mask:0xf bound_ctrl:1
	v_mul_f32_e32 v120, v120, v132
	v_mul_f32_e32 v116, v122, v116
	v_mul_f32_e32 v122, v127, v130
	v_cndmask_b32_e64 v104, v104, -v104, s[4:5]
	v_mul_f32_dpp v101, v119, v101 row_ror:8 row_mask:0xf bank_mask:0xf bound_ctrl:1
	v_mul_f32_e32 v121, v121, v130
	v_mul_f32_e32 v118, v122, v118
	v_mul_f32_dpp v113, v120, v113 row_ror:8 row_mask:0xf bank_mask:0xf bound_ctrl:1
	v_mul_f32_dpp v109, v117, v109 row_ror:8 row_mask:0xf bank_mask:0xf bound_ctrl:1
	v_fmac_f32_e32 v104, v106, v125
	v_cndmask_b32_e64 v106, v101, -v101, s[4:5]
	v_mul_f32_e32 v121, v121, v133
	v_cndmask_b32_e64 v113, v113, -v113, s[4:5]
	v_cndmask_b32_e64 v109, v109, -v109, s[4:5]
	v_fmac_f32_e32 v106, v100, v119
	v_mul_f32_dpp v100, v118, v103 row_ror:8 row_mask:0xf bank_mask:0xf bound_ctrl:1
	v_fmac_f32_e32 v113, v112, v120
	v_mul_f32_dpp v112, v121, v115 row_ror:8 row_mask:0xf bank_mask:0xf bound_ctrl:1
	v_fmac_f32_e32 v109, v108, v117
	v_mul_f32_dpp v108, v116, v111 row_ror:8 row_mask:0xf bank_mask:0xf bound_ctrl:1
	v_cndmask_b32_e64 v103, v100, -v100, s[4:5]
	v_cndmask_b32_e64 v112, v112, -v112, s[4:5]
	v_cndmask_b32_e64 v108, v108, -v108, s[4:5]
	v_fmac_f32_e32 v103, v102, v118
	v_fmac_f32_e32 v112, v114, v121
	v_fmac_f32_e32 v108, v110, v116
	v_cvt_pk_bf16_f32 v100, v113, v112
	v_cvt_pk_bf16_f32 v101, v109, v108
	v_cvt_pk_bf16_f32 v102, v105, v104
	v_cvt_pk_bf16_f32 v103, v106, v103
	flat_store_dwordx4 v[172:173], v[100:103]
	flat_load_dwordx4 v[100:103], v[160:161]
	s_nop 0
	flat_load_dwordx4 v[104:107], v[160:161] offset:16
	v_and_b32_e32 v113, 0xffff0000, v96
	v_lshlrev_b32_e32 v112, 16, v96
	v_mul_f32_e32 v110, v113, v113
	v_and_b32_e32 v96, 0xffff0000, v97
	v_lshlrev_b32_e32 v97, 16, v97
	v_fmac_f32_e32 v110, v112, v112
	v_pk_mul_f32 v[108:109], v[96:97], v[96:97]
	s_nop 0
	v_add_f32_e32 v109, v109, v110
	v_add_f32_e32 v114, v108, v109
	v_and_b32_e32 v108, 0xffff0000, v98
	v_lshlrev_b32_e32 v109, 16, v98
	v_pk_mul_f32 v[110:111], v[108:109], v[108:109]
	s_nop 0
	v_add_f32_e32 v98, v111, v114
	v_add_f32_e32 v114, v110, v98
	v_and_b32_e32 v98, 0xffff0000, v99
	v_lshlrev_b32_e32 v99, 16, v99
	v_pk_mul_f32 v[110:111], v[98:99], v[98:99]
	s_nop 0
	v_add_f32_e32 v111, v111, v114
	v_add_f32_e32 v110, v110, v111
	s_nop 1
	v_add_f32_dpp v110, v110, v110 quad_perm:[1,0,3,2] row_mask:0xf bank_mask:0xf bound_ctrl:1
	s_nop 1
	v_add_f32_dpp v110, v110, v110 quad_perm:[2,3,0,1] row_mask:0xf bank_mask:0xf bound_ctrl:1
	s_nop 1
	v_add_f32_dpp v110, v110, v110 row_half_mirror row_mask:0xf bank_mask:0xf bound_ctrl:1
	s_nop 1
	v_add_f32_dpp v110, v110, v110 row_mirror row_mask:0xf bank_mask:0xf bound_ctrl:1
	v_fmamk_f32 v110, v110, 0x3c000000, v157
	v_mul_f32_e32 v111, 0x4b800000, v110
	v_cmp_gt_f32_e32 vcc, s24, v110
	s_nop 1
	v_cndmask_b32_e32 v110, v110, v111, vcc
	v_rsq_f32_e32 v110, v110
	s_nop 0
	v_mul_f32_e32 v111, 0x45800000, v110
	v_cndmask_b32_e32 v110, v110, v111, vcc
	s_waitcnt vmcnt(0) lgkmcnt(0)
; __device__ __forceinline__ unsigned cvt_pk_bf16(float lo, float hi) { unsigned r; asm volatile("v_cvt_pk_bf16_f32 %0, %1, %2" : "=v"(r) : "v"(lo), "v"(hi)); return r; }
; __device__ __forceinline__ float bflo(unsigned w) { return __uint_as_float(w << 16); }
; __device__ __forceinline__ float bfhi(unsigned w) { return __uint_as_float(w & 0xffff0000u); }
; __device__ __forceinline__ float shx(float v, int m, int lane) { return __int_as_float(__builtin_amdgcn_ds_bpermute((lane ^ m) << 2, __float_as_int(v))); }
; #define DPPF(v, ctrl) __int_as_float(__builtin_amdgcn_update_dpp(0, __float_as_int(v), (ctrl), 0xf, 0xf, false))
; __device__ __forceinline__ float row16_sum(float x) { x += DPPF(x, 0xB1); x += DPPF(x, 0x4E); x += DPPF(x, 0x141); x += DPPF(x, 0x140); return x; }
; template <bool NORM, int ROT> __device__ __forceinline__ void rope_chunk(bf16_t* p, const u32x4 w, const f32x4 (&tb)[4], const float* g, float sc, int lane) {
;     const int j = lane & 15;
;     float x[8] = {bflo(w.x), bfhi(w.x), bflo(w.y), bfhi(w.y), bflo(w.z), bfhi(w.z), bflo(w.w), bfhi(w.w)};
;     if (NORM) {
;         float ss = 0.f;
; #pragma unroll
;         for (int q = 0; q < 8; ++q) ss += x[q] * x[q];
;         ss = row16_sum(ss);
;         const float rstd = rsqrtf(ss * (1.f / 128.f) + EPS);
;         const f32x4 g0 = *(const f32x4*)(g + j * 8), g1 = *(const f32x4*)(g + j * 8 + 4);
; #pragma unroll
;         for (int q = 0; q < 4; ++q) { x[q] *= rstd * g0[q]; x[4 + q] *= rstd * g1[q]; }
;     }
;     constexpr int HALFL = ROT / 16;
;     const bool rot = (ROT == 128) || (j < 8); const bool first = (j & HALFL) == 0;
;     float o[8];
; #pragma unroll
;     for (int q = 0; q < 8; ++q) {
;         const float other = (ROT == 128) ? DPPF(x[q], 0x128)   : shx(x[q], HALFL, lane);
;         const float cs = tb[q >> 1][(q & 1) * 2], sn = tb[q >> 1][(q & 1) * 2 + 1];
;         const float r = first ? (x[q] * cs - other * sn) : (x[q] * cs + other * sn);
;         o[q] = (rot ? r : x[q]) * sc;
;     }
;     u32x4 ow; ow.x = cvt_pk_bf16(o[0], o[1]); ow.y = cvt_pk_bf16(o[2], o[3]); ow.z = cvt_pk_bf16(o[4], o[5]); ow.w = cvt_pk_bf16(o[6], o[7]);
;     *(u32x4*)(p + lane * 8) = ow;
; }
	v_mul_f32_e32 v102, v102, v110
	v_mul_f32_e32 v104, v104, v110
	v_mul_f32_e32 v104, v104, v109
	v_mul_f32_e32 v105, v105, v110
	v_mul_f32_e32 v105, v105, v108
	v_mul_f32_dpp v81, v104, v81 row_ror:8 row_mask:0xf bank_mask:0xf bound_ctrl:1
	v_mul_f32_e32 v97, v102, v97
	v_mul_f32_e32 v102, v106, v110
	v_cndmask_b32_e64 v81, v81, -v81, s[4:5]
	v_mul_f32_e32 v100, v100, v110
	v_mul_f32_e32 v99, v102, v99
	v_mul_f32_e32 v102, v103, v110
	v_fmac_f32_e32 v81, v80, v104
	v_mul_f32_dpp v80, v105, v83 row_ror:8 row_mask:0xf bank_mask:0xf bound_ctrl:1
	v_mul_f32_e32 v100, v100, v112
	v_mul_f32_e32 v96, v102, v96
	v_mul_f32_e32 v102, v107, v110
	v_cndmask_b32_e64 v80, v80, -v80, s[4:5]
	v_mul_f32_dpp v73, v99, v73 row_ror:8 row_mask:0xf bank_mask:0xf bound_ctrl:1
	v_mul_f32_e32 v101, v101, v110
	v_mul_f32_e32 v98, v102, v98
	v_mul_f32_dpp v93, v100, v93 row_ror:8 row_mask:0xf bank_mask:0xf bound_ctrl:1
	v_mul_f32_dpp v89, v97, v89 row_ror:8 row_mask:0xf bank_mask:0xf bound_ctrl:1
	v_fmac_f32_e32 v80, v82, v105
	v_cndmask_b32_e64 v82, v73, -v73, s[4:5]
	v_mul_f32_e32 v101, v101, v113
	v_cndmask_b32_e64 v93, v93, -v93, s[4:5]
	v_cndmask_b32_e64 v89, v89, -v89, s[4:5]
	v_fmac_f32_e32 v82, v72, v99
	v_mul_f32_dpp v72, v98, v75 row_ror:8 row_mask:0xf bank_mask:0xf bound_ctrl:1
	v_fmac_f32_e32 v93, v92, v100
	v_mul_f32_dpp v92, v101, v95 row_ror:8 row_mask:0xf bank_mask:0xf bound_ctrl:1
	v_fmac_f32_e32 v89, v88, v97
	v_mul_f32_dpp v88, v96, v91 row_ror:8 row_mask:0xf bank_mask:0xf bound_ctrl:1
	v_cndmask_b32_e64 v75, v72, -v72, s[4:5]
	v_cndmask_b32_e64 v92, v92, -v92, s[4:5]
	v_cndmask_b32_e64 v88, v88, -v88, s[4:5]
	v_fmac_f32_e32 v75, v74, v98
	v_fmac_f32_e32 v92, v94, v101
	v_fmac_f32_e32 v88, v90, v96
	v_cvt_pk_bf16_f32 v72, v93, v92
	v_cvt_pk_bf16_f32 v73, v89, v88
	v_cvt_pk_bf16_f32 v74, v81, v80
	v_cvt_pk_bf16_f32 v75, v82, v75
	flat_store_dwordx4 v[170:171], v[72:75]
	flat_load_dwordx4 v[72:75], v[160:161]
	s_nop 0
	flat_load_dwordx4 v[80:83], v[160:161] offset:16
	v_and_b32_e32 v93, 0xffff0000, v60
	v_lshlrev_b32_e32 v92, 16, v60
	v_mul_f32_e32 v90, v93, v93
	v_and_b32_e32 v60, 0xffff0000, v61
	v_lshlrev_b32_e32 v61, 16, v61
	v_fmac_f32_e32 v90, v92, v92
	v_pk_mul_f32 v[88:89], v[60:61], v[60:61]
	s_nop 0
	v_add_f32_e32 v89, v89, v90
	v_add_f32_e32 v94, v88, v89
	v_and_b32_e32 v88, 0xffff0000, v62
	v_lshlrev_b32_e32 v89, 16, v62
	v_pk_mul_f32 v[90:91], v[88:89], v[88:89]
	s_nop 0
	v_add_f32_e32 v62, v91, v94
	v_add_f32_e32 v94, v90, v62
	v_and_b32_e32 v62, 0xffff0000, v63
	v_lshlrev_b32_e32 v63, 16, v63
	v_pk_mul_f32 v[90:91], v[62:63], v[62:63]
	s_nop 0
	v_add_f32_e32 v91, v91, v94
	v_add_f32_e32 v90, v90, v91
	s_nop 1
	v_add_f32_dpp v90, v90, v90 quad_perm:[1,0,3,2] row_mask:0xf bank_mask:0xf bound_ctrl:1
	s_nop 1
	v_add_f32_dpp v90, v90, v90 quad_perm:[2,3,0,1] row_mask:0xf bank_mask:0xf bound_ctrl:1
	s_nop 1
	v_add_f32_dpp v90, v90, v90 row_half_mirror row_mask:0xf bank_mask:0xf bound_ctrl:1
	s_nop 1
	v_add_f32_dpp v90, v90, v90 row_mirror row_mask:0xf bank_mask:0xf bound_ctrl:1
	v_fmamk_f32 v90, v90, 0x3c000000, v157
	v_mul_f32_e32 v91, 0x4b800000, v90
	v_cmp_gt_f32_e32 vcc, s24, v90
	s_nop 1
	v_cndmask_b32_e32 v90, v90, v91, vcc
	v_rsq_f32_e32 v90, v90
	s_nop 0
	v_mul_f32_e32 v91, 0x45800000, v90
	v_cndmask_b32_e32 v90, v90, v91, vcc
	s_waitcnt vmcnt(0) lgkmcnt(0)
	v_mul_f32_e32 v74, v74, v90
	v_mul_f32_e32 v61, v74, v61
	v_mul_f32_e32 v74, v82, v90
	v_mul_f32_e32 v72, v72, v90
	v_mul_f32_e32 v63, v74, v63
	v_mul_f32_e32 v74, v75, v90
	v_mul_f32_e32 v72, v72, v92
	v_mul_f32_e32 v60, v74, v60
	v_mul_f32_e32 v74, v83, v90
	v_mul_f32_e32 v73, v73, v90
	v_mul_f32_e32 v62, v74, v62
	v_mul_f32_dpp v74, v72, v85 row_ror:8 row_mask:0xf bank_mask:0xf bound_ctrl:1
	v_mul_f32_e32 v73, v73, v93
	v_cndmask_b32_e64 v74, v74, -v74, s[4:5]
	v_fmac_f32_e32 v74, v84, v72
	v_mul_f32_dpp v72, v73, v87 row_ror:8 row_mask:0xf bank_mask:0xf bound_ctrl:1
	v_cndmask_b32_e64 v72, v72, -v72, s[4:5]
	v_fmac_f32_e32 v72, v86, v73
	v_mul_f32_dpp v73, v61, v77 row_ror:8 row_mask:0xf bank_mask:0xf bound_ctrl:1
	v_cndmask_b32_e64 v73, v73, -v73, s[4:5]
	v_mul_f32_e32 v80, v80, v90
	v_fmac_f32_e32 v73, v76, v61
	v_mul_f32_dpp v61, v60, v79 row_ror:8 row_mask:0xf bank_mask:0xf bound_ctrl:1
	v_mul_f32_e32 v80, v80, v89
	v_mul_f32_e32 v81, v81, v90
	v_cndmask_b32_e64 v61, v61, -v61, s[4:5]
	v_mul_f32_e32 v81, v81, v88
	v_fmac_f32_e32 v61, v78, v60
	v_mul_f32_dpp v60, v80, v69 row_ror:8 row_mask:0xf bank_mask:0xf bound_ctrl:1
	v_cndmask_b32_e64 v69, v60, -v60, s[4:5]
	v_fmac_f32_e32 v69, v68, v80
	v_mul_f32_dpp v60, v81, v71 row_ror:8 row_mask:0xf bank_mask:0xf bound_ctrl:1
	v_cndmask_b32_e64 v68, v60, -v60, s[4:5]
	v_fmac_f32_e32 v68, v70, v81
	v_mul_f32_dpp v60, v63, v65 row_ror:8 row_mask:0xf bank_mask:0xf bound_ctrl:1
	v_cndmask_b32_e64 v65, v60, -v60, s[4:5]
	v_fmac_f32_e32 v65, v64, v63
	v_mul_f32_dpp v60, v62, v67 row_ror:8 row_mask:0xf bank_mask:0xf bound_ctrl:1
	v_cndmask_b32_e64 v63, v60, -v60, s[4:5]
	v_fmac_f32_e32 v63, v66, v62
	v_cvt_pk_bf16_f32 v60, v74, v72
	v_cvt_pk_bf16_f32 v61, v73, v61
	v_cvt_pk_bf16_f32 v62, v69, v68
	v_cvt_pk_bf16_f32 v63, v65, v63
	flat_store_dwordx4 v[168:169], v[60:63]
	flat_load_dwordx4 v[60:63], v[160:161]
	s_nop 0
	flat_load_dwordx4 v[64:67], v[160:161] offset:16
	v_and_b32_e32 v73, 0xffff0000, v56
	v_lshlrev_b32_e32 v72, 16, v56
	v_mul_f32_e32 v70, v73, v73
	v_and_b32_e32 v56, 0xffff0000, v57
	v_lshlrev_b32_e32 v57, 16, v57
	v_fmac_f32_e32 v70, v72, v72
	v_pk_mul_f32 v[68:69], v[56:57], v[56:57]
	s_nop 0
	v_add_f32_e32 v69, v69, v70
	v_add_f32_e32 v74, v68, v69
	v_and_b32_e32 v68, 0xffff0000, v58
	v_lshlrev_b32_e32 v69, 16, v58
	v_pk_mul_f32 v[70:71], v[68:69], v[68:69]
	s_nop 0
	v_add_f32_e32 v58, v71, v74
	v_add_f32_e32 v74, v70, v58
	v_and_b32_e32 v58, 0xffff0000, v59
	v_lshlrev_b32_e32 v59, 16, v59
	v_pk_mul_f32 v[70:71], v[58:59], v[58:59]
	s_nop 0
	v_add_f32_e32 v71, v71, v74
	v_add_f32_e32 v70, v70, v71
	s_nop 1
	v_add_f32_dpp v70, v70, v70 quad_perm:[1,0,3,2] row_mask:0xf bank_mask:0xf bound_ctrl:1
	s_nop 1
	v_add_f32_dpp v70, v70, v70 quad_perm:[2,3,0,1] row_mask:0xf bank_mask:0xf bound_ctrl:1
	s_nop 1
	v_add_f32_dpp v70, v70, v70 row_half_mirror row_mask:0xf bank_mask:0xf bound_ctrl:1
	s_nop 1
	v_add_f32_dpp v70, v70, v70 row_mirror row_mask:0xf bank_mask:0xf bound_ctrl:1
	v_fmamk_f32 v70, v70, 0x3c000000, v157
	v_mul_f32_e32 v71, 0x4b800000, v70
	v_cmp_gt_f32_e32 vcc, s24, v70
	s_nop 1
	v_cndmask_b32_e32 v70, v70, v71, vcc
	v_rsq_f32_e32 v70, v70
	s_nop 0
	v_mul_f32_e32 v71, 0x45800000, v70
	v_cndmask_b32_e32 v70, v70, v71, vcc
	s_waitcnt vmcnt(0) lgkmcnt(0)
; __device__ __forceinline__ unsigned cvt_pk_bf16(float lo, float hi) { unsigned r; asm volatile("v_cvt_pk_bf16_f32 %0, %1, %2" : "=v"(r) : "v"(lo), "v"(hi)); return r; }
; __device__ __forceinline__ float bflo(unsigned w) { return __uint_as_float(w << 16); }
; __device__ __forceinline__ float bfhi(unsigned w) { return __uint_as_float(w & 0xffff0000u); }
; __device__ __forceinline__ float shx(float v, int m, int lane) { return __int_as_float(__builtin_amdgcn_ds_bpermute((lane ^ m) << 2, __float_as_int(v))); }
; #define DPPF(v, ctrl) __int_as_float(__builtin_amdgcn_update_dpp(0, __float_as_int(v), (ctrl), 0xf, 0xf, false))
; __device__ __forceinline__ float row16_sum(float x) { x += DPPF(x, 0xB1); x += DPPF(x, 0x4E); x += DPPF(x, 0x141); x += DPPF(x, 0x140); return x; }
; template <bool NORM, int ROT> __device__ __forceinline__ void rope_chunk(bf16_t* p, const u32x4 w, const f32x4 (&tb)[4], const float* g, float sc, int lane) {
;     const int j = lane & 15;
;     float x[8] = {bflo(w.x), bfhi(w.x), bflo(w.y), bfhi(w.y), bflo(w.z), bfhi(w.z), bflo(w.w), bfhi(w.w)};
;     if (NORM) {
;         float ss = 0.f;
; #pragma unroll
;         for (int q = 0; q < 8; ++q) ss += x[q] * x[q];
;         ss = row16_sum(ss);
;         const float rstd = rsqrtf(ss * (1.f / 128.f) + EPS);
;         const f32x4 g0 = *(const f32x4*)(g + j * 8), g1 = *(const f32x4*)(g + j * 8 + 4);
; #pragma unroll
;         for (int q = 0; q < 4; ++q) { x[q] *= rstd * g0[q]; x[4 + q] *= rstd * g1[q]; }
;     }
;     constexpr int HALFL = ROT / 16;
;     const bool rot = (ROT == 128) || (j < 8); const bool first = (j & HALFL) == 0;
;     float o[8];
; #pragma unroll
;     for (int q = 0; q < 8; ++q) {
;         const float other = (ROT == 128) ? DPPF(x[q], 0x128)   : shx(x[q], HALFL, lane);
;         const float cs = tb[q >> 1][(q & 1) * 2], sn = tb[q >> 1][(q & 1) * 2 + 1];
;         const float r = first ? (x[q] * cs - other * sn) : (x[q] * cs + other * sn);
;         o[q] = (rot ? r : x[q]) * sc;
;     }
;     u32x4 ow; ow.x = cvt_pk_bf16(o[0], o[1]); ow.y = cvt_pk_bf16(o[2], o[3]); ow.z = cvt_pk_bf16(o[4], o[5]); ow.w = cvt_pk_bf16(o[6], o[7]);
;     *(u32x4*)(p + lane * 8) = ow;
; }
	v_mul_f32_e32 v62, v62, v70
	v_mul_f32_e32 v64, v64, v70
	v_mul_f32_e32 v64, v64, v69
	v_mul_f32_e32 v65, v65, v70
	v_mul_f32_e32 v65, v65, v68
	v_mul_f32_dpp v45, v64, v45 row_ror:8 row_mask:0xf bank_mask:0xf bound_ctrl:1
	v_mul_f32_e32 v57, v62, v57
	v_mul_f32_e32 v62, v66, v70
	v_cndmask_b32_e64 v45, v45, -v45, s[4:5]
	v_mul_f32_e32 v60, v60, v70
	v_mul_f32_e32 v59, v62, v59
	v_mul_f32_e32 v62, v63, v70
	v_fmac_f32_e32 v45, v44, v64
	v_mul_f32_dpp v44, v65, v47 row_ror:8 row_mask:0xf bank_mask:0xf bound_ctrl:1
	v_mul_f32_e32 v60, v60, v72
	v_mul_f32_e32 v56, v62, v56
	v_mul_f32_e32 v62, v67, v70
	v_cndmask_b32_e64 v44, v44, -v44, s[4:5]
	v_mul_f32_dpp v41, v59, v41 row_ror:8 row_mask:0xf bank_mask:0xf bound_ctrl:1
	v_mul_f32_e32 v61, v61, v70
	v_mul_f32_e32 v58, v62, v58
	v_mul_f32_dpp v53, v60, v53 row_ror:8 row_mask:0xf bank_mask:0xf bound_ctrl:1
	v_mul_f32_dpp v49, v57, v49 row_ror:8 row_mask:0xf bank_mask:0xf bound_ctrl:1
	v_fmac_f32_e32 v44, v46, v65
	v_cndmask_b32_e64 v46, v41, -v41, s[4:5]
	v_mul_f32_e32 v61, v61, v73
	v_cndmask_b32_e64 v53, v53, -v53, s[4:5]
	v_cndmask_b32_e64 v49, v49, -v49, s[4:5]
	v_fmac_f32_e32 v46, v40, v59
	v_mul_f32_dpp v40, v58, v43 row_ror:8 row_mask:0xf bank_mask:0xf bound_ctrl:1
	v_fmac_f32_e32 v53, v52, v60
	v_mul_f32_dpp v52, v61, v55 row_ror:8 row_mask:0xf bank_mask:0xf bound_ctrl:1
	v_fmac_f32_e32 v49, v48, v57
	v_mul_f32_dpp v48, v56, v51 row_ror:8 row_mask:0xf bank_mask:0xf bound_ctrl:1
	v_cndmask_b32_e64 v43, v40, -v40, s[4:5]
	v_cndmask_b32_e64 v52, v52, -v52, s[4:5]
	v_cndmask_b32_e64 v48, v48, -v48, s[4:5]
	v_fmac_f32_e32 v43, v42, v58
	v_fmac_f32_e32 v52, v54, v61
	v_fmac_f32_e32 v48, v50, v56
	v_cvt_pk_bf16_f32 v40, v53, v52
	v_cvt_pk_bf16_f32 v41, v49, v48
	v_cvt_pk_bf16_f32 v42, v45, v44
	v_cvt_pk_bf16_f32 v43, v46, v43
	flat_store_dwordx4 v[166:167], v[40:43]
	flat_load_dwordx4 v[40:43], v[160:161]
	s_nop 0
	flat_load_dwordx4 v[44:47], v[160:161] offset:16
	v_and_b32_e32 v57, 0xffff0000, v36
	v_lshlrev_b32_e32 v56, 16, v36
	v_and_b32_e32 v36, 0xffff0000, v37
	v_lshlrev_b32_e32 v37, 16, v37
	v_mul_f32_e32 v58, v57, v57
	v_pk_mul_f32 v[50:51], v[36:37], v[36:37]
	v_fmac_f32_e32 v58, v56, v56
	v_and_b32_e32 v48, 0xffff0000, v38
	v_lshlrev_b32_e32 v49, 16, v38
	v_add_f32_e32 v51, v51, v58
	v_pk_mul_f32 v[52:53], v[48:49], v[48:49]
	v_add_f32_e32 v50, v50, v51
	v_and_b32_e32 v38, 0xffff0000, v39
	v_lshlrev_b32_e32 v39, 16, v39
	v_add_f32_e32 v50, v53, v50
	v_pk_mul_f32 v[54:55], v[38:39], v[38:39]
	v_add_f32_e32 v50, v52, v50
	v_add_f32_e32 v50, v55, v50
	v_add_f32_e32 v50, v54, v50
	s_nop 1
	v_add_f32_dpp v50, v50, v50 quad_perm:[1,0,3,2] row_mask:0xf bank_mask:0xf bound_ctrl:1
	s_nop 1
	v_add_f32_dpp v50, v50, v50 quad_perm:[2,3,0,1] row_mask:0xf bank_mask:0xf bound_ctrl:1
	s_nop 1
	v_add_f32_dpp v50, v50, v50 row_half_mirror row_mask:0xf bank_mask:0xf bound_ctrl:1
	s_nop 1
	v_add_f32_dpp v50, v50, v50 row_mirror row_mask:0xf bank_mask:0xf bound_ctrl:1
	v_fmamk_f32 v50, v50, 0x3c000000, v157
	v_mul_f32_e32 v51, 0x4b800000, v50
	v_cmp_gt_f32_e32 vcc, s24, v50
	s_nop 1
	v_cndmask_b32_e32 v50, v50, v51, vcc
	v_rsq_f32_e32 v50, v50
	s_nop 0
	v_mul_f32_e32 v51, 0x45800000, v50
	v_cndmask_b32_e32 v50, v50, v51, vcc
	s_waitcnt vmcnt(0) lgkmcnt(0)
; __device__ __forceinline__ unsigned cvt_pk_bf16(float lo, float hi) { unsigned r; asm volatile("v_cvt_pk_bf16_f32 %0, %1, %2" : "=v"(r) : "v"(lo), "v"(hi)); return r; }
; __device__ __forceinline__ float bflo(unsigned w) { return __uint_as_float(w << 16); }
; __device__ __forceinline__ float bfhi(unsigned w) { return __uint_as_float(w & 0xffff0000u); }
; __device__ __forceinline__ float shx(float v, int m, int lane) { return __int_as_float(__builtin_amdgcn_ds_bpermute((lane ^ m) << 2, __float_as_int(v))); }
; #define DPPF(v, ctrl) __int_as_float(__builtin_amdgcn_update_dpp(0, __float_as_int(v), (ctrl), 0xf, 0xf, false))
; __device__ __forceinline__ float row16_sum(float x) { x += DPPF(x, 0xB1); x += DPPF(x, 0x4E); x += DPPF(x, 0x141); x += DPPF(x, 0x140); return x; }
; template <bool NORM, int ROT> __device__ __forceinline__ void rope_chunk(bf16_t* p, const u32x4 w, const f32x4 (&tb)[4], const float* g, float sc, int lane) {
;     const int j = lane & 15;
;     float x[8] = {bflo(w.x), bfhi(w.x), bflo(w.y), bfhi(w.y), bflo(w.z), bfhi(w.z), bflo(w.w), bfhi(w.w)};
;     if (NORM) {
;         float ss = 0.f;
; #pragma unroll
;         for (int q = 0; q < 8; ++q) ss += x[q] * x[q];
;         ss = row16_sum(ss);
;         const float rstd = rsqrtf(ss * (1.f / 128.f) + EPS);
;         const f32x4 g0 = *(const f32x4*)(g + j * 8), g1 = *(const f32x4*)(g + j * 8 + 4);
; #pragma unroll
;         for (int q = 0; q < 4; ++q) { x[q] *= rstd * g0[q]; x[4 + q] *= rstd * g1[q]; }
;     }
;     constexpr int HALFL = ROT / 16;
;     const bool rot = (ROT == 128) || (j < 8); const bool first = (j & HALFL) == 0;
;     float o[8];
; #pragma unroll
;     for (int q = 0; q < 8; ++q) {
;         const float other = (ROT == 128) ? DPPF(x[q], 0x128)   : shx(x[q], HALFL, lane);
;         const float cs = tb[q >> 1][(q & 1) * 2], sn = tb[q >> 1][(q & 1) * 2 + 1];
;         const float r = first ? (x[q] * cs - other * sn) : (x[q] * cs + other * sn);
;         o[q] = (rot ? r : x[q]) * sc;
;     }
;     u32x4 ow; ow.x = cvt_pk_bf16(o[0], o[1]); ow.y = cvt_pk_bf16(o[2], o[3]); ow.z = cvt_pk_bf16(o[4], o[5]); ow.w = cvt_pk_bf16(o[6], o[7]);
;     *(u32x4*)(p + lane * 8) = ow;
; }
	v_mul_f32_e32 v42, v42, v50
	v_mul_f32_e32 v44, v44, v50
	v_mul_f32_e32 v44, v44, v49
	v_mul_f32_e32 v45, v45, v50
	v_mul_f32_e32 v46, v46, v50
	v_mul_f32_dpp v25, v44, v25 row_ror:8 row_mask:0xf bank_mask:0xf bound_ctrl:1
	v_mul_f32_e32 v45, v45, v48
	v_cndmask_b32_e64 v25, v25, -v25, s[4:5]
	v_mul_f32_e32 v40, v40, v50
	v_mul_f32_e32 v37, v42, v37
	v_mul_f32_e32 v39, v46, v39
	v_mul_f32_e32 v42, v43, v50
	v_fmac_f32_e32 v25, v24, v44
	v_mul_f32_dpp v24, v45, v27 row_ror:8 row_mask:0xf bank_mask:0xf bound_ctrl:1
	v_mul_f32_e32 v40, v40, v56
	v_mul_f32_e32 v36, v42, v36
	v_mul_f32_e32 v42, v47, v50
	v_cndmask_b32_e64 v24, v24, -v24, s[4:5]
	v_mul_f32_dpp v21, v39, v21 row_ror:8 row_mask:0xf bank_mask:0xf bound_ctrl:1
	v_mul_f32_e32 v41, v41, v50
	v_mul_f32_e32 v38, v42, v38
	v_mul_f32_dpp v33, v40, v33 row_ror:8 row_mask:0xf bank_mask:0xf bound_ctrl:1
	v_mul_f32_dpp v29, v37, v29 row_ror:8 row_mask:0xf bank_mask:0xf bound_ctrl:1
	v_fmac_f32_e32 v24, v26, v45
	v_cndmask_b32_e64 v26, v21, -v21, s[4:5]
	v_mul_f32_e32 v41, v41, v57
	v_cndmask_b32_e64 v33, v33, -v33, s[4:5]
	v_cndmask_b32_e64 v29, v29, -v29, s[4:5]
	v_fmac_f32_e32 v26, v20, v39
	v_mul_f32_dpp v20, v38, v23 row_ror:8 row_mask:0xf bank_mask:0xf bound_ctrl:1
	v_fmac_f32_e32 v33, v32, v40
	v_mul_f32_dpp v32, v41, v35 row_ror:8 row_mask:0xf bank_mask:0xf bound_ctrl:1
	v_fmac_f32_e32 v29, v28, v37
	v_mul_f32_dpp v28, v36, v31 row_ror:8 row_mask:0xf bank_mask:0xf bound_ctrl:1
	v_cndmask_b32_e64 v23, v20, -v20, s[4:5]
	v_cndmask_b32_e64 v32, v32, -v32, s[4:5]
	v_cndmask_b32_e64 v28, v28, -v28, s[4:5]
	v_fmac_f32_e32 v23, v22, v38
	v_fmac_f32_e32 v32, v34, v41
	v_fmac_f32_e32 v28, v30, v36
	v_cvt_pk_bf16_f32 v20, v33, v32
	v_cvt_pk_bf16_f32 v21, v29, v28
	v_cvt_pk_bf16_f32 v22, v25, v24
	v_cvt_pk_bf16_f32 v23, v26, v23
	flat_store_dwordx4 v[164:165], v[20:23]
	flat_load_dwordx4 v[20:23], v[160:161]
	s_nop 0
	flat_load_dwordx4 v[24:27], v[160:161] offset:16
	v_and_b32_e32 v37, 0xffff0000, v16
	v_lshlrev_b32_e32 v36, 16, v16
	v_and_b32_e32 v16, 0xffff0000, v17
	v_lshlrev_b32_e32 v17, 16, v17
	v_mul_f32_e32 v38, v37, v37
	v_pk_mul_f32 v[30:31], v[16:17], v[16:17]
	v_fmac_f32_e32 v38, v36, v36
	v_and_b32_e32 v28, 0xffff0000, v18
	v_lshlrev_b32_e32 v29, 16, v18
	v_add_f32_e32 v31, v31, v38
	v_pk_mul_f32 v[32:33], v[28:29], v[28:29]
	v_add_f32_e32 v30, v30, v31
	v_and_b32_e32 v18, 0xffff0000, v19
	v_lshlrev_b32_e32 v19, 16, v19
	v_add_f32_e32 v30, v33, v30
	v_pk_mul_f32 v[34:35], v[18:19], v[18:19]
	v_add_f32_e32 v30, v32, v30
	v_add_f32_e32 v30, v35, v30
	v_add_f32_e32 v30, v34, v30
	s_nop 1
	v_add_f32_dpp v30, v30, v30 quad_perm:[1,0,3,2] row_mask:0xf bank_mask:0xf bound_ctrl:1
	s_nop 1
	v_add_f32_dpp v30, v30, v30 quad_perm:[2,3,0,1] row_mask:0xf bank_mask:0xf bound_ctrl:1
	s_nop 1
	v_add_f32_dpp v30, v30, v30 row_half_mirror row_mask:0xf bank_mask:0xf bound_ctrl:1
	s_nop 1
	v_add_f32_dpp v30, v30, v30 row_mirror row_mask:0xf bank_mask:0xf bound_ctrl:1
	v_fmamk_f32 v30, v30, 0x3c000000, v157
	v_mul_f32_e32 v31, 0x4b800000, v30
	v_cmp_gt_f32_e32 vcc, s24, v30
	s_nop 1
	v_cndmask_b32_e32 v30, v30, v31, vcc
	v_rsq_f32_e32 v30, v30
	s_nop 0
	v_mul_f32_e32 v31, 0x45800000, v30
	v_cndmask_b32_e32 v30, v30, v31, vcc
	s_waitcnt vmcnt(0) lgkmcnt(0)
	v_mul_f32_e32 v22, v22, v30
	v_mul_f32_e32 v24, v24, v30
	v_mul_f32_e32 v24, v24, v29
	v_mul_f32_e32 v25, v25, v30
	v_mul_f32_e32 v26, v26, v30
	v_mul_f32_dpp v5, v24, v5 row_ror:8 row_mask:0xf bank_mask:0xf bound_ctrl:1
	v_mul_f32_e32 v25, v25, v28
	v_cndmask_b32_e64 v5, v5, -v5, s[4:5]
	v_mul_f32_e32 v19, v26, v19
	v_fmac_f32_e32 v5, v4, v24
	v_mul_f32_dpp v4, v25, v7 row_ror:8 row_mask:0xf bank_mask:0xf bound_ctrl:1
	v_mul_f32_e32 v27, v27, v30
	v_mul_f32_e32 v17, v22, v17
	v_cndmask_b32_e64 v4, v4, -v4, s[4:5]
	v_mul_f32_dpp v1, v19, v1 row_ror:8 row_mask:0xf bank_mask:0xf bound_ctrl:1
	v_mul_f32_e32 v20, v20, v30
	v_mul_f32_e32 v21, v21, v30
	v_mul_f32_e32 v23, v23, v30
	v_mul_f32_e32 v18, v27, v18
	v_mul_f32_dpp v9, v17, v9 row_ror:8 row_mask:0xf bank_mask:0xf bound_ctrl:1
	v_fmac_f32_e32 v4, v6, v25
	v_cndmask_b32_e64 v6, v1, -v1, s[4:5]
	v_mul_f32_e32 v20, v20, v36
	v_mul_f32_e32 v21, v21, v37
	v_mul_f32_e32 v16, v23, v16
	v_cndmask_b32_e64 v9, v9, -v9, s[4:5]
	v_fmac_f32_e32 v6, v0, v19
	v_mul_f32_dpp v0, v18, v3 row_ror:8 row_mask:0xf bank_mask:0xf bound_ctrl:1
	v_mul_f32_dpp v13, v20, v13 row_ror:8 row_mask:0xf bank_mask:0xf bound_ctrl:1
	v_mul_f32_dpp v15, v21, v15 row_ror:8 row_mask:0xf bank_mask:0xf bound_ctrl:1
	v_fmac_f32_e32 v9, v8, v17
	v_mul_f32_dpp v8, v16, v11 row_ror:8 row_mask:0xf bank_mask:0xf bound_ctrl:1
	v_cndmask_b32_e64 v3, v0, -v0, s[4:5]
	v_cndmask_b32_e64 v13, v13, -v13, s[4:5]
	v_cndmask_b32_e64 v15, v15, -v15, s[4:5]
	v_cndmask_b32_e64 v8, v8, -v8, s[4:5]
	v_fmac_f32_e32 v3, v2, v18
	v_fmac_f32_e32 v13, v12, v20
	v_fmac_f32_e32 v15, v14, v21
	v_fmac_f32_e32 v8, v10, v16
	v_cvt_pk_bf16_f32 v0, v13, v15
	v_cvt_pk_bf16_f32 v1, v9, v8
	v_cvt_pk_bf16_f32 v2, v5, v4
	v_cvt_pk_bf16_f32 v3, v6, v3
	flat_store_dwordx4 v[162:163], v[0:3]
	v_lshl_add_u64 v[162:163], v[162:163], 0, s[16:17]
	s_cbranch_scc1 .Lrb_1074
.Lrb_1075:
	s_branch .LBB0_4694
.LBB0_4694:
	v_readlane_b32 s36, v255, 4
	v_readlane_b32 s37, v255, 5
